# all per-phase s_setprio flips in the GEMM loops deleted; one static s_setprio 1 for waves 4-7 at kernel entry
# speedup vs baseline: 1.0022x; 1.0014x over previous
; #define LAS __attribute__((address_space(3)))
; __device__ __forceinline__ unsigned xb_add(unsigned* p, unsigned v) { return __hip_atomic_fetch_add(p, v, __ATOMIC_RELAXED, __HIP_MEMORY_SCOPE_AGENT); }
; __device__ __forceinline__ unsigned xb_xcc_id() { return (unsigned)__builtin_amdgcn_s_getreg((3 << 11) | 20) & 0xFu; }
; __global__ void __launch_bounds__(NT, 2) trunk_fwd(Args args) {
;     ...
;     const int tid = threadIdx.x, wave = __builtin_amdgcn_readfirstlane(tid >> 6), G = gridDim.x, bx = blockIdx.x;
;     LAS unsigned long long* PT = (LAS unsigned long long*)(lds + LDS_PT);
;     if (tid == 0) {
; #pragma unroll
;         for (int i = 0; i < 25; ++i) PT[i] = (unsigned long long)args.in[i];
;         PT[25] = (unsigned long long)args.out; PT[26] = (unsigned long long)args.ws;
;         ((LAS unsigned*)(lds + LDS_PT + 256))[0] = 0u; ((LAS unsigned*)(lds + LDS_PT + 256))[1] = 0u;
;         (void)xb_add((unsigned*)(args.ws + WS_CTL) + XB_XCNT(xb_xcc_id()), 1u);
;     }
_Z9trunk_fwd4Args:
	s_load_dwordx2 s[34:35], s[0:1], 0xe0
	s_load_dword s54, s[0:1], 0xe8
	s_add_u32 s52, s0, 0xe0
	v_and_b32_e32 v232, 0x3ff, v0
	s_addc_u32 s53, s1, 0
	v_readfirstlane_b32 s3, v232
	v_cmp_eq_u32_e64 s[78:79], 0, v232
	s_nop 1
	s_lshr_b32 s4, s3, 6
	s_cmp_ge_u32 s4, 4
	s_cbranch_scc0 .Lprio_k_done
	s_setprio 1
.Lprio_k_done:
	s_and_saveexec_b64 s[4:5], s[78:79]
	s_cbranch_execz .LBB0_3
	s_load_dwordx16 s[16:31], s[0:1], 0x0
	s_add_i32 s8, 0, 0x25000
	s_load_dwordx16 s[36:51], s[0:1], 0x40
	v_mov_b32_e32 v1, s8
	s_add_i32 s8, 0, 0x25010
	s_waitcnt lgkmcnt(0)
	v_mov_b32_e32 v2, s16
	v_mov_b32_e32 v3, s17
	v_mov_b32_e32 v4, s18
	v_mov_b32_e32 v5, s19
	ds_write_b128 v1, v[2:5]
	v_mov_b32_e32 v2, s20
	v_mov_b32_e32 v3, s21
	v_mov_b32_e32 v4, s22
	v_mov_b32_e32 v5, s23
	v_mov_b32_e32 v1, s8
	s_add_i32 s8, 0, 0x25020
	ds_write_b128 v1, v[2:5]
	v_mov_b32_e32 v2, s24
	v_mov_b32_e32 v3, s25
	v_mov_b32_e32 v4, s26
	v_mov_b32_e32 v5, s27
	v_mov_b32_e32 v1, s8
	s_add_i32 s8, 0, 0x25030
	ds_write_b128 v1, v[2:5]
	v_mov_b32_e32 v2, s28
	v_mov_b32_e32 v3, s29
	v_mov_b32_e32 v4, s30
	v_mov_b32_e32 v5, s31
	v_mov_b32_e32 v1, s8
	s_add_i32 s8, 0, 0x25040
	s_load_dwordx16 s[16:31], s[0:1], 0x80
	ds_write_b128 v1, v[2:5]
	v_mov_b32_e32 v2, s36
	v_mov_b32_e32 v3, s37
	v_mov_b32_e32 v4, s38
	v_mov_b32_e32 v5, s39
	v_mov_b32_e32 v1, s8
	s_add_i32 s8, 0, 0x25050
	ds_write_b128 v1, v[2:5]
	v_mov_b32_e32 v2, s40
	v_mov_b32_e32 v3, s41
	v_mov_b32_e32 v4, s42
	v_mov_b32_e32 v5, s43
	v_mov_b32_e32 v1, s8
	s_add_i32 s8, 0, 0x25060
	ds_write_b128 v1, v[2:5]
	v_mov_b32_e32 v2, s44
	v_mov_b32_e32 v3, s45
	v_mov_b32_e32 v4, s46
	v_mov_b32_e32 v5, s47
	v_mov_b32_e32 v1, s8
	s_add_i32 s8, 0, 0x25070
	ds_write_b128 v1, v[2:5]
	v_mov_b32_e32 v2, s48
	v_mov_b32_e32 v3, s49
	v_mov_b32_e32 v4, s50
	v_mov_b32_e32 v5, s51
	v_mov_b32_e32 v1, s8
	s_add_i32 s8, 0, 0x25080
	ds_write_b128 v1, v[2:5]
	s_waitcnt lgkmcnt(0)
	v_mov_b32_e32 v2, s16
	v_mov_b32_e32 v3, s17
	v_mov_b32_e32 v4, s18
	v_mov_b32_e32 v5, s19
	v_mov_b32_e32 v1, s8
	s_add_i32 s8, 0, 0x25090
	ds_write_b128 v1, v[2:5]
	v_mov_b32_e32 v2, s20
	v_mov_b32_e32 v3, s21
	v_mov_b32_e32 v4, s22
	v_mov_b32_e32 v5, s23
	v_mov_b32_e32 v1, s8
	s_add_i32 s8, 0, 0x250a0
	ds_write_b128 v1, v[2:5]
	v_mov_b32_e32 v2, s24
	v_mov_b32_e32 v3, s25
	v_mov_b32_e32 v4, s26
	v_mov_b32_e32 v5, s27
	v_mov_b32_e32 v1, s8
	ds_write_b128 v1, v[2:5]
	s_load_dwordx2 s[8:9], s[0:1], 0xd0
	s_load_dwordx4 s[12:15], s[0:1], 0xc0
	s_add_i32 s10, 0, 0x250b0
	v_mov_b32_e32 v2, s28
	v_mov_b32_e32 v3, s29
	v_mov_b32_e32 v4, s30
	v_mov_b32_e32 v5, s31
	v_mov_b32_e32 v1, s10
	s_add_i32 s10, 0, 0x250c0
	ds_write_b128 v1, v[2:5]
	s_waitcnt lgkmcnt(0)
	v_mov_b32_e32 v2, s12
	v_mov_b32_e32 v3, s13
	v_mov_b32_e32 v4, s14
	v_mov_b32_e32 v5, s15
	v_mov_b32_e32 v1, s10
	s_add_i32 s10, 0, 0x250d0
	ds_write_b128 v1, v[2:5]
	v_mov_b32_e32 v1, s10
	v_mov_b64_e32 v[2:3], s[8:9]
	ds_write_b64 v1, v[2:3]
	s_add_i32 s10, 0, 0x25100
	v_mov_b32_e32 v2, 0
	s_mov_b64 s[6:7], exec
	v_mov_b32_e32 v3, v2
	v_mov_b32_e32 v1, s10
	ds_write_b64 v1, v[2:3]
	v_mbcnt_lo_u32_b32 v1, s6, 0
	v_mbcnt_hi_u32_b32 v1, s7, v1
	s_getreg_b32 s10, hwreg(HW_REG_XCC_ID, 0, 4)
	v_cmp_eq_u32_e32 vcc, 0, v1
	s_and_b64 exec, exec, vcc
	s_cbranch_execz .LBB0_3
	s_lshl_b32 s10, s10, 8
	s_and_b32 s10, s10, 0xf00
	s_add_u32 s8, s8, s10
	s_addc_u32 s9, s9, 0
	s_bcnt1_i32_b64 s6, s[6:7]
	v_mov_b32_e32 v1, 0x1e600000
	v_mov_b32_e32 v2, s6
	global_atomic_add v1, v2, s[8:9] offset:1024

; #define PG8_STAGE(bufoff, gbase, voff) do { _Pragma("unroll") for (int _i = 0; _i < 2; ++_i) \
;         __builtin_amdgcn_global_load_lds((const unsigned*)((const char*)(gbase) + (voff)[_i]), (PG8_LAS unsigned*)(lds + (bufoff) + ldsw + _i * 8192), 16, 0, 0); } while (0)
; #define PG8_LDA(dst, b, h) do { _Pragma("unroll") for (int m = 0; m < 4; ++m) _Pragma("unroll") for (int k = 0; k < 2; ++k) dst[m][k] = *(const PG8_LAS bf16x8*)(lds + PG8_SA(b, h) + aoff + m * 2048 + k * 1024); } while (0)
; #define PG8_LDB(dst, b, h) do { _Pragma("unroll") for (int n = 0; n < 2; ++n) _Pragma("unroll") for (int k = 0; k < 2; ++k) dst[n][k] = *(const PG8_LAS bf16x8*)(lds + PG8_SB(b, h) + boff + n * 2048 + k * 1024); } while (0)
; #define PG8_MMA(ai, bj, At, Bt) do { __builtin_amdgcn_s_setprio(1); _Pragma("unroll") for (int m = 0; m < 4; ++m) _Pragma("unroll") for (int n = 0; n < 2; ++n) _Pragma("unroll") for (int k = 0; k < 2; ++k) \
;         acc[ai][bj][m][n] = mma16<Epi::F16A>(Bt[n][k], At[m][k], acc[ai][bj][m][n]); __builtin_amdgcn_s_setprio(0); } while (0)
; #define PG8_WAIT_V(n) asm volatile("s_waitcnt vmcnt(" #n ")" ::: "memory")
; #define PG8_WAIT_L(n) asm volatile("s_waitcnt lgkmcnt(" #n ")" ::: "memory")
; #define PG8_BAR __builtin_amdgcn_s_barrier()
; #define PG8_SCHED __builtin_amdgcn_sched_barrier(0)
; template <class Epi, class Sched, bool ALIGN_EPI = false, bool SP2 = false>
; __device__ __forceinline__ void gemm_phase(PG8_LAS unsigned char* lds, const Gemm g, const Sched& S, const Epi& E) {
;     ...
;             PG8_LDB(B0, 0, 0); PG8_LDB(B1, 0, 1); PG8_SCHED; PG8_LDA(At, 0, 0); PG8_STAGE(PG8_SA(1, 1), a1 + hstep, voffA);
;             PG8_WAIT_V(8); PG8_WAIT_L(0); PG8_BAR; PG8_MMA(0, 0, At, B0); PG8_MMA(0, 1, At, B1); PG8_BAR; PG8_SCHED;
;             PG8_LDA(At, 0, 1); PG8_STAGE(PG8_SB(0, 0), b2, voffB); PG8_STAGE(PG8_SB(0, 1), b2 + hstep, voffB); PG8_STAGE(PG8_SA(0, 0), a2, voffA);
;             PG8_WAIT_V(8); PG8_WAIT_L(0); PG8_BAR; PG8_MMA(1, 0, At, B0); PG8_MMA(1, 1, At, B1); PG8_BAR; PG8_SCHED;
.LBB0_286:
	s_add_u32 s37, s26, 0xfffc0080
	s_addc_u32 s38, s27, -1
	s_add_i32 s59, 0, 0x10000
	s_cmp_eq_u32 s57, 12
	s_cselect_b32 s41, s21, s38
	s_cselect_b32 s40, s52, s37
	s_cselect_b32 s39, s17, s55
	s_cselect_b32 s38, s53, s54
	s_add_i32 s37, 0, 0x14000
	v_add_u32_e32 v156, s59, v146
	v_add_u32_e32 v190, s37, v146
	ds_read_b128 v[140:143], v156
	ds_read_b128 v[148:151], v156 offset:1024
	ds_read_b128 v[152:155], v156 offset:2048
	ds_read_b128 v[156:159], v156 offset:3072
	ds_read_b128 v[160:163], v190
	ds_read_b128 v[182:185], v190 offset:1024
	ds_read_b128 v[186:189], v190 offset:2048
	ds_read_b128 v[190:193], v190 offset:3072
	v_lshl_add_u64 v[226:227], s[26:27], 0, v[136:137]
	s_add_i32 m0, s30, 0xc000
	ds_read_b128 v[194:197], v147
	ds_read_b128 v[198:201], v147 offset:1024
	ds_read_b128 v[202:205], v147 offset:2048
	ds_read_b128 v[206:209], v147 offset:3072
	ds_read_b128 v[210:213], v147 offset:4096
	ds_read_b128 v[214:217], v147 offset:5120
	ds_read_b128 v[218:221], v147 offset:6144
	ds_read_b128 v[222:225], v147 offset:7168
	global_load_lds_dwordx4 v[226:227], off
	v_lshl_add_u64 v[226:227], s[26:27], 0, v[138:139]
	s_add_i32 m0, s30, 0xe000
	s_nop 0
	global_load_lds_dwordx4 v[226:227], off
	s_waitcnt vmcnt(8)
	s_waitcnt lgkmcnt(0)
	s_barrier
	s_waitcnt lgkmcnt(0)
	v_mfma_f32_16x16x32_bf16 v[126:129], v[140:143], v[194:197], v[126:129]
	v_mfma_f32_16x16x32_bf16 v[122:125], v[152:155], v[194:197], v[122:125]
	v_mfma_f32_16x16x32_bf16 v[118:121], v[140:143], v[202:205], v[118:121]
	v_mfma_f32_16x16x32_bf16 v[114:117], v[152:155], v[202:205], v[114:117]
	v_mfma_f32_16x16x32_bf16 v[94:97], v[140:143], v[210:213], v[94:97]
	v_mfma_f32_16x16x32_bf16 v[90:93], v[152:155], v[210:213], v[90:93]
	v_mfma_f32_16x16x32_bf16 v[86:89], v[140:143], v[218:221], v[86:89]
	v_mfma_f32_16x16x32_bf16 v[82:85], v[152:155], v[218:221], v[82:85]
	v_mfma_f32_16x16x32_bf16 v[126:129], v[148:151], v[198:201], v[126:129]
	v_mfma_f32_16x16x32_bf16 v[122:125], v[156:159], v[198:201], v[122:125]
	v_mfma_f32_16x16x32_bf16 v[118:121], v[148:151], v[206:209], v[118:121]
	v_mfma_f32_16x16x32_bf16 v[114:117], v[156:159], v[206:209], v[114:117]
	v_mfma_f32_16x16x32_bf16 v[94:97], v[148:151], v[214:217], v[94:97]
	v_mfma_f32_16x16x32_bf16 v[90:93], v[156:159], v[214:217], v[90:93]
	v_mfma_f32_16x16x32_bf16 v[86:89], v[148:151], v[222:225], v[86:89]
	v_mfma_f32_16x16x32_bf16 v[82:85], v[156:159], v[222:225], v[82:85]
	v_mfma_f32_16x16x32_bf16 v[110:113], v[160:163], v[194:197], v[110:113]
	v_mfma_f32_16x16x32_bf16 v[106:109], v[186:189], v[194:197], v[106:109]
	v_mfma_f32_16x16x32_bf16 v[102:105], v[160:163], v[202:205], v[102:105]
	v_mfma_f32_16x16x32_bf16 v[98:101], v[186:189], v[202:205], v[98:101]
	v_mfma_f32_16x16x32_bf16 v[78:81], v[160:163], v[210:213], v[78:81]
	v_mfma_f32_16x16x32_bf16 v[74:77], v[186:189], v[210:213], v[74:77]
	v_mfma_f32_16x16x32_bf16 v[70:73], v[160:163], v[218:221], v[70:73]
	v_mfma_f32_16x16x32_bf16 v[66:69], v[186:189], v[218:221], v[66:69]
	v_mfma_f32_16x16x32_bf16 v[110:113], v[182:185], v[198:201], v[110:113]
	v_mfma_f32_16x16x32_bf16 v[106:109], v[190:193], v[198:201], v[106:109]
	v_mfma_f32_16x16x32_bf16 v[102:105], v[182:185], v[206:209], v[102:105]
	v_mfma_f32_16x16x32_bf16 v[98:101], v[190:193], v[206:209], v[98:101]
	v_mfma_f32_16x16x32_bf16 v[78:81], v[182:185], v[214:217], v[78:81]
	v_mfma_f32_16x16x32_bf16 v[74:77], v[190:193], v[214:217], v[74:77]
	v_mfma_f32_16x16x32_bf16 v[70:73], v[182:185], v[222:225], v[70:73]
	v_mfma_f32_16x16x32_bf16 v[66:69], v[190:193], v[222:225], v[66:69]
	s_barrier
	s_add_i32 s59, s59, s14
	v_lshl_add_u64 v[226:227], s[38:39], 0, v[0:1]
	s_mov_b32 m0, s59
	ds_read_b128 v[194:197], v147 offset:16384
	ds_read_b128 v[198:201], v147 offset:17408
	ds_read_b128 v[202:205], v147 offset:18432
	ds_read_b128 v[206:209], v147 offset:19456
	ds_read_b128 v[210:213], v147 offset:20480
	ds_read_b128 v[214:217], v147 offset:21504
	ds_read_b128 v[218:221], v147 offset:22528
	ds_read_b128 v[222:225], v147 offset:23552
	global_load_lds_dwordx4 v[226:227], off
	s_add_i32 m0, s59, 0x2000
	s_add_u32 s64, s38, 0x40000
	v_lshl_add_u64 v[228:229], s[38:39], 0, v[130:131]
	s_addc_u32 s65, s39, 0
	s_add_i32 s37, s37, s14
	global_load_lds_dwordx4 v[228:229], off
	v_lshl_add_u64 v[230:231], s[64:65], 0, v[0:1]
	s_mov_b32 m0, s37
	v_lshl_add_u64 v[234:235], s[40:41], 0, v[132:133]
	global_load_lds_dwordx4 v[230:231], off
	v_lshl_add_u64 v[230:231], s[64:65], 0, v[130:131]
	s_add_i32 m0, s37, 0x2000
	s_nop 0
	global_load_lds_dwordx4 v[230:231], off
	v_lshl_add_u64 v[230:231], s[40:41], 0, v[134:135]
	s_mov_b32 m0, s30
	s_nop 0
	global_load_lds_dwordx4 v[230:231], off
	s_mov_b32 m0, s31
	s_nop 0
	global_load_lds_dwordx4 v[234:235], off
	s_waitcnt vmcnt(8)
	s_waitcnt lgkmcnt(0)
	s_barrier
; #define PG8_STAGE(bufoff, gbase, voff) do { _Pragma("unroll") for (int _i = 0; _i < 2; ++_i) \
;         __builtin_amdgcn_global_load_lds((const unsigned*)((const char*)(gbase) + (voff)[_i]), (PG8_LAS unsigned*)(lds + (bufoff) + ldsw + _i * 8192), 16, 0, 0); } while (0)
; #define PG8_LDA(dst, b, h) do { _Pragma("unroll") for (int m = 0; m < 4; ++m) _Pragma("unroll") for (int k = 0; k < 2; ++k) dst[m][k] = *(const PG8_LAS bf16x8*)(lds + PG8_SA(b, h) + aoff + m * 2048 + k * 1024); } while (0)
; #define PG8_LDB(dst, b, h) do { _Pragma("unroll") for (int n = 0; n < 2; ++n) _Pragma("unroll") for (int k = 0; k < 2; ++k) dst[n][k] = *(const PG8_LAS bf16x8*)(lds + PG8_SB(b, h) + boff + n * 2048 + k * 1024); } while (0)
; #define PG8_MMA(ai, bj, At, Bt) do { __builtin_amdgcn_s_setprio(1); _Pragma("unroll") for (int m = 0; m < 4; ++m) _Pragma("unroll") for (int n = 0; n < 2; ++n) _Pragma("unroll") for (int k = 0; k < 2; ++k) \
;         acc[ai][bj][m][n] = mma16<Epi::F16A>(Bt[n][k], At[m][k], acc[ai][bj][m][n]); __builtin_amdgcn_s_setprio(0); } while (0)
; #define PG8_WAIT_V(n) asm volatile("s_waitcnt vmcnt(" #n ")" ::: "memory")
; #define PG8_WAIT_L(n) asm volatile("s_waitcnt lgkmcnt(" #n ")" ::: "memory")
; #define PG8_BAR __builtin_amdgcn_s_barrier()
; #define PG8_SCHED __builtin_amdgcn_sched_barrier(0)
; template <class Epi, class Sched, bool ALIGN_EPI = false, bool SP2 = false>
; __device__ __forceinline__ void gemm_phase(PG8_LAS unsigned char* lds, const Gemm g, const Sched& S, const Epi& E) {
;     ...
;             PG8_WAIT_V(8); PG8_WAIT_L(0); PG8_BAR; PG8_MMA(1, 0, At, B0); PG8_MMA(1, 1, At, B1); PG8_BAR; PG8_SCHED;
;             PG8_LDB(B0, 1, 0); PG8_LDB(B1, 1, 1); PG8_SCHED; PG8_LDA(At, 1, 0); PG8_STAGE(PG8_SA(0, 1), a2 + hstep, voffA);
;             PG8_WAIT_V(8); PG8_WAIT_L(0); PG8_BAR; PG8_MMA(0, 0, At, B0); PG8_MMA(0, 1, At, B1); PG8_BAR; PG8_SCHED;
	s_waitcnt lgkmcnt(0)
	v_mfma_f32_16x16x32_bf16 v[62:65], v[140:143], v[194:197], v[62:65]
	v_mfma_f32_16x16x32_bf16 v[58:61], v[152:155], v[194:197], v[58:61]
	v_mfma_f32_16x16x32_bf16 v[54:57], v[140:143], v[202:205], v[54:57]
	v_mfma_f32_16x16x32_bf16 v[50:53], v[152:155], v[202:205], v[50:53]
	v_mfma_f32_16x16x32_bf16 v[30:33], v[140:143], v[210:213], v[30:33]
	v_mfma_f32_16x16x32_bf16 v[26:29], v[152:155], v[210:213], v[26:29]
	v_mfma_f32_16x16x32_bf16 v[22:25], v[140:143], v[218:221], v[22:25]
	v_mfma_f32_16x16x32_bf16 v[18:21], v[152:155], v[218:221], v[18:21]
	v_mfma_f32_16x16x32_bf16 v[62:65], v[148:151], v[198:201], v[62:65]
	v_mfma_f32_16x16x32_bf16 v[58:61], v[156:159], v[198:201], v[58:61]
	v_mfma_f32_16x16x32_bf16 v[54:57], v[148:151], v[206:209], v[54:57]
	v_mfma_f32_16x16x32_bf16 v[50:53], v[156:159], v[206:209], v[50:53]
	v_mfma_f32_16x16x32_bf16 v[30:33], v[148:151], v[214:217], v[30:33]
	v_mfma_f32_16x16x32_bf16 v[26:29], v[156:159], v[214:217], v[26:29]
	v_mfma_f32_16x16x32_bf16 v[22:25], v[148:151], v[222:225], v[22:25]
	v_mfma_f32_16x16x32_bf16 v[18:21], v[156:159], v[222:225], v[18:21]
	v_mfma_f32_16x16x32_bf16 v[46:49], v[160:163], v[194:197], v[46:49]
	v_mfma_f32_16x16x32_bf16 v[42:45], v[186:189], v[194:197], v[42:45]
	v_mfma_f32_16x16x32_bf16 v[38:41], v[160:163], v[202:205], v[38:41]
	v_mfma_f32_16x16x32_bf16 v[34:37], v[186:189], v[202:205], v[34:37]
	v_mfma_f32_16x16x32_bf16 v[14:17], v[160:163], v[210:213], v[14:17]
	v_mfma_f32_16x16x32_bf16 v[10:13], v[186:189], v[210:213], v[10:13]
	v_mfma_f32_16x16x32_bf16 v[6:9], v[160:163], v[218:221], v[6:9]
	v_mfma_f32_16x16x32_bf16 v[2:5], v[186:189], v[218:221], v[2:5]
	v_mfma_f32_16x16x32_bf16 v[46:49], v[182:185], v[198:201], v[46:49]
	v_mfma_f32_16x16x32_bf16 v[42:45], v[190:193], v[198:201], v[42:45]
	v_mfma_f32_16x16x32_bf16 v[38:41], v[182:185], v[206:209], v[38:41]
	v_mfma_f32_16x16x32_bf16 v[34:37], v[190:193], v[206:209], v[34:37]
	v_mfma_f32_16x16x32_bf16 v[14:17], v[182:185], v[214:217], v[14:17]
	v_mfma_f32_16x16x32_bf16 v[10:13], v[190:193], v[214:217], v[10:13]
	v_mfma_f32_16x16x32_bf16 v[6:9], v[182:185], v[222:225], v[6:9]
	v_mfma_f32_16x16x32_bf16 v[2:5], v[190:193], v[222:225], v[2:5]
	s_barrier
	s_add_i32 s37, 0, 0x18000
	s_add_i32 s59, 0, 0x1c000
	v_add_u32_e32 v156, s37, v146
	v_add_u32_e32 v190, s59, v146
	ds_read_b128 v[140:143], v156
	ds_read_b128 v[148:151], v156 offset:1024
	ds_read_b128 v[152:155], v156 offset:2048
	ds_read_b128 v[156:159], v156 offset:3072
	ds_read_b128 v[160:163], v190
	ds_read_b128 v[182:185], v190 offset:1024
	ds_read_b128 v[186:189], v190 offset:2048
	ds_read_b128 v[190:193], v190 offset:3072
	s_add_u32 s40, s40, 0x40000
	s_addc_u32 s41, s41, 0
	s_mov_b32 m0, s33
	v_lshl_add_u64 v[236:237], s[40:41], 0, v[134:135]
	ds_read_b128 v[194:197], v147 offset:32768
	ds_read_b128 v[198:201], v147 offset:33792
	ds_read_b128 v[202:205], v147 offset:34816
	ds_read_b128 v[206:209], v147 offset:35840
	ds_read_b128 v[210:213], v147 offset:36864
	ds_read_b128 v[214:217], v147 offset:37888
	ds_read_b128 v[218:221], v147 offset:38912
	ds_read_b128 v[222:225], v147 offset:39936
	global_load_lds_dwordx4 v[236:237], off
	v_lshl_add_u64 v[236:237], s[40:41], 0, v[132:133]
	s_mov_b32 m0, s36
	s_nop 0
	global_load_lds_dwordx4 v[236:237], off
	s_waitcnt vmcnt(8)
	s_waitcnt lgkmcnt(0)
	s_barrier
	s_waitcnt lgkmcnt(0)
	v_mfma_f32_16x16x32_bf16 v[126:129], v[140:143], v[194:197], v[126:129]
	v_mfma_f32_16x16x32_bf16 v[122:125], v[152:155], v[194:197], v[122:125]
	v_mfma_f32_16x16x32_bf16 v[118:121], v[140:143], v[202:205], v[118:121]
	v_mfma_f32_16x16x32_bf16 v[114:117], v[152:155], v[202:205], v[114:117]
	v_mfma_f32_16x16x32_bf16 v[94:97], v[140:143], v[210:213], v[94:97]
	v_mfma_f32_16x16x32_bf16 v[90:93], v[152:155], v[210:213], v[90:93]
	v_mfma_f32_16x16x32_bf16 v[86:89], v[140:143], v[218:221], v[86:89]
	v_mfma_f32_16x16x32_bf16 v[82:85], v[152:155], v[218:221], v[82:85]
	v_mfma_f32_16x16x32_bf16 v[126:129], v[148:151], v[198:201], v[126:129]
	v_mfma_f32_16x16x32_bf16 v[122:125], v[156:159], v[198:201], v[122:125]
	v_mfma_f32_16x16x32_bf16 v[118:121], v[148:151], v[206:209], v[118:121]
	v_mfma_f32_16x16x32_bf16 v[114:117], v[156:159], v[206:209], v[114:117]
	v_mfma_f32_16x16x32_bf16 v[94:97], v[148:151], v[214:217], v[94:97]
	v_mfma_f32_16x16x32_bf16 v[90:93], v[156:159], v[214:217], v[90:93]
	v_mfma_f32_16x16x32_bf16 v[86:89], v[148:151], v[222:225], v[86:89]
	v_mfma_f32_16x16x32_bf16 v[82:85], v[156:159], v[222:225], v[82:85]
	v_mfma_f32_16x16x32_bf16 v[110:113], v[160:163], v[194:197], v[110:113]
	v_mfma_f32_16x16x32_bf16 v[106:109], v[186:189], v[194:197], v[106:109]
	v_mfma_f32_16x16x32_bf16 v[102:105], v[160:163], v[202:205], v[102:105]
	v_mfma_f32_16x16x32_bf16 v[98:101], v[186:189], v[202:205], v[98:101]
	v_mfma_f32_16x16x32_bf16 v[78:81], v[160:163], v[210:213], v[78:81]
	v_mfma_f32_16x16x32_bf16 v[74:77], v[186:189], v[210:213], v[74:77]
	v_mfma_f32_16x16x32_bf16 v[70:73], v[160:163], v[218:221], v[70:73]
	v_mfma_f32_16x16x32_bf16 v[66:69], v[186:189], v[218:221], v[66:69]
	v_mfma_f32_16x16x32_bf16 v[110:113], v[182:185], v[198:201], v[110:113]
	v_mfma_f32_16x16x32_bf16 v[106:109], v[190:193], v[198:201], v[106:109]
	v_mfma_f32_16x16x32_bf16 v[102:105], v[182:185], v[206:209], v[102:105]
	v_mfma_f32_16x16x32_bf16 v[98:101], v[190:193], v[206:209], v[98:101]
	v_mfma_f32_16x16x32_bf16 v[78:81], v[182:185], v[214:217], v[78:81]
	v_mfma_f32_16x16x32_bf16 v[74:77], v[190:193], v[214:217], v[74:77]
	v_mfma_f32_16x16x32_bf16 v[70:73], v[182:185], v[222:225], v[70:73]
	v_mfma_f32_16x16x32_bf16 v[66:69], v[190:193], v[222:225], v[66:69]
	s_barrier
; #define PG8_STAGE(bufoff, gbase, voff) do { _Pragma("unroll") for (int _i = 0; _i < 2; ++_i) \
;         __builtin_amdgcn_global_load_lds((const unsigned*)((const char*)(gbase) + (voff)[_i]), (PG8_LAS unsigned*)(lds + (bufoff) + ldsw + _i * 8192), 16, 0, 0); } while (0)
; #define PG8_LDA(dst, b, h) do { _Pragma("unroll") for (int m = 0; m < 4; ++m) _Pragma("unroll") for (int k = 0; k < 2; ++k) dst[m][k] = *(const PG8_LAS bf16x8*)(lds + PG8_SA(b, h) + aoff + m * 2048 + k * 1024); } while (0)
; #define PG8_MMA(ai, bj, At, Bt) do { __builtin_amdgcn_s_setprio(1); _Pragma("unroll") for (int m = 0; m < 4; ++m) _Pragma("unroll") for (int n = 0; n < 2; ++n) _Pragma("unroll") for (int k = 0; k < 2; ++k) \
;         acc[ai][bj][m][n] = mma16<Epi::F16A>(Bt[n][k], At[m][k], acc[ai][bj][m][n]); __builtin_amdgcn_s_setprio(0); } while (0)
; #define PG8_WAIT_V(n) asm volatile("s_waitcnt vmcnt(" #n ")" ::: "memory")
; #define PG8_WAIT_L(n) asm volatile("s_waitcnt lgkmcnt(" #n ")" ::: "memory")
; #define PG8_BAR __builtin_amdgcn_s_barrier()
; #define PG8_SCHED __builtin_amdgcn_sched_barrier(0)
; template <class Epi, class Sched, bool ALIGN_EPI = false, bool SP2 = false>
; __device__ __forceinline__ void gemm_phase(PG8_LAS unsigned char* lds, const Gemm g, const Sched& S, const Epi& E) {
;     ...
;             PG8_WAIT_V(8); PG8_WAIT_L(0); PG8_BAR; PG8_MMA(0, 0, At, B0); PG8_MMA(0, 1, At, B1); PG8_BAR; PG8_SCHED;
;             PG8_LDA(At, 1, 1); PG8_STAGE(PG8_SB(1, 0), b3, voffB); PG8_STAGE(PG8_SB(1, 1), b3 + hstep, voffB); PG8_STAGE(PG8_SA(1, 0), a3, voffA);
;             PG8_WAIT_V(8); PG8_WAIT_L(0); PG8_BAR; PG8_MMA(1, 0, At, B0); PG8_MMA(1, 1, At, B1); PG8_BAR; PG8_SCHED;
;     ...
;         if constexpr (ALIGN_EPI) { if (wr == 0) PG8_BAR; }
	s_add_i32 s37, s37, s14
	v_lshl_add_u64 v[226:227], v[226:227], 0, s[92:93]
	s_mov_b32 m0, s37
	ds_read_b128 v[194:197], v147 offset:49152
	ds_read_b128 v[198:201], v147 offset:50176
	ds_read_b128 v[202:205], v147 offset:51200
	ds_read_b128 v[206:209], v147 offset:52224
	ds_read_b128 v[210:213], v147 offset:53248
	ds_read_b128 v[214:217], v147 offset:54272
	ds_read_b128 v[218:221], v147 offset:55296
	ds_read_b128 v[222:225], v147 offset:56320
	global_load_lds_dwordx4 v[226:227], off
	s_add_i32 m0, s37, 0x2000
	s_add_u32 s38, s38, 0x40080
	v_lshl_add_u64 v[226:227], v[228:229], 0, s[92:93]
	s_addc_u32 s39, s39, 0
	s_add_i32 s37, s59, s14
	global_load_lds_dwordx4 v[226:227], off
	v_lshl_add_u64 v[226:227], s[38:39], 0, v[0:1]
	s_mov_b32 m0, s37
	s_nop 0
	global_load_lds_dwordx4 v[226:227], off
	v_lshl_add_u64 v[226:227], s[38:39], 0, v[130:131]
	s_add_i32 m0, s37, 0x2000
	s_nop 0
	global_load_lds_dwordx4 v[226:227], off
	v_lshl_add_u64 v[226:227], v[230:231], 0, s[92:93]
	s_mov_b32 m0, s45
	s_nop 0
	global_load_lds_dwordx4 v[226:227], off
	v_lshl_add_u64 v[226:227], v[234:235], 0, s[92:93]
	s_mov_b32 m0, s46
	s_nop 0
	global_load_lds_dwordx4 v[226:227], off
	s_waitcnt vmcnt(8)
	s_waitcnt lgkmcnt(0)
	s_barrier
	s_waitcnt lgkmcnt(0)
	v_mfma_f32_16x16x32_bf16 v[62:65], v[140:143], v[194:197], v[62:65]
	v_mfma_f32_16x16x32_bf16 v[58:61], v[152:155], v[194:197], v[58:61]
	v_mfma_f32_16x16x32_bf16 v[54:57], v[140:143], v[202:205], v[54:57]
	v_mfma_f32_16x16x32_bf16 v[50:53], v[152:155], v[202:205], v[50:53]
	v_mfma_f32_16x16x32_bf16 v[30:33], v[140:143], v[210:213], v[30:33]
	v_mfma_f32_16x16x32_bf16 v[26:29], v[152:155], v[210:213], v[26:29]
	v_mfma_f32_16x16x32_bf16 v[22:25], v[140:143], v[218:221], v[22:25]
	v_mfma_f32_16x16x32_bf16 v[18:21], v[152:155], v[218:221], v[18:21]
	v_mfma_f32_16x16x32_bf16 v[62:65], v[148:151], v[198:201], v[62:65]
	v_mfma_f32_16x16x32_bf16 v[58:61], v[156:159], v[198:201], v[58:61]
	v_mfma_f32_16x16x32_bf16 v[54:57], v[148:151], v[206:209], v[54:57]
	v_mfma_f32_16x16x32_bf16 v[50:53], v[156:159], v[206:209], v[50:53]
	v_mfma_f32_16x16x32_bf16 v[30:33], v[148:151], v[214:217], v[30:33]
	v_mfma_f32_16x16x32_bf16 v[26:29], v[156:159], v[214:217], v[26:29]
	v_mfma_f32_16x16x32_bf16 v[22:25], v[148:151], v[222:225], v[22:25]
	v_mfma_f32_16x16x32_bf16 v[18:21], v[156:159], v[222:225], v[18:21]
	v_mfma_f32_16x16x32_bf16 v[46:49], v[160:163], v[194:197], v[46:49]
	v_mfma_f32_16x16x32_bf16 v[42:45], v[186:189], v[194:197], v[42:45]
	v_mfma_f32_16x16x32_bf16 v[38:41], v[160:163], v[202:205], v[38:41]
	v_mfma_f32_16x16x32_bf16 v[34:37], v[186:189], v[202:205], v[34:37]
	v_mfma_f32_16x16x32_bf16 v[14:17], v[160:163], v[210:213], v[14:17]
	v_mfma_f32_16x16x32_bf16 v[10:13], v[186:189], v[210:213], v[10:13]
	v_mfma_f32_16x16x32_bf16 v[6:9], v[160:163], v[218:221], v[6:9]
	v_mfma_f32_16x16x32_bf16 v[2:5], v[186:189], v[218:221], v[2:5]
	v_mfma_f32_16x16x32_bf16 v[46:49], v[182:185], v[198:201], v[46:49]
	v_mfma_f32_16x16x32_bf16 v[42:45], v[190:193], v[198:201], v[42:45]
	v_mfma_f32_16x16x32_bf16 v[38:41], v[182:185], v[206:209], v[38:41]
	v_mfma_f32_16x16x32_bf16 v[34:37], v[190:193], v[206:209], v[34:37]
	v_mfma_f32_16x16x32_bf16 v[14:17], v[182:185], v[214:217], v[14:17]
	v_mfma_f32_16x16x32_bf16 v[10:13], v[190:193], v[214:217], v[10:13]
	v_mfma_f32_16x16x32_bf16 v[6:9], v[182:185], v[222:225], v[6:9]
	v_mfma_f32_16x16x32_bf16 v[2:5], v[190:193], v[222:225], v[2:5]
	s_barrier
	s_add_i32 s57, s57, 2
	s_add_u32 s26, s26, 0x100
	s_addc_u32 s27, s27, 0
	s_add_u32 s54, s54, 0x100
	s_addc_u32 s55, s55, 0
	s_cmp_gt_u32 s57, 13
	s_cbranch_scc0 .LBB0_286
	s_and_b64 vcc, exec, s[6:7]
	s_cbranch_vccz .LBB0_289
	s_barrier

; #define PG8_STAGE(bufoff, gbase, voff) do { _Pragma("unroll") for (int _i = 0; _i < 2; ++_i) \
;         __builtin_amdgcn_global_load_lds((const unsigned*)((const char*)(gbase) + (voff)[_i]), (PG8_LAS unsigned*)(lds + (bufoff) + ldsw + _i * 8192), 16, 0, 0); } while (0)
; #define PG8_LDA(dst, b, h) do { _Pragma("unroll") for (int m = 0; m < 4; ++m) _Pragma("unroll") for (int k = 0; k < 2; ++k) dst[m][k] = *(const PG8_LAS bf16x8*)(lds + PG8_SA(b, h) + aoff + m * 2048 + k * 1024); } while (0)
; #define PG8_LDB(dst, b, h) do { _Pragma("unroll") for (int n = 0; n < 2; ++n) _Pragma("unroll") for (int k = 0; k < 2; ++k) dst[n][k] = *(const PG8_LAS bf16x8*)(lds + PG8_SB(b, h) + boff + n * 2048 + k * 1024); } while (0)
; #define PG8_MMA(ai, bj, At, Bt) do { __builtin_amdgcn_s_setprio(1); _Pragma("unroll") for (int m = 0; m < 4; ++m) _Pragma("unroll") for (int n = 0; n < 2; ++n) _Pragma("unroll") for (int k = 0; k < 2; ++k) \
;         acc[ai][bj][m][n] = mma16<Epi::F16A>(Bt[n][k], At[m][k], acc[ai][bj][m][n]); __builtin_amdgcn_s_setprio(0); } while (0)
; #define PG8_WAIT_V(n) asm volatile("s_waitcnt vmcnt(" #n ")" ::: "memory")
; #define PG8_WAIT_L(n) asm volatile("s_waitcnt lgkmcnt(" #n ")" ::: "memory")
; #define PG8_BAR __builtin_amdgcn_s_barrier()
; #define PG8_SCHED __builtin_amdgcn_sched_barrier(0)
; template <class Epi, class Sched, bool ALIGN_EPI = false, bool SP2 = false>
; __device__ __forceinline__ void gemm_phase(PG8_LAS unsigned char* lds, const Gemm g, const Sched& S, const Epi& E) {
;     ...
;             PG8_LDB(B0, 0, 0); PG8_LDB(B1, 0, 1); PG8_SCHED; PG8_LDA(At, 0, 0); PG8_STAGE(PG8_SA(1, 1), a1 + hstep, voffA);
;             PG8_WAIT_V(8); PG8_WAIT_L(0); PG8_BAR; PG8_MMA(0, 0, At, B0); PG8_MMA(0, 1, At, B1); PG8_BAR; PG8_SCHED;
;             PG8_LDA(At, 0, 1); PG8_STAGE(PG8_SB(0, 0), b2, voffB); PG8_STAGE(PG8_SB(0, 1), b2 + hstep, voffB); PG8_STAGE(PG8_SA(0, 0), a2, voffA);
;             PG8_WAIT_V(8); PG8_WAIT_L(0); PG8_BAR; PG8_MMA(1, 0, At, B0); PG8_MMA(1, 1, At, B1); PG8_BAR; PG8_SCHED;
.LBB0_326:
	s_add_u32 s22, s20, 0xfffc0080
	s_addc_u32 s23, s21, -1
	s_add_i32 s37, 0, 0x10000
	s_cmp_eq_u32 s70, 12
	s_cselect_b32 s25, s31, s23
	s_cselect_b32 s24, s39, s22
	s_cselect_b32 s23, s17, s69
	s_cselect_b32 s22, s43, s62
	s_add_i32 s71, 0, 0x14000
	v_add_u32_e32 v154, s37, v160
	v_add_u32_e32 v162, s71, v160
	ds_read_b128 v[142:145], v154
	ds_read_b128 v[146:149], v154 offset:1024
	ds_read_b128 v[150:153], v154 offset:2048
	ds_read_b128 v[154:157], v154 offset:3072
	ds_read_b128 v[182:185], v162
	ds_read_b128 v[186:189], v162 offset:1024
	ds_read_b128 v[190:193], v162 offset:2048
	ds_read_b128 v[194:197], v162 offset:3072
	v_lshl_add_u64 v[162:163], s[20:21], 0, v[138:139]
	s_add_i32 m0, s27, 0xc000
	ds_read_b128 v[198:201], v161
	ds_read_b128 v[202:205], v161 offset:1024
	ds_read_b128 v[206:209], v161 offset:2048
	ds_read_b128 v[210:213], v161 offset:3072
	ds_read_b128 v[214:217], v161 offset:4096
	ds_read_b128 v[218:221], v161 offset:5120
	ds_read_b128 v[222:225], v161 offset:6144
	ds_read_b128 v[226:229], v161 offset:7168
	global_load_lds_dwordx4 v[162:163], off
	v_lshl_add_u64 v[162:163], s[20:21], 0, v[140:141]
	s_add_i32 m0, s27, 0xe000
	s_nop 0
	global_load_lds_dwordx4 v[162:163], off
	s_waitcnt vmcnt(8)
	s_waitcnt lgkmcnt(0)
	s_barrier
	s_waitcnt lgkmcnt(0)
	v_mfma_f32_16x16x32_bf16 v[126:129], v[142:145], v[198:201], v[126:129]
	v_mfma_f32_16x16x32_bf16 v[122:125], v[150:153], v[198:201], v[122:125]
	v_mfma_f32_16x16x32_bf16 v[118:121], v[142:145], v[206:209], v[118:121]
	v_mfma_f32_16x16x32_bf16 v[110:113], v[150:153], v[206:209], v[110:113]
	v_mfma_f32_16x16x32_bf16 v[102:105], v[142:145], v[214:217], v[102:105]
	v_mfma_f32_16x16x32_bf16 v[94:97], v[150:153], v[214:217], v[94:97]
	v_mfma_f32_16x16x32_bf16 v[86:89], v[142:145], v[222:225], v[86:89]
	v_mfma_f32_16x16x32_bf16 v[78:81], v[150:153], v[222:225], v[78:81]
	v_mfma_f32_16x16x32_bf16 v[126:129], v[146:149], v[202:205], v[126:129]
	v_mfma_f32_16x16x32_bf16 v[122:125], v[154:157], v[202:205], v[122:125]
	v_mfma_f32_16x16x32_bf16 v[118:121], v[146:149], v[210:213], v[118:121]
	v_mfma_f32_16x16x32_bf16 v[110:113], v[154:157], v[210:213], v[110:113]
	v_mfma_f32_16x16x32_bf16 v[102:105], v[146:149], v[218:221], v[102:105]
	v_mfma_f32_16x16x32_bf16 v[94:97], v[154:157], v[218:221], v[94:97]
	v_mfma_f32_16x16x32_bf16 v[86:89], v[146:149], v[226:229], v[86:89]
	v_mfma_f32_16x16x32_bf16 v[78:81], v[154:157], v[226:229], v[78:81]
	v_mfma_f32_16x16x32_bf16 v[114:117], v[182:185], v[198:201], v[114:117]
	v_mfma_f32_16x16x32_bf16 v[106:109], v[190:193], v[198:201], v[106:109]
	v_mfma_f32_16x16x32_bf16 v[98:101], v[182:185], v[206:209], v[98:101]
	v_mfma_f32_16x16x32_bf16 v[90:93], v[190:193], v[206:209], v[90:93]
	v_mfma_f32_16x16x32_bf16 v[82:85], v[182:185], v[214:217], v[82:85]
	v_mfma_f32_16x16x32_bf16 v[74:77], v[190:193], v[214:217], v[74:77]
	v_mfma_f32_16x16x32_bf16 v[70:73], v[182:185], v[222:225], v[70:73]
	v_mfma_f32_16x16x32_bf16 v[66:69], v[190:193], v[222:225], v[66:69]
	v_mfma_f32_16x16x32_bf16 v[114:117], v[186:189], v[202:205], v[114:117]
	v_mfma_f32_16x16x32_bf16 v[106:109], v[194:197], v[202:205], v[106:109]
	v_mfma_f32_16x16x32_bf16 v[98:101], v[186:189], v[210:213], v[98:101]
	v_mfma_f32_16x16x32_bf16 v[90:93], v[194:197], v[210:213], v[90:93]
	v_mfma_f32_16x16x32_bf16 v[82:85], v[186:189], v[218:221], v[82:85]
	v_mfma_f32_16x16x32_bf16 v[74:77], v[194:197], v[218:221], v[74:77]
	v_mfma_f32_16x16x32_bf16 v[70:73], v[186:189], v[226:229], v[70:73]
	v_mfma_f32_16x16x32_bf16 v[66:69], v[194:197], v[226:229], v[66:69]
	s_barrier
	s_add_i32 s37, s37, s14
	v_lshl_add_u64 v[162:163], s[22:23], 0, v[0:1]
	s_mov_b32 m0, s37
	ds_read_b128 v[198:201], v161 offset:16384
	ds_read_b128 v[202:205], v161 offset:17408
	ds_read_b128 v[206:209], v161 offset:18432
	ds_read_b128 v[210:213], v161 offset:19456
	ds_read_b128 v[214:217], v161 offset:20480
	ds_read_b128 v[218:221], v161 offset:21504
	ds_read_b128 v[222:225], v161 offset:22528
	ds_read_b128 v[226:229], v161 offset:23552
	global_load_lds_dwordx4 v[162:163], off
	s_add_i32 m0, s37, 0x2000
	s_add_u32 s76, s22, 0x40000
	v_lshl_add_u64 v[230:231], s[22:23], 0, v[132:133]
	s_addc_u32 s77, s23, 0
	s_add_i32 s37, s71, s14
	global_load_lds_dwordx4 v[230:231], off
	v_lshl_add_u64 v[234:235], s[76:77], 0, v[0:1]
	s_mov_b32 m0, s37
	v_lshl_add_u64 v[236:237], s[24:25], 0, v[134:135]
	global_load_lds_dwordx4 v[234:235], off
	v_lshl_add_u64 v[234:235], s[76:77], 0, v[132:133]
	s_add_i32 m0, s37, 0x2000
	s_nop 0
	global_load_lds_dwordx4 v[234:235], off
	v_lshl_add_u64 v[234:235], s[24:25], 0, v[136:137]
	s_mov_b32 m0, s27
	s_nop 0
	global_load_lds_dwordx4 v[234:235], off
	s_mov_b32 m0, s28
	s_nop 0
	global_load_lds_dwordx4 v[236:237], off
	s_waitcnt vmcnt(8)
	s_waitcnt lgkmcnt(0)
	s_barrier
; #define PG8_STAGE(bufoff, gbase, voff) do { _Pragma("unroll") for (int _i = 0; _i < 2; ++_i) \
;         __builtin_amdgcn_global_load_lds((const unsigned*)((const char*)(gbase) + (voff)[_i]), (PG8_LAS unsigned*)(lds + (bufoff) + ldsw + _i * 8192), 16, 0, 0); } while (0)
; #define PG8_LDA(dst, b, h) do { _Pragma("unroll") for (int m = 0; m < 4; ++m) _Pragma("unroll") for (int k = 0; k < 2; ++k) dst[m][k] = *(const PG8_LAS bf16x8*)(lds + PG8_SA(b, h) + aoff + m * 2048 + k * 1024); } while (0)
; #define PG8_LDB(dst, b, h) do { _Pragma("unroll") for (int n = 0; n < 2; ++n) _Pragma("unroll") for (int k = 0; k < 2; ++k) dst[n][k] = *(const PG8_LAS bf16x8*)(lds + PG8_SB(b, h) + boff + n * 2048 + k * 1024); } while (0)
; #define PG8_MMA(ai, bj, At, Bt) do { __builtin_amdgcn_s_setprio(1); _Pragma("unroll") for (int m = 0; m < 4; ++m) _Pragma("unroll") for (int n = 0; n < 2; ++n) _Pragma("unroll") for (int k = 0; k < 2; ++k) \
;         acc[ai][bj][m][n] = mma16<Epi::F16A>(Bt[n][k], At[m][k], acc[ai][bj][m][n]); __builtin_amdgcn_s_setprio(0); } while (0)
; #define PG8_WAIT_V(n) asm volatile("s_waitcnt vmcnt(" #n ")" ::: "memory")
; #define PG8_WAIT_L(n) asm volatile("s_waitcnt lgkmcnt(" #n ")" ::: "memory")
; #define PG8_BAR __builtin_amdgcn_s_barrier()
; #define PG8_SCHED __builtin_amdgcn_sched_barrier(0)
; template <class Epi, class Sched, bool ALIGN_EPI = false, bool SP2 = false>
; __device__ __forceinline__ void gemm_phase(PG8_LAS unsigned char* lds, const Gemm g, const Sched& S, const Epi& E) {
;     ...
;             PG8_WAIT_V(8); PG8_WAIT_L(0); PG8_BAR; PG8_MMA(1, 0, At, B0); PG8_MMA(1, 1, At, B1); PG8_BAR; PG8_SCHED;
;             PG8_LDB(B0, 1, 0); PG8_LDB(B1, 1, 1); PG8_SCHED; PG8_LDA(At, 1, 0); PG8_STAGE(PG8_SA(0, 1), a2 + hstep, voffA);
;             PG8_WAIT_V(8); PG8_WAIT_L(0); PG8_BAR; PG8_MMA(0, 0, At, B0); PG8_MMA(0, 1, At, B1); PG8_BAR; PG8_SCHED;
	s_waitcnt lgkmcnt(0)
	v_mfma_f32_16x16x32_bf16 v[62:65], v[142:145], v[198:201], v[62:65]
	v_mfma_f32_16x16x32_bf16 v[58:61], v[150:153], v[198:201], v[58:61]
	v_mfma_f32_16x16x32_bf16 v[54:57], v[142:145], v[206:209], v[54:57]
	v_mfma_f32_16x16x32_bf16 v[46:49], v[150:153], v[206:209], v[46:49]
	v_mfma_f32_16x16x32_bf16 v[38:41], v[142:145], v[214:217], v[38:41]
	v_mfma_f32_16x16x32_bf16 v[30:33], v[150:153], v[214:217], v[30:33]
	v_mfma_f32_16x16x32_bf16 v[22:25], v[142:145], v[222:225], v[22:25]
	v_mfma_f32_16x16x32_bf16 v[14:17], v[150:153], v[222:225], v[14:17]
	v_mfma_f32_16x16x32_bf16 v[62:65], v[146:149], v[202:205], v[62:65]
	v_mfma_f32_16x16x32_bf16 v[58:61], v[154:157], v[202:205], v[58:61]
	v_mfma_f32_16x16x32_bf16 v[54:57], v[146:149], v[210:213], v[54:57]
	v_mfma_f32_16x16x32_bf16 v[46:49], v[154:157], v[210:213], v[46:49]
	v_mfma_f32_16x16x32_bf16 v[38:41], v[146:149], v[218:221], v[38:41]
	v_mfma_f32_16x16x32_bf16 v[30:33], v[154:157], v[218:221], v[30:33]
	v_mfma_f32_16x16x32_bf16 v[22:25], v[146:149], v[226:229], v[22:25]
	v_mfma_f32_16x16x32_bf16 v[14:17], v[154:157], v[226:229], v[14:17]
	v_mfma_f32_16x16x32_bf16 v[50:53], v[182:185], v[198:201], v[50:53]
	v_mfma_f32_16x16x32_bf16 v[42:45], v[190:193], v[198:201], v[42:45]
	v_mfma_f32_16x16x32_bf16 v[34:37], v[182:185], v[206:209], v[34:37]
	v_mfma_f32_16x16x32_bf16 v[26:29], v[190:193], v[206:209], v[26:29]
	v_mfma_f32_16x16x32_bf16 v[18:21], v[182:185], v[214:217], v[18:21]
	v_mfma_f32_16x16x32_bf16 v[10:13], v[190:193], v[214:217], v[10:13]
	v_mfma_f32_16x16x32_bf16 v[6:9], v[182:185], v[222:225], v[6:9]
	v_mfma_f32_16x16x32_bf16 v[2:5], v[190:193], v[222:225], v[2:5]
	v_mfma_f32_16x16x32_bf16 v[50:53], v[186:189], v[202:205], v[50:53]
	v_mfma_f32_16x16x32_bf16 v[42:45], v[194:197], v[202:205], v[42:45]
	v_mfma_f32_16x16x32_bf16 v[34:37], v[186:189], v[210:213], v[34:37]
	v_mfma_f32_16x16x32_bf16 v[26:29], v[194:197], v[210:213], v[26:29]
	v_mfma_f32_16x16x32_bf16 v[18:21], v[186:189], v[218:221], v[18:21]
	v_mfma_f32_16x16x32_bf16 v[10:13], v[194:197], v[218:221], v[10:13]
	v_mfma_f32_16x16x32_bf16 v[6:9], v[186:189], v[226:229], v[6:9]
	v_mfma_f32_16x16x32_bf16 v[2:5], v[194:197], v[226:229], v[2:5]
	s_barrier
	s_add_i32 s37, 0, 0x18000
	s_add_i32 s71, 0, 0x1c000
	v_add_u32_e32 v154, s37, v160
	v_add_u32_e32 v194, s71, v160
	ds_read_b128 v[142:145], v154
	ds_read_b128 v[146:149], v154 offset:1024
	ds_read_b128 v[150:153], v154 offset:2048
	ds_read_b128 v[154:157], v154 offset:3072
	ds_read_b128 v[182:185], v194
	ds_read_b128 v[186:189], v194 offset:1024
	ds_read_b128 v[190:193], v194 offset:2048
	ds_read_b128 v[194:197], v194 offset:3072
	s_add_u32 s24, s24, 0x40000
	s_addc_u32 s25, s25, 0
	s_mov_b32 m0, s33
	v_lshl_add_u64 v[240:241], s[24:25], 0, v[136:137]
	ds_read_b128 v[198:201], v161 offset:32768
	ds_read_b128 v[202:205], v161 offset:33792
	ds_read_b128 v[206:209], v161 offset:34816
	ds_read_b128 v[210:213], v161 offset:35840
	ds_read_b128 v[214:217], v161 offset:36864
	ds_read_b128 v[218:221], v161 offset:37888
	ds_read_b128 v[222:225], v161 offset:38912
	ds_read_b128 v[226:229], v161 offset:39936
	global_load_lds_dwordx4 v[240:241], off
	v_lshl_add_u64 v[240:241], s[24:25], 0, v[134:135]
	s_mov_b32 m0, s36
	s_nop 0
	global_load_lds_dwordx4 v[240:241], off
	s_waitcnt vmcnt(8)
	s_waitcnt lgkmcnt(0)
	s_barrier
	s_waitcnt lgkmcnt(0)
	v_mfma_f32_16x16x32_bf16 v[126:129], v[142:145], v[198:201], v[126:129]
	v_mfma_f32_16x16x32_bf16 v[122:125], v[150:153], v[198:201], v[122:125]
	v_mfma_f32_16x16x32_bf16 v[118:121], v[142:145], v[206:209], v[118:121]
	v_mfma_f32_16x16x32_bf16 v[110:113], v[150:153], v[206:209], v[110:113]
	v_mfma_f32_16x16x32_bf16 v[102:105], v[142:145], v[214:217], v[102:105]
	v_mfma_f32_16x16x32_bf16 v[94:97], v[150:153], v[214:217], v[94:97]
	v_mfma_f32_16x16x32_bf16 v[86:89], v[142:145], v[222:225], v[86:89]
	v_mfma_f32_16x16x32_bf16 v[78:81], v[150:153], v[222:225], v[78:81]
	v_mfma_f32_16x16x32_bf16 v[126:129], v[146:149], v[202:205], v[126:129]
	v_mfma_f32_16x16x32_bf16 v[122:125], v[154:157], v[202:205], v[122:125]
	v_mfma_f32_16x16x32_bf16 v[118:121], v[146:149], v[210:213], v[118:121]
	v_mfma_f32_16x16x32_bf16 v[110:113], v[154:157], v[210:213], v[110:113]
	v_mfma_f32_16x16x32_bf16 v[102:105], v[146:149], v[218:221], v[102:105]
	v_mfma_f32_16x16x32_bf16 v[94:97], v[154:157], v[218:221], v[94:97]
	v_mfma_f32_16x16x32_bf16 v[86:89], v[146:149], v[226:229], v[86:89]
	v_mfma_f32_16x16x32_bf16 v[78:81], v[154:157], v[226:229], v[78:81]
	v_mfma_f32_16x16x32_bf16 v[114:117], v[182:185], v[198:201], v[114:117]
	v_mfma_f32_16x16x32_bf16 v[106:109], v[190:193], v[198:201], v[106:109]
	v_mfma_f32_16x16x32_bf16 v[98:101], v[182:185], v[206:209], v[98:101]
	v_mfma_f32_16x16x32_bf16 v[90:93], v[190:193], v[206:209], v[90:93]
	v_mfma_f32_16x16x32_bf16 v[82:85], v[182:185], v[214:217], v[82:85]
	v_mfma_f32_16x16x32_bf16 v[74:77], v[190:193], v[214:217], v[74:77]
	v_mfma_f32_16x16x32_bf16 v[70:73], v[182:185], v[222:225], v[70:73]
	v_mfma_f32_16x16x32_bf16 v[66:69], v[190:193], v[222:225], v[66:69]
	v_mfma_f32_16x16x32_bf16 v[114:117], v[186:189], v[202:205], v[114:117]
	v_mfma_f32_16x16x32_bf16 v[106:109], v[194:197], v[202:205], v[106:109]
	v_mfma_f32_16x16x32_bf16 v[98:101], v[186:189], v[210:213], v[98:101]
	v_mfma_f32_16x16x32_bf16 v[90:93], v[194:197], v[210:213], v[90:93]
	v_mfma_f32_16x16x32_bf16 v[82:85], v[186:189], v[218:221], v[82:85]
	v_mfma_f32_16x16x32_bf16 v[74:77], v[194:197], v[218:221], v[74:77]
	v_mfma_f32_16x16x32_bf16 v[70:73], v[186:189], v[226:229], v[70:73]
	v_mfma_f32_16x16x32_bf16 v[66:69], v[194:197], v[226:229], v[66:69]
	s_barrier
; #define PG8_STAGE(bufoff, gbase, voff) do { _Pragma("unroll") for (int _i = 0; _i < 2; ++_i) \
;         __builtin_amdgcn_global_load_lds((const unsigned*)((const char*)(gbase) + (voff)[_i]), (PG8_LAS unsigned*)(lds + (bufoff) + ldsw + _i * 8192), 16, 0, 0); } while (0)
; #define PG8_LDA(dst, b, h) do { _Pragma("unroll") for (int m = 0; m < 4; ++m) _Pragma("unroll") for (int k = 0; k < 2; ++k) dst[m][k] = *(const PG8_LAS bf16x8*)(lds + PG8_SA(b, h) + aoff + m * 2048 + k * 1024); } while (0)
; #define PG8_MMA(ai, bj, At, Bt) do { __builtin_amdgcn_s_setprio(1); _Pragma("unroll") for (int m = 0; m < 4; ++m) _Pragma("unroll") for (int n = 0; n < 2; ++n) _Pragma("unroll") for (int k = 0; k < 2; ++k) \
;         acc[ai][bj][m][n] = mma16<Epi::F16A>(Bt[n][k], At[m][k], acc[ai][bj][m][n]); __builtin_amdgcn_s_setprio(0); } while (0)
; #define PG8_WAIT_V(n) asm volatile("s_waitcnt vmcnt(" #n ")" ::: "memory")
; #define PG8_WAIT_L(n) asm volatile("s_waitcnt lgkmcnt(" #n ")" ::: "memory")
; #define PG8_BAR __builtin_amdgcn_s_barrier()
; #define PG8_SCHED __builtin_amdgcn_sched_barrier(0)
; template <class Epi, class Sched, bool ALIGN_EPI = false, bool SP2 = false>
; __device__ __forceinline__ void gemm_phase(PG8_LAS unsigned char* lds, const Gemm g, const Sched& S, const Epi& E) {
;     ...
;             PG8_WAIT_V(8); PG8_WAIT_L(0); PG8_BAR; PG8_MMA(0, 0, At, B0); PG8_MMA(0, 1, At, B1); PG8_BAR; PG8_SCHED;
;             PG8_LDA(At, 1, 1); PG8_STAGE(PG8_SB(1, 0), b3, voffB); PG8_STAGE(PG8_SB(1, 1), b3 + hstep, voffB); PG8_STAGE(PG8_SA(1, 0), a3, voffA);
;             PG8_WAIT_V(8); PG8_WAIT_L(0); PG8_BAR; PG8_MMA(1, 0, At, B0); PG8_MMA(1, 1, At, B1); PG8_BAR; PG8_SCHED;
;     ...
;         if constexpr (ALIGN_EPI) { if (wr == 0) PG8_BAR; }
	s_add_i32 s24, s37, s14
	v_lshl_add_u64 v[162:163], v[162:163], 0, s[92:93]
	s_mov_b32 m0, s24
	ds_read_b128 v[198:201], v161 offset:49152
	ds_read_b128 v[202:205], v161 offset:50176
	ds_read_b128 v[206:209], v161 offset:51200
	ds_read_b128 v[210:213], v161 offset:52224
	ds_read_b128 v[214:217], v161 offset:53248
	ds_read_b128 v[218:221], v161 offset:54272
	ds_read_b128 v[222:225], v161 offset:55296
	ds_read_b128 v[226:229], v161 offset:56320
	global_load_lds_dwordx4 v[162:163], off
	s_add_i32 m0, s24, 0x2000
	s_add_u32 s22, s22, 0x40080
	v_lshl_add_u64 v[162:163], v[230:231], 0, s[92:93]
	s_addc_u32 s23, s23, 0
	s_add_i32 s24, s71, s14
	global_load_lds_dwordx4 v[162:163], off
	v_lshl_add_u64 v[162:163], s[22:23], 0, v[0:1]
	s_mov_b32 m0, s24
	s_nop 0
	global_load_lds_dwordx4 v[162:163], off
	v_lshl_add_u64 v[162:163], s[22:23], 0, v[132:133]
	s_add_i32 m0, s24, 0x2000
	s_nop 0
	global_load_lds_dwordx4 v[162:163], off
	v_lshl_add_u64 v[162:163], v[234:235], 0, s[92:93]
	s_mov_b32 m0, s53
	s_nop 0
	global_load_lds_dwordx4 v[162:163], off
	v_lshl_add_u64 v[162:163], v[236:237], 0, s[92:93]
	s_mov_b32 m0, s54
	s_nop 0
	global_load_lds_dwordx4 v[162:163], off
	s_waitcnt vmcnt(8)
	s_waitcnt lgkmcnt(0)
	s_barrier
	s_waitcnt lgkmcnt(0)
	v_mfma_f32_16x16x32_bf16 v[62:65], v[142:145], v[198:201], v[62:65]
	v_mfma_f32_16x16x32_bf16 v[58:61], v[150:153], v[198:201], v[58:61]
	v_mfma_f32_16x16x32_bf16 v[54:57], v[142:145], v[206:209], v[54:57]
	v_mfma_f32_16x16x32_bf16 v[46:49], v[150:153], v[206:209], v[46:49]
	v_mfma_f32_16x16x32_bf16 v[38:41], v[142:145], v[214:217], v[38:41]
	v_mfma_f32_16x16x32_bf16 v[30:33], v[150:153], v[214:217], v[30:33]
	v_mfma_f32_16x16x32_bf16 v[22:25], v[142:145], v[222:225], v[22:25]
	v_mfma_f32_16x16x32_bf16 v[14:17], v[150:153], v[222:225], v[14:17]
	v_mfma_f32_16x16x32_bf16 v[62:65], v[146:149], v[202:205], v[62:65]
	v_mfma_f32_16x16x32_bf16 v[58:61], v[154:157], v[202:205], v[58:61]
	v_mfma_f32_16x16x32_bf16 v[54:57], v[146:149], v[210:213], v[54:57]
	v_mfma_f32_16x16x32_bf16 v[46:49], v[154:157], v[210:213], v[46:49]
	v_mfma_f32_16x16x32_bf16 v[38:41], v[146:149], v[218:221], v[38:41]
	v_mfma_f32_16x16x32_bf16 v[30:33], v[154:157], v[218:221], v[30:33]
	v_mfma_f32_16x16x32_bf16 v[22:25], v[146:149], v[226:229], v[22:25]
	v_mfma_f32_16x16x32_bf16 v[14:17], v[154:157], v[226:229], v[14:17]
	v_mfma_f32_16x16x32_bf16 v[50:53], v[182:185], v[198:201], v[50:53]
	v_mfma_f32_16x16x32_bf16 v[42:45], v[190:193], v[198:201], v[42:45]
	v_mfma_f32_16x16x32_bf16 v[34:37], v[182:185], v[206:209], v[34:37]
	v_mfma_f32_16x16x32_bf16 v[26:29], v[190:193], v[206:209], v[26:29]
	v_mfma_f32_16x16x32_bf16 v[18:21], v[182:185], v[214:217], v[18:21]
	v_mfma_f32_16x16x32_bf16 v[10:13], v[190:193], v[214:217], v[10:13]
	v_mfma_f32_16x16x32_bf16 v[6:9], v[182:185], v[222:225], v[6:9]
	v_mfma_f32_16x16x32_bf16 v[2:5], v[190:193], v[222:225], v[2:5]
	v_mfma_f32_16x16x32_bf16 v[50:53], v[186:189], v[202:205], v[50:53]
	v_mfma_f32_16x16x32_bf16 v[42:45], v[194:197], v[202:205], v[42:45]
	v_mfma_f32_16x16x32_bf16 v[34:37], v[186:189], v[210:213], v[34:37]
	v_mfma_f32_16x16x32_bf16 v[26:29], v[194:197], v[210:213], v[26:29]
	v_mfma_f32_16x16x32_bf16 v[18:21], v[186:189], v[218:221], v[18:21]
	v_mfma_f32_16x16x32_bf16 v[10:13], v[194:197], v[218:221], v[10:13]
	v_mfma_f32_16x16x32_bf16 v[6:9], v[186:189], v[226:229], v[6:9]
	v_mfma_f32_16x16x32_bf16 v[2:5], v[194:197], v[226:229], v[2:5]
	s_barrier
	s_add_i32 s70, s70, 2
	s_add_u32 s20, s20, 0x100
	s_addc_u32 s21, s21, 0
	s_add_u32 s62, s62, 0x100
	s_addc_u32 s69, s69, 0
	s_cmp_gt_u32 s70, 13
	s_cbranch_scc0 .LBB0_326
	s_and_b64 vcc, exec, s[12:13]
	s_cbranch_vccz .LBB0_329
	s_barrier

; #define PG8_STAGE(bufoff, gbase, voff) do { _Pragma("unroll") for (int _i = 0; _i < 2; ++_i) \
;         __builtin_amdgcn_global_load_lds((const unsigned*)((const char*)(gbase) + (voff)[_i]), (PG8_LAS unsigned*)(lds + (bufoff) + ldsw + _i * 8192), 16, 0, 0); } while (0)
; #define PG8_LDA(dst, b, h) do { _Pragma("unroll") for (int m = 0; m < 4; ++m) _Pragma("unroll") for (int k = 0; k < 2; ++k) dst[m][k] = *(const PG8_LAS bf16x8*)(lds + PG8_SA(b, h) + aoff + m * 2048 + k * 1024); } while (0)
; #define PG8_LDB(dst, b, h) do { _Pragma("unroll") for (int n = 0; n < 2; ++n) _Pragma("unroll") for (int k = 0; k < 2; ++k) dst[n][k] = *(const PG8_LAS bf16x8*)(lds + PG8_SB(b, h) + boff + n * 2048 + k * 1024); } while (0)
; #define PG8_MMA(ai, bj, At, Bt) do { __builtin_amdgcn_s_setprio(1); _Pragma("unroll") for (int m = 0; m < 4; ++m) _Pragma("unroll") for (int n = 0; n < 2; ++n) _Pragma("unroll") for (int k = 0; k < 2; ++k) \
;         acc[ai][bj][m][n] = mma16<Epi::F16A>(Bt[n][k], At[m][k], acc[ai][bj][m][n]); __builtin_amdgcn_s_setprio(0); } while (0)
; #define PG8_WAIT_V(n) asm volatile("s_waitcnt vmcnt(" #n ")" ::: "memory")
; #define PG8_WAIT_L(n) asm volatile("s_waitcnt lgkmcnt(" #n ")" ::: "memory")
; #define PG8_BAR __builtin_amdgcn_s_barrier()
; #define PG8_SCHED __builtin_amdgcn_sched_barrier(0)
; template <class Epi, class Sched, bool ALIGN_EPI = false, bool SP2 = false>
; __device__ __forceinline__ void gemm_phase(PG8_LAS unsigned char* lds, const Gemm g, const Sched& S, const Epi& E) {
;     ...
;             PG8_LDB(B0, 0, 0); PG8_LDB(B1, 0, 1); PG8_SCHED; PG8_LDA(At, 0, 0); PG8_STAGE(PG8_SA(1, 1), a1 + hstep, voffA);
;             PG8_WAIT_V(8); PG8_WAIT_L(0); PG8_BAR; PG8_MMA(0, 0, At, B0); PG8_MMA(0, 1, At, B1); PG8_BAR; PG8_SCHED;
;             PG8_LDA(At, 0, 1); PG8_STAGE(PG8_SB(0, 0), b2, voffB); PG8_STAGE(PG8_SB(0, 1), b2 + hstep, voffB); PG8_STAGE(PG8_SA(0, 0), a2, voffA);
;             PG8_WAIT_V(8); PG8_WAIT_L(0); PG8_BAR; PG8_MMA(1, 0, At, B0); PG8_MMA(1, 1, At, B1); PG8_BAR; PG8_SCHED;
.LBB0_407:
	s_add_u32 s20, s6, 0xfffc0080
	s_addc_u32 s21, s7, -1
	s_add_i32 s37, 0, 0x10000
	s_cmp_eq_u32 s62, 12
	s_cselect_b32 s23, s25, s21
	s_cselect_b32 s22, s30, s20
	v_add_u32_e32 v0, s37, v161
	s_cselect_b32 s21, s31, s49
	s_cselect_b32 s20, s43, s47
	s_add_i32 s76, 0, 0x14000
	ds_read_b128 v[142:145], v0
	ds_read_b128 v[146:149], v0 offset:1024
	ds_read_b128 v[186:189], v0 offset:2048
	ds_read_b128 v[190:193], v0 offset:3072
	v_add_u32_e32 v0, s76, v161
	ds_read_b128 v[194:197], v0
	ds_read_b128 v[198:201], v0 offset:1024
	ds_read_b128 v[202:205], v0 offset:2048
	ds_read_b128 v[206:209], v0 offset:3072
	v_lshl_add_u64 v[150:151], s[6:7], 0, v[138:139]
	s_add_i32 m0, s65, 0xc000
	ds_read_b128 v[210:213], v184
	ds_read_b128 v[214:217], v184 offset:1024
	ds_read_b128 v[218:221], v184 offset:2048
	ds_read_b128 v[222:225], v184 offset:3072
	ds_read_b128 v[226:229], v184 offset:4096
	ds_read_b128 v[234:237], v184 offset:5120
	ds_read_b128 v[240:243], v184 offset:6144
	ds_read_b128 v[244:247], v184 offset:7168
	global_load_lds_dwordx4 v[150:151], off
	v_lshl_add_u64 v[150:151], s[6:7], 0, v[140:141]
	s_add_i32 m0, s65, 0xe000
	s_nop 0
	global_load_lds_dwordx4 v[150:151], off
	s_waitcnt vmcnt(8)
	s_waitcnt lgkmcnt(0)
	s_barrier
	s_waitcnt lgkmcnt(0)
	v_mfma_f32_16x16x32_bf16 v[126:129], v[142:145], v[210:213], v[126:129]
	v_mfma_f32_16x16x32_bf16 v[122:125], v[186:189], v[210:213], v[122:125]
	v_mfma_f32_16x16x32_bf16 v[118:121], v[142:145], v[218:221], v[118:121]
	v_mfma_f32_16x16x32_bf16 v[110:113], v[186:189], v[218:221], v[110:113]
	v_mfma_f32_16x16x32_bf16 v[102:105], v[142:145], v[226:229], v[102:105]
	v_mfma_f32_16x16x32_bf16 v[94:97], v[186:189], v[226:229], v[94:97]
	v_mfma_f32_16x16x32_bf16 v[86:89], v[142:145], v[240:243], v[86:89]
	v_mfma_f32_16x16x32_bf16 v[78:81], v[186:189], v[240:243], v[78:81]
	v_mfma_f32_16x16x32_bf16 v[126:129], v[146:149], v[214:217], v[126:129]
	v_mfma_f32_16x16x32_bf16 v[122:125], v[190:193], v[214:217], v[122:125]
	v_mfma_f32_16x16x32_bf16 v[118:121], v[146:149], v[222:225], v[118:121]
	v_mfma_f32_16x16x32_bf16 v[110:113], v[190:193], v[222:225], v[110:113]
	v_mfma_f32_16x16x32_bf16 v[102:105], v[146:149], v[234:237], v[102:105]
	v_mfma_f32_16x16x32_bf16 v[94:97], v[190:193], v[234:237], v[94:97]
	v_mfma_f32_16x16x32_bf16 v[86:89], v[146:149], v[244:247], v[86:89]
	v_mfma_f32_16x16x32_bf16 v[78:81], v[190:193], v[244:247], v[78:81]
	v_mfma_f32_16x16x32_bf16 v[114:117], v[194:197], v[210:213], v[114:117]
	v_mfma_f32_16x16x32_bf16 v[106:109], v[202:205], v[210:213], v[106:109]
	v_mfma_f32_16x16x32_bf16 v[98:101], v[194:197], v[218:221], v[98:101]
	v_mfma_f32_16x16x32_bf16 v[90:93], v[202:205], v[218:221], v[90:93]
	v_mfma_f32_16x16x32_bf16 v[82:85], v[194:197], v[226:229], v[82:85]
	v_mfma_f32_16x16x32_bf16 v[74:77], v[202:205], v[226:229], v[74:77]
	v_mfma_f32_16x16x32_bf16 v[70:73], v[194:197], v[240:243], v[70:73]
	v_mfma_f32_16x16x32_bf16 v[66:69], v[202:205], v[240:243], v[66:69]
	v_mfma_f32_16x16x32_bf16 v[114:117], v[198:201], v[214:217], v[114:117]
	v_mfma_f32_16x16x32_bf16 v[106:109], v[206:209], v[214:217], v[106:109]
	v_mfma_f32_16x16x32_bf16 v[98:101], v[198:201], v[222:225], v[98:101]
	v_mfma_f32_16x16x32_bf16 v[90:93], v[206:209], v[222:225], v[90:93]
	v_mfma_f32_16x16x32_bf16 v[82:85], v[198:201], v[234:237], v[82:85]
	v_mfma_f32_16x16x32_bf16 v[74:77], v[206:209], v[234:237], v[74:77]
	v_mfma_f32_16x16x32_bf16 v[70:73], v[198:201], v[244:247], v[70:73]
	v_mfma_f32_16x16x32_bf16 v[66:69], v[206:209], v[244:247], v[66:69]
	s_barrier
	s_add_i32 s37, s37, s41
	v_lshl_add_u64 v[150:151], s[20:21], 0, v[134:135]
	s_mov_b32 m0, s37
	ds_read_b128 v[210:213], v184 offset:16384
	ds_read_b128 v[214:217], v184 offset:17408
	ds_read_b128 v[218:221], v184 offset:18432
	ds_read_b128 v[222:225], v184 offset:19456
	ds_read_b128 v[226:229], v184 offset:20480
	ds_read_b128 v[234:237], v184 offset:21504
	ds_read_b128 v[240:243], v184 offset:22528
	ds_read_b128 v[244:247], v184 offset:23552
	global_load_lds_dwordx4 v[150:151], off
	s_add_i32 m0, s37, 0x2000
	s_add_u32 s94, s20, 0x40000
	v_lshl_add_u64 v[154:155], s[20:21], 0, v[130:131]
	s_addc_u32 s95, s21, 0
	s_add_i32 s37, s76, s41
	global_load_lds_dwordx4 v[154:155], off
	v_lshl_add_u64 v[158:159], s[94:95], 0, v[134:135]
	s_mov_b32 m0, s37
	v_lshl_add_u64 v[162:163], s[22:23], 0, v[132:133]
	global_load_lds_dwordx4 v[158:159], off
	v_lshl_add_u64 v[158:159], s[94:95], 0, v[130:131]
	s_add_i32 m0, s37, 0x2000
	s_nop 0
	global_load_lds_dwordx4 v[158:159], off
	v_lshl_add_u64 v[158:159], s[22:23], 0, v[136:137]
	s_mov_b32 m0, s65
	s_nop 0
	global_load_lds_dwordx4 v[158:159], off
	s_mov_b32 m0, s66
	s_nop 0
	global_load_lds_dwordx4 v[162:163], off
	s_waitcnt vmcnt(8)
	s_waitcnt lgkmcnt(0)
	s_barrier
; #define PG8_STAGE(bufoff, gbase, voff) do { _Pragma("unroll") for (int _i = 0; _i < 2; ++_i) \
;         __builtin_amdgcn_global_load_lds((const unsigned*)((const char*)(gbase) + (voff)[_i]), (PG8_LAS unsigned*)(lds + (bufoff) + ldsw + _i * 8192), 16, 0, 0); } while (0)
; #define PG8_LDA(dst, b, h) do { _Pragma("unroll") for (int m = 0; m < 4; ++m) _Pragma("unroll") for (int k = 0; k < 2; ++k) dst[m][k] = *(const PG8_LAS bf16x8*)(lds + PG8_SA(b, h) + aoff + m * 2048 + k * 1024); } while (0)
; #define PG8_LDB(dst, b, h) do { _Pragma("unroll") for (int n = 0; n < 2; ++n) _Pragma("unroll") for (int k = 0; k < 2; ++k) dst[n][k] = *(const PG8_LAS bf16x8*)(lds + PG8_SB(b, h) + boff + n * 2048 + k * 1024); } while (0)
; #define PG8_MMA(ai, bj, At, Bt) do { __builtin_amdgcn_s_setprio(1); _Pragma("unroll") for (int m = 0; m < 4; ++m) _Pragma("unroll") for (int n = 0; n < 2; ++n) _Pragma("unroll") for (int k = 0; k < 2; ++k) \
;         acc[ai][bj][m][n] = mma16<Epi::F16A>(Bt[n][k], At[m][k], acc[ai][bj][m][n]); __builtin_amdgcn_s_setprio(0); } while (0)
; #define PG8_WAIT_V(n) asm volatile("s_waitcnt vmcnt(" #n ")" ::: "memory")
; #define PG8_WAIT_L(n) asm volatile("s_waitcnt lgkmcnt(" #n ")" ::: "memory")
; #define PG8_BAR __builtin_amdgcn_s_barrier()
; #define PG8_SCHED __builtin_amdgcn_sched_barrier(0)
; template <class Epi, class Sched, bool ALIGN_EPI = false, bool SP2 = false>
; __device__ __forceinline__ void gemm_phase(PG8_LAS unsigned char* lds, const Gemm g, const Sched& S, const Epi& E) {
;     ...
;             PG8_WAIT_V(8); PG8_WAIT_L(0); PG8_BAR; PG8_MMA(1, 0, At, B0); PG8_MMA(1, 1, At, B1); PG8_BAR; PG8_SCHED;
;             PG8_LDB(B0, 1, 0); PG8_LDB(B1, 1, 1); PG8_SCHED; PG8_LDA(At, 1, 0); PG8_STAGE(PG8_SA(0, 1), a2 + hstep, voffA);
;             PG8_WAIT_V(8); PG8_WAIT_L(0); PG8_BAR; PG8_MMA(0, 0, At, B0); PG8_MMA(0, 1, At, B1); PG8_BAR; PG8_SCHED;
	s_waitcnt lgkmcnt(0)
	v_mfma_f32_16x16x32_bf16 v[62:65], v[142:145], v[210:213], v[62:65]
	v_mfma_f32_16x16x32_bf16 v[58:61], v[186:189], v[210:213], v[58:61]
	v_mfma_f32_16x16x32_bf16 v[54:57], v[142:145], v[218:221], v[54:57]
	v_mfma_f32_16x16x32_bf16 v[46:49], v[186:189], v[218:221], v[46:49]
	v_mfma_f32_16x16x32_bf16 v[38:41], v[142:145], v[226:229], v[38:41]
	v_mfma_f32_16x16x32_bf16 v[30:33], v[186:189], v[226:229], v[30:33]
	v_mfma_f32_16x16x32_bf16 v[22:25], v[142:145], v[240:243], v[22:25]
	v_mfma_f32_16x16x32_bf16 v[14:17], v[186:189], v[240:243], v[14:17]
	v_mfma_f32_16x16x32_bf16 v[62:65], v[146:149], v[214:217], v[62:65]
	v_mfma_f32_16x16x32_bf16 v[58:61], v[190:193], v[214:217], v[58:61]
	v_mfma_f32_16x16x32_bf16 v[54:57], v[146:149], v[222:225], v[54:57]
	v_mfma_f32_16x16x32_bf16 v[46:49], v[190:193], v[222:225], v[46:49]
	v_mfma_f32_16x16x32_bf16 v[38:41], v[146:149], v[234:237], v[38:41]
	v_mfma_f32_16x16x32_bf16 v[30:33], v[190:193], v[234:237], v[30:33]
	v_mfma_f32_16x16x32_bf16 v[22:25], v[146:149], v[244:247], v[22:25]
	v_mfma_f32_16x16x32_bf16 v[14:17], v[190:193], v[244:247], v[14:17]
	v_mfma_f32_16x16x32_bf16 v[50:53], v[194:197], v[210:213], v[50:53]
	v_mfma_f32_16x16x32_bf16 v[42:45], v[202:205], v[210:213], v[42:45]
	v_mfma_f32_16x16x32_bf16 v[34:37], v[194:197], v[218:221], v[34:37]
	v_mfma_f32_16x16x32_bf16 v[26:29], v[202:205], v[218:221], v[26:29]
	v_mfma_f32_16x16x32_bf16 v[18:21], v[194:197], v[226:229], v[18:21]
	v_mfma_f32_16x16x32_bf16 v[10:13], v[202:205], v[226:229], v[10:13]
	v_mfma_f32_16x16x32_bf16 v[6:9], v[194:197], v[240:243], v[6:9]
	v_mfma_f32_16x16x32_bf16 v[2:5], v[202:205], v[240:243], v[2:5]
	v_mfma_f32_16x16x32_bf16 v[50:53], v[198:201], v[214:217], v[50:53]
	v_mfma_f32_16x16x32_bf16 v[42:45], v[206:209], v[214:217], v[42:45]
	v_mfma_f32_16x16x32_bf16 v[34:37], v[198:201], v[222:225], v[34:37]
	v_mfma_f32_16x16x32_bf16 v[26:29], v[206:209], v[222:225], v[26:29]
	v_mfma_f32_16x16x32_bf16 v[18:21], v[198:201], v[234:237], v[18:21]
	v_mfma_f32_16x16x32_bf16 v[10:13], v[206:209], v[234:237], v[10:13]
	v_mfma_f32_16x16x32_bf16 v[6:9], v[198:201], v[244:247], v[6:9]
	v_mfma_f32_16x16x32_bf16 v[2:5], v[206:209], v[244:247], v[2:5]
	s_barrier
	s_add_i32 s37, 0, 0x18000
	v_add_u32_e32 v0, s37, v161
	s_add_i32 s76, 0, 0x1c000
	ds_read_b128 v[142:145], v0
	ds_read_b128 v[146:149], v0 offset:1024
	ds_read_b128 v[186:189], v0 offset:2048
	ds_read_b128 v[190:193], v0 offset:3072
	v_add_u32_e32 v0, s76, v161
	ds_read_b128 v[194:197], v0
	ds_read_b128 v[198:201], v0 offset:1024
	ds_read_b128 v[202:205], v0 offset:2048
	ds_read_b128 v[206:209], v0 offset:3072
	s_add_u32 s22, s22, 0x40000
	s_addc_u32 s23, s23, 0
	s_mov_b32 m0, s67
	v_lshl_add_u64 v[182:183], s[22:23], 0, v[136:137]
	ds_read_b128 v[210:213], v184 offset:32768
	ds_read_b128 v[214:217], v184 offset:33792
	ds_read_b128 v[218:221], v184 offset:34816
	ds_read_b128 v[222:225], v184 offset:35840
	ds_read_b128 v[226:229], v184 offset:36864
	ds_read_b128 v[234:237], v184 offset:37888
	ds_read_b128 v[240:243], v184 offset:38912
	ds_read_b128 v[244:247], v184 offset:39936
	global_load_lds_dwordx4 v[182:183], off
	v_lshl_add_u64 v[182:183], s[22:23], 0, v[132:133]
	s_mov_b32 m0, s33
	s_nop 0
	global_load_lds_dwordx4 v[182:183], off
	s_waitcnt vmcnt(8)
	s_waitcnt lgkmcnt(0)
	s_barrier
	s_waitcnt lgkmcnt(0)
	v_mfma_f32_16x16x32_bf16 v[126:129], v[142:145], v[210:213], v[126:129]
	v_mfma_f32_16x16x32_bf16 v[122:125], v[186:189], v[210:213], v[122:125]
	v_mfma_f32_16x16x32_bf16 v[118:121], v[142:145], v[218:221], v[118:121]
	v_mfma_f32_16x16x32_bf16 v[110:113], v[186:189], v[218:221], v[110:113]
	v_mfma_f32_16x16x32_bf16 v[102:105], v[142:145], v[226:229], v[102:105]
	v_mfma_f32_16x16x32_bf16 v[94:97], v[186:189], v[226:229], v[94:97]
	v_mfma_f32_16x16x32_bf16 v[86:89], v[142:145], v[240:243], v[86:89]
	v_mfma_f32_16x16x32_bf16 v[78:81], v[186:189], v[240:243], v[78:81]
	v_mfma_f32_16x16x32_bf16 v[126:129], v[146:149], v[214:217], v[126:129]
	v_mfma_f32_16x16x32_bf16 v[122:125], v[190:193], v[214:217], v[122:125]
	v_mfma_f32_16x16x32_bf16 v[118:121], v[146:149], v[222:225], v[118:121]
	v_mfma_f32_16x16x32_bf16 v[110:113], v[190:193], v[222:225], v[110:113]
	v_mfma_f32_16x16x32_bf16 v[102:105], v[146:149], v[234:237], v[102:105]
	v_mfma_f32_16x16x32_bf16 v[94:97], v[190:193], v[234:237], v[94:97]
	v_mfma_f32_16x16x32_bf16 v[86:89], v[146:149], v[244:247], v[86:89]
	v_mfma_f32_16x16x32_bf16 v[78:81], v[190:193], v[244:247], v[78:81]
	v_mfma_f32_16x16x32_bf16 v[114:117], v[194:197], v[210:213], v[114:117]
	v_mfma_f32_16x16x32_bf16 v[106:109], v[202:205], v[210:213], v[106:109]
	v_mfma_f32_16x16x32_bf16 v[98:101], v[194:197], v[218:221], v[98:101]
	v_mfma_f32_16x16x32_bf16 v[90:93], v[202:205], v[218:221], v[90:93]
	v_mfma_f32_16x16x32_bf16 v[82:85], v[194:197], v[226:229], v[82:85]
	v_mfma_f32_16x16x32_bf16 v[74:77], v[202:205], v[226:229], v[74:77]
	v_mfma_f32_16x16x32_bf16 v[70:73], v[194:197], v[240:243], v[70:73]
	v_mfma_f32_16x16x32_bf16 v[66:69], v[202:205], v[240:243], v[66:69]
	v_mfma_f32_16x16x32_bf16 v[114:117], v[198:201], v[214:217], v[114:117]
	v_mfma_f32_16x16x32_bf16 v[106:109], v[206:209], v[214:217], v[106:109]
	v_mfma_f32_16x16x32_bf16 v[98:101], v[198:201], v[222:225], v[98:101]
	v_mfma_f32_16x16x32_bf16 v[90:93], v[206:209], v[222:225], v[90:93]
	v_mfma_f32_16x16x32_bf16 v[82:85], v[198:201], v[234:237], v[82:85]
	v_mfma_f32_16x16x32_bf16 v[74:77], v[206:209], v[234:237], v[74:77]
	v_mfma_f32_16x16x32_bf16 v[70:73], v[198:201], v[244:247], v[70:73]
	v_mfma_f32_16x16x32_bf16 v[66:69], v[206:209], v[244:247], v[66:69]
	s_barrier
; #define PG8_STAGE(bufoff, gbase, voff) do { _Pragma("unroll") for (int _i = 0; _i < 2; ++_i) \
;         __builtin_amdgcn_global_load_lds((const unsigned*)((const char*)(gbase) + (voff)[_i]), (PG8_LAS unsigned*)(lds + (bufoff) + ldsw + _i * 8192), 16, 0, 0); } while (0)
; #define PG8_LDA(dst, b, h) do { _Pragma("unroll") for (int m = 0; m < 4; ++m) _Pragma("unroll") for (int k = 0; k < 2; ++k) dst[m][k] = *(const PG8_LAS bf16x8*)(lds + PG8_SA(b, h) + aoff + m * 2048 + k * 1024); } while (0)
; #define PG8_MMA(ai, bj, At, Bt) do { __builtin_amdgcn_s_setprio(1); _Pragma("unroll") for (int m = 0; m < 4; ++m) _Pragma("unroll") for (int n = 0; n < 2; ++n) _Pragma("unroll") for (int k = 0; k < 2; ++k) \
;         acc[ai][bj][m][n] = mma16<Epi::F16A>(Bt[n][k], At[m][k], acc[ai][bj][m][n]); __builtin_amdgcn_s_setprio(0); } while (0)
; #define PG8_WAIT_V(n) asm volatile("s_waitcnt vmcnt(" #n ")" ::: "memory")
; #define PG8_WAIT_L(n) asm volatile("s_waitcnt lgkmcnt(" #n ")" ::: "memory")
; #define PG8_BAR __builtin_amdgcn_s_barrier()
; #define PG8_SCHED __builtin_amdgcn_sched_barrier(0)
; template <class Epi, class Sched, bool ALIGN_EPI = false, bool SP2 = false>
; __device__ __forceinline__ void gemm_phase(PG8_LAS unsigned char* lds, const Gemm g, const Sched& S, const Epi& E) {
;     ...
;         for (int t = 0; t < nt; t += 2) {
;             const bool last = (t == nt - 2);
;     ...
;             PG8_LDA(At, 1, 1); PG8_STAGE(PG8_SB(1, 0), b3, voffB); PG8_STAGE(PG8_SB(1, 1), b3 + hstep, voffB); PG8_STAGE(PG8_SA(1, 0), a3, voffA);
;             PG8_WAIT_V(8); PG8_WAIT_L(0); PG8_BAR; PG8_MMA(1, 0, At, B0); PG8_MMA(1, 1, At, B1); PG8_BAR; PG8_SCHED;
	s_add_i32 s22, s37, s41
	v_lshl_add_u64 v[150:151], v[150:151], 0, s[92:93]
	s_mov_b32 m0, s22
	ds_read_b128 v[210:213], v184 offset:49152
	ds_read_b128 v[214:217], v184 offset:50176
	ds_read_b128 v[218:221], v184 offset:51200
	ds_read_b128 v[222:225], v184 offset:52224
	ds_read_b128 v[226:229], v184 offset:53248
	ds_read_b128 v[234:237], v184 offset:54272
	ds_read_b128 v[240:243], v184 offset:55296
	ds_read_b128 v[244:247], v184 offset:56320
	global_load_lds_dwordx4 v[150:151], off
	s_add_i32 m0, s22, 0x2000
	s_add_u32 s20, s20, 0x40080
	v_lshl_add_u64 v[150:151], v[154:155], 0, s[92:93]
	s_addc_u32 s21, s21, 0
	s_add_i32 s22, s76, s41
	global_load_lds_dwordx4 v[150:151], off
	v_lshl_add_u64 v[150:151], s[20:21], 0, v[134:135]
	s_mov_b32 m0, s22
	s_nop 0
	global_load_lds_dwordx4 v[150:151], off
	v_lshl_add_u64 v[150:151], s[20:21], 0, v[130:131]
	s_add_i32 m0, s22, 0x2000
	s_nop 0
	global_load_lds_dwordx4 v[150:151], off
	v_lshl_add_u64 v[150:151], v[158:159], 0, s[92:93]
	s_mov_b32 m0, s69
	s_nop 0
	global_load_lds_dwordx4 v[150:151], off
	v_lshl_add_u64 v[150:151], v[162:163], 0, s[92:93]
	s_mov_b32 m0, s54
	s_nop 0
	global_load_lds_dwordx4 v[150:151], off
	s_waitcnt vmcnt(8)
	s_waitcnt lgkmcnt(0)
	s_barrier
	s_waitcnt lgkmcnt(0)
	v_mfma_f32_16x16x32_bf16 v[62:65], v[142:145], v[210:213], v[62:65]
	v_mfma_f32_16x16x32_bf16 v[58:61], v[186:189], v[210:213], v[58:61]
	v_mfma_f32_16x16x32_bf16 v[54:57], v[142:145], v[218:221], v[54:57]
	v_mfma_f32_16x16x32_bf16 v[46:49], v[186:189], v[218:221], v[46:49]
	v_mfma_f32_16x16x32_bf16 v[38:41], v[142:145], v[226:229], v[38:41]
	v_mfma_f32_16x16x32_bf16 v[30:33], v[186:189], v[226:229], v[30:33]
	v_mfma_f32_16x16x32_bf16 v[22:25], v[142:145], v[240:243], v[22:25]
	v_mfma_f32_16x16x32_bf16 v[14:17], v[186:189], v[240:243], v[14:17]
	v_mfma_f32_16x16x32_bf16 v[62:65], v[146:149], v[214:217], v[62:65]
	v_mfma_f32_16x16x32_bf16 v[58:61], v[190:193], v[214:217], v[58:61]
	v_mfma_f32_16x16x32_bf16 v[54:57], v[146:149], v[222:225], v[54:57]
	v_mfma_f32_16x16x32_bf16 v[46:49], v[190:193], v[222:225], v[46:49]
	v_mfma_f32_16x16x32_bf16 v[38:41], v[146:149], v[234:237], v[38:41]
	v_mfma_f32_16x16x32_bf16 v[30:33], v[190:193], v[234:237], v[30:33]
	v_mfma_f32_16x16x32_bf16 v[22:25], v[146:149], v[244:247], v[22:25]
	v_mfma_f32_16x16x32_bf16 v[14:17], v[190:193], v[244:247], v[14:17]
	v_mfma_f32_16x16x32_bf16 v[50:53], v[194:197], v[210:213], v[50:53]
	v_mfma_f32_16x16x32_bf16 v[42:45], v[202:205], v[210:213], v[42:45]
	v_mfma_f32_16x16x32_bf16 v[34:37], v[194:197], v[218:221], v[34:37]
	v_mfma_f32_16x16x32_bf16 v[26:29], v[202:205], v[218:221], v[26:29]
	v_mfma_f32_16x16x32_bf16 v[18:21], v[194:197], v[226:229], v[18:21]
	v_mfma_f32_16x16x32_bf16 v[10:13], v[202:205], v[226:229], v[10:13]
	v_mfma_f32_16x16x32_bf16 v[6:9], v[194:197], v[240:243], v[6:9]
	v_mfma_f32_16x16x32_bf16 v[2:5], v[202:205], v[240:243], v[2:5]
	v_mfma_f32_16x16x32_bf16 v[50:53], v[198:201], v[214:217], v[50:53]
	v_mfma_f32_16x16x32_bf16 v[42:45], v[206:209], v[214:217], v[42:45]
	v_mfma_f32_16x16x32_bf16 v[34:37], v[198:201], v[222:225], v[34:37]
	v_mfma_f32_16x16x32_bf16 v[26:29], v[206:209], v[222:225], v[26:29]
	v_mfma_f32_16x16x32_bf16 v[18:21], v[198:201], v[234:237], v[18:21]
	v_mfma_f32_16x16x32_bf16 v[10:13], v[206:209], v[234:237], v[10:13]
	v_mfma_f32_16x16x32_bf16 v[6:9], v[198:201], v[244:247], v[6:9]
	v_mfma_f32_16x16x32_bf16 v[2:5], v[206:209], v[244:247], v[2:5]
	s_barrier
	s_add_i32 s62, s62, 2
	s_add_u32 s6, s6, 0x100
	s_addc_u32 s7, s7, 0
	s_add_u32 s47, s47, 0x100
	s_addc_u32 s49, s49, 0
	s_cmp_gt_u32 s62, 13
	s_cbranch_scc0 .LBB0_407
	s_and_b64 vcc, exec, s[44:45]
	s_cbranch_vccz .LBB0_410
	s_barrier

; #define PG8_STAGE(bufoff, gbase, voff) do { _Pragma("unroll") for (int _i = 0; _i < 2; ++_i) \
;         __builtin_amdgcn_global_load_lds((const unsigned*)((const char*)(gbase) + (voff)[_i]), (PG8_LAS unsigned*)(lds + (bufoff) + ldsw + _i * 8192), 16, 0, 0); } while (0)
; #define PG8_LDA(dst, b, h) do { _Pragma("unroll") for (int m = 0; m < 4; ++m) _Pragma("unroll") for (int k = 0; k < 2; ++k) dst[m][k] = *(const PG8_LAS bf16x8*)(lds + PG8_SA(b, h) + aoff + m * 2048 + k * 1024); } while (0)
; #define PG8_LDB(dst, b, h) do { _Pragma("unroll") for (int n = 0; n < 2; ++n) _Pragma("unroll") for (int k = 0; k < 2; ++k) dst[n][k] = *(const PG8_LAS bf16x8*)(lds + PG8_SB(b, h) + boff + n * 2048 + k * 1024); } while (0)
; #define PG8_MMA(ai, bj, At, Bt) do { __builtin_amdgcn_s_setprio(1); _Pragma("unroll") for (int m = 0; m < 4; ++m) _Pragma("unroll") for (int n = 0; n < 2; ++n) _Pragma("unroll") for (int k = 0; k < 2; ++k) \
;         acc[ai][bj][m][n] = mma16<Epi::F16A>(Bt[n][k], At[m][k], acc[ai][bj][m][n]); __builtin_amdgcn_s_setprio(0); } while (0)
; #define PG8_WAIT_V(n) asm volatile("s_waitcnt vmcnt(" #n ")" ::: "memory")
; #define PG8_WAIT_L(n) asm volatile("s_waitcnt lgkmcnt(" #n ")" ::: "memory")
; #define PG8_BAR __builtin_amdgcn_s_barrier()
; template <class Epi, class Sched, bool ALIGN_EPI = false, bool SP2 = false>
; __device__ __forceinline__ void gemm_phase(PG8_LAS unsigned char* lds, const Gemm g, const Sched& S, const Epi& E) {
;     ...
;             const bool last = (t == nt - 2);
;             const char* a1 = cA + (size_t)(t + 1) * kstep;
;             const char* a2 = last ? nA : cA + (size_t)(t + 2) * kstep; const char* b2 = last ? nB : cB + (size_t)(t + 2) * kstep;
;             const char* a3 = a2 + kstep; const char* b3 = b2 + kstep;
;             if (last && has_next) S.a_ready(nxt);
;             if constexpr (SP2) {
;             PG8_LDB(B0, 0, 0); PG8_LDB(B1, 0, 1); PG8_SCHED; PG8_LDA(At, 0, 0); PG8_STAGE(PG8_SA(1, 1), a1 + hstep, voffA);
;             PG8_WAIT_V(8); PG8_WAIT_L(0); PG8_BAR; PG8_MMA(0, 0, At, B0); PG8_MMA(0, 1, At, B1); PG8_BAR; PG8_SCHED;
;             PG8_LDA(At, 0, 1); PG8_STAGE(PG8_SB(0, 0), b2, voffB); PG8_STAGE(PG8_SB(0, 1), b2 + hstep, voffB); PG8_STAGE(PG8_SA(0, 0), a2, voffA);
;             PG8_WAIT_V(8); PG8_WAIT_L(0); PG8_BAR; PG8_MMA(1, 0, At, B0); PG8_MMA(1, 1, At, B1); PG8_BAR; PG8_SCHED;
.LBB0_770:
	s_add_u32 s37, s26, 0xfffc0080
	s_addc_u32 s38, s27, -1
	s_add_i32 s57, 0, 0x10000
	s_cmp_eq_u32 s5, 12
	s_cselect_b32 s41, s21, s38
	s_cselect_b32 s40, s53, s37
	v_add_u32_e32 v144, s57, v148
	s_cselect_b32 s39, s17, s4
	s_cselect_b32 s38, s54, s55
	s_add_i32 s37, 0, 0x14000
	ds_read_b128 v[140:143], v144
	ds_read_b128 v[150:153], v144 offset:1024
	ds_read_b128 v[154:157], v144 offset:2048
	ds_read_b128 v[158:161], v144 offset:3072
	v_add_u32_e32 v144, s37, v148
	ds_read_b128 v[182:185], v144
	ds_read_b128 v[186:189], v144 offset:1024
	ds_read_b128 v[190:193], v144 offset:2048
	ds_read_b128 v[194:197], v144 offset:3072
	v_lshl_add_u64 v[144:145], s[26:27], 0, v[136:137]
	s_add_i32 m0, s33, 0xc000
	ds_read_b128 v[198:201], v149
	ds_read_b128 v[202:205], v149 offset:1024
	ds_read_b128 v[206:209], v149 offset:2048
	ds_read_b128 v[210:213], v149 offset:3072
	ds_read_b128 v[214:217], v149 offset:4096
	ds_read_b128 v[218:221], v149 offset:5120
	ds_read_b128 v[222:225], v149 offset:6144
	ds_read_b128 v[226:229], v149 offset:7168
	global_load_lds_dwordx4 v[144:145], off
	v_lshl_add_u64 v[144:145], s[26:27], 0, v[138:139]
	s_add_i32 m0, s33, 0xe000
	s_nop 0
	global_load_lds_dwordx4 v[144:145], off
	s_waitcnt vmcnt(8)
	s_waitcnt lgkmcnt(0)
	s_barrier
	s_waitcnt lgkmcnt(0)
	v_mfma_f32_16x16x32_bf16 v[126:129], v[140:143], v[198:201], v[126:129]
	v_mfma_f32_16x16x32_bf16 v[122:125], v[154:157], v[198:201], v[122:125]
	v_mfma_f32_16x16x32_bf16 v[110:113], v[140:143], v[206:209], v[110:113]
	v_mfma_f32_16x16x32_bf16 v[106:109], v[154:157], v[206:209], v[106:109]
	v_mfma_f32_16x16x32_bf16 v[94:97], v[140:143], v[214:217], v[94:97]
	v_mfma_f32_16x16x32_bf16 v[90:93], v[154:157], v[214:217], v[90:93]
	v_mfma_f32_16x16x32_bf16 v[78:81], v[140:143], v[222:225], v[78:81]
	v_mfma_f32_16x16x32_bf16 v[74:77], v[154:157], v[222:225], v[74:77]
	v_mfma_f32_16x16x32_bf16 v[126:129], v[150:153], v[202:205], v[126:129]
	v_mfma_f32_16x16x32_bf16 v[122:125], v[158:161], v[202:205], v[122:125]
	v_mfma_f32_16x16x32_bf16 v[110:113], v[150:153], v[210:213], v[110:113]
	v_mfma_f32_16x16x32_bf16 v[106:109], v[158:161], v[210:213], v[106:109]
	v_mfma_f32_16x16x32_bf16 v[94:97], v[150:153], v[218:221], v[94:97]
	v_mfma_f32_16x16x32_bf16 v[90:93], v[158:161], v[218:221], v[90:93]
	v_mfma_f32_16x16x32_bf16 v[78:81], v[150:153], v[226:229], v[78:81]
	v_mfma_f32_16x16x32_bf16 v[74:77], v[158:161], v[226:229], v[74:77]
	v_mfma_f32_16x16x32_bf16 v[118:121], v[182:185], v[198:201], v[118:121]
	v_mfma_f32_16x16x32_bf16 v[114:117], v[190:193], v[198:201], v[114:117]
	v_mfma_f32_16x16x32_bf16 v[102:105], v[182:185], v[206:209], v[102:105]
	v_mfma_f32_16x16x32_bf16 v[98:101], v[190:193], v[206:209], v[98:101]
	v_mfma_f32_16x16x32_bf16 v[86:89], v[182:185], v[214:217], v[86:89]
	v_mfma_f32_16x16x32_bf16 v[82:85], v[190:193], v[214:217], v[82:85]
	v_mfma_f32_16x16x32_bf16 v[70:73], v[182:185], v[222:225], v[70:73]
	v_mfma_f32_16x16x32_bf16 v[66:69], v[190:193], v[222:225], v[66:69]
	v_mfma_f32_16x16x32_bf16 v[118:121], v[186:189], v[202:205], v[118:121]
	v_mfma_f32_16x16x32_bf16 v[114:117], v[194:197], v[202:205], v[114:117]
	v_mfma_f32_16x16x32_bf16 v[102:105], v[186:189], v[210:213], v[102:105]
	v_mfma_f32_16x16x32_bf16 v[98:101], v[194:197], v[210:213], v[98:101]
	v_mfma_f32_16x16x32_bf16 v[86:89], v[186:189], v[218:221], v[86:89]
	v_mfma_f32_16x16x32_bf16 v[82:85], v[194:197], v[218:221], v[82:85]
	v_mfma_f32_16x16x32_bf16 v[70:73], v[186:189], v[226:229], v[70:73]
	v_mfma_f32_16x16x32_bf16 v[66:69], v[194:197], v[226:229], v[66:69]
	s_barrier
	s_add_i32 s57, s57, s31
	v_lshl_add_u64 v[144:145], s[38:39], 0, v[0:1]
	s_mov_b32 m0, s57
	ds_read_b128 v[198:201], v149 offset:16384
	ds_read_b128 v[202:205], v149 offset:17408
	ds_read_b128 v[206:209], v149 offset:18432
	ds_read_b128 v[210:213], v149 offset:19456
	ds_read_b128 v[214:217], v149 offset:20480
	ds_read_b128 v[218:221], v149 offset:21504
	ds_read_b128 v[222:225], v149 offset:22528
	ds_read_b128 v[226:229], v149 offset:23552
	global_load_lds_dwordx4 v[144:145], off
	s_add_i32 m0, s57, 0x2000
	s_add_u32 s64, s38, 0x40000
	v_lshl_add_u64 v[162:163], s[38:39], 0, v[130:131]
	s_addc_u32 s65, s39, 0
	s_add_i32 s37, s37, s31
	global_load_lds_dwordx4 v[162:163], off
	v_lshl_add_u64 v[230:231], s[64:65], 0, v[0:1]
	s_mov_b32 m0, s37
	v_lshl_add_u64 v[234:235], s[40:41], 0, v[132:133]
	global_load_lds_dwordx4 v[230:231], off
	v_lshl_add_u64 v[230:231], s[64:65], 0, v[130:131]
	s_add_i32 m0, s37, 0x2000
	s_nop 0
	global_load_lds_dwordx4 v[230:231], off
	v_lshl_add_u64 v[230:231], s[40:41], 0, v[134:135]
	s_mov_b32 m0, s33
	s_nop 0
	global_load_lds_dwordx4 v[230:231], off
	s_mov_b32 m0, s36
	s_nop 0
	global_load_lds_dwordx4 v[234:235], off
	s_waitcnt vmcnt(8)
	s_waitcnt lgkmcnt(0)
	s_barrier
; #define PG8_STAGE(bufoff, gbase, voff) do { _Pragma("unroll") for (int _i = 0; _i < 2; ++_i) \
;         __builtin_amdgcn_global_load_lds((const unsigned*)((const char*)(gbase) + (voff)[_i]), (PG8_LAS unsigned*)(lds + (bufoff) + ldsw + _i * 8192), 16, 0, 0); } while (0)
; #define PG8_LDA(dst, b, h) do { _Pragma("unroll") for (int m = 0; m < 4; ++m) _Pragma("unroll") for (int k = 0; k < 2; ++k) dst[m][k] = *(const PG8_LAS bf16x8*)(lds + PG8_SA(b, h) + aoff + m * 2048 + k * 1024); } while (0)
; #define PG8_LDB(dst, b, h) do { _Pragma("unroll") for (int n = 0; n < 2; ++n) _Pragma("unroll") for (int k = 0; k < 2; ++k) dst[n][k] = *(const PG8_LAS bf16x8*)(lds + PG8_SB(b, h) + boff + n * 2048 + k * 1024); } while (0)
; #define PG8_MMA(ai, bj, At, Bt) do { __builtin_amdgcn_s_setprio(1); _Pragma("unroll") for (int m = 0; m < 4; ++m) _Pragma("unroll") for (int n = 0; n < 2; ++n) _Pragma("unroll") for (int k = 0; k < 2; ++k) \
;         acc[ai][bj][m][n] = mma16<Epi::F16A>(Bt[n][k], At[m][k], acc[ai][bj][m][n]); __builtin_amdgcn_s_setprio(0); } while (0)
; #define PG8_WAIT_V(n) asm volatile("s_waitcnt vmcnt(" #n ")" ::: "memory")
; #define PG8_WAIT_L(n) asm volatile("s_waitcnt lgkmcnt(" #n ")" ::: "memory")
; #define PG8_BAR __builtin_amdgcn_s_barrier()
; #define PG8_SCHED __builtin_amdgcn_sched_barrier(0)
; template <class Epi, class Sched, bool ALIGN_EPI = false, bool SP2 = false>
; __device__ __forceinline__ void gemm_phase(PG8_LAS unsigned char* lds, const Gemm g, const Sched& S, const Epi& E) {
;     ...
;             PG8_WAIT_V(8); PG8_WAIT_L(0); PG8_BAR; PG8_MMA(1, 0, At, B0); PG8_MMA(1, 1, At, B1); PG8_BAR; PG8_SCHED;
;             PG8_LDB(B0, 1, 0); PG8_LDB(B1, 1, 1); PG8_SCHED; PG8_LDA(At, 1, 0); PG8_STAGE(PG8_SA(0, 1), a2 + hstep, voffA);
;             PG8_WAIT_V(8); PG8_WAIT_L(0); PG8_BAR; PG8_MMA(0, 0, At, B0); PG8_MMA(0, 1, At, B1); PG8_BAR; PG8_SCHED;
	s_waitcnt lgkmcnt(0)
	v_mfma_f32_16x16x32_bf16 v[62:65], v[140:143], v[198:201], v[62:65]
	v_mfma_f32_16x16x32_bf16 v[58:61], v[154:157], v[198:201], v[58:61]
	v_mfma_f32_16x16x32_bf16 v[46:49], v[140:143], v[206:209], v[46:49]
	v_mfma_f32_16x16x32_bf16 v[42:45], v[154:157], v[206:209], v[42:45]
	v_mfma_f32_16x16x32_bf16 v[30:33], v[140:143], v[214:217], v[30:33]
	v_mfma_f32_16x16x32_bf16 v[26:29], v[154:157], v[214:217], v[26:29]
	v_mfma_f32_16x16x32_bf16 v[14:17], v[140:143], v[222:225], v[14:17]
	v_mfma_f32_16x16x32_bf16 v[10:13], v[154:157], v[222:225], v[10:13]
	v_mfma_f32_16x16x32_bf16 v[62:65], v[150:153], v[202:205], v[62:65]
	v_mfma_f32_16x16x32_bf16 v[58:61], v[158:161], v[202:205], v[58:61]
	v_mfma_f32_16x16x32_bf16 v[46:49], v[150:153], v[210:213], v[46:49]
	v_mfma_f32_16x16x32_bf16 v[42:45], v[158:161], v[210:213], v[42:45]
	v_mfma_f32_16x16x32_bf16 v[30:33], v[150:153], v[218:221], v[30:33]
	v_mfma_f32_16x16x32_bf16 v[26:29], v[158:161], v[218:221], v[26:29]
	v_mfma_f32_16x16x32_bf16 v[14:17], v[150:153], v[226:229], v[14:17]
	v_mfma_f32_16x16x32_bf16 v[10:13], v[158:161], v[226:229], v[10:13]
	v_mfma_f32_16x16x32_bf16 v[54:57], v[182:185], v[198:201], v[54:57]
	v_mfma_f32_16x16x32_bf16 v[50:53], v[190:193], v[198:201], v[50:53]
	v_mfma_f32_16x16x32_bf16 v[38:41], v[182:185], v[206:209], v[38:41]
	v_mfma_f32_16x16x32_bf16 v[34:37], v[190:193], v[206:209], v[34:37]
	v_mfma_f32_16x16x32_bf16 v[22:25], v[182:185], v[214:217], v[22:25]
	v_mfma_f32_16x16x32_bf16 v[18:21], v[190:193], v[214:217], v[18:21]
	v_mfma_f32_16x16x32_bf16 v[6:9], v[182:185], v[222:225], v[6:9]
	v_mfma_f32_16x16x32_bf16 v[2:5], v[190:193], v[222:225], v[2:5]
	v_mfma_f32_16x16x32_bf16 v[54:57], v[186:189], v[202:205], v[54:57]
	v_mfma_f32_16x16x32_bf16 v[50:53], v[194:197], v[202:205], v[50:53]
	v_mfma_f32_16x16x32_bf16 v[38:41], v[186:189], v[210:213], v[38:41]
	v_mfma_f32_16x16x32_bf16 v[34:37], v[194:197], v[210:213], v[34:37]
	v_mfma_f32_16x16x32_bf16 v[22:25], v[186:189], v[218:221], v[22:25]
	v_mfma_f32_16x16x32_bf16 v[18:21], v[194:197], v[218:221], v[18:21]
	v_mfma_f32_16x16x32_bf16 v[6:9], v[186:189], v[226:229], v[6:9]
	v_mfma_f32_16x16x32_bf16 v[2:5], v[194:197], v[226:229], v[2:5]
	s_barrier
	s_add_i32 s37, 0, 0x18000
	s_add_i32 s57, 0, 0x1c000
	v_add_u32_e32 v158, s37, v148
	v_add_u32_e32 v194, s57, v148
	ds_read_b128 v[140:143], v158
	ds_read_b128 v[150:153], v158 offset:1024
	ds_read_b128 v[154:157], v158 offset:2048
	ds_read_b128 v[158:161], v158 offset:3072
	ds_read_b128 v[182:185], v194
	ds_read_b128 v[186:189], v194 offset:1024
	ds_read_b128 v[190:193], v194 offset:2048
	ds_read_b128 v[194:197], v194 offset:3072
	s_add_u32 s40, s40, 0x40000
	s_addc_u32 s41, s41, 0
	s_mov_b32 m0, s43
	v_lshl_add_u64 v[236:237], s[40:41], 0, v[134:135]
	ds_read_b128 v[198:201], v149 offset:32768
	ds_read_b128 v[202:205], v149 offset:33792
	ds_read_b128 v[206:209], v149 offset:34816
	ds_read_b128 v[210:213], v149 offset:35840
	ds_read_b128 v[214:217], v149 offset:36864
	ds_read_b128 v[218:221], v149 offset:37888
	ds_read_b128 v[222:225], v149 offset:38912
	ds_read_b128 v[226:229], v149 offset:39936
	global_load_lds_dwordx4 v[236:237], off
	v_lshl_add_u64 v[236:237], s[40:41], 0, v[132:133]
	s_mov_b32 m0, s44
	s_nop 0
	global_load_lds_dwordx4 v[236:237], off
	s_waitcnt vmcnt(8)
	s_waitcnt lgkmcnt(0)
	s_barrier
	s_waitcnt lgkmcnt(0)
	v_mfma_f32_16x16x32_bf16 v[126:129], v[140:143], v[198:201], v[126:129]
	v_mfma_f32_16x16x32_bf16 v[122:125], v[154:157], v[198:201], v[122:125]
	v_mfma_f32_16x16x32_bf16 v[110:113], v[140:143], v[206:209], v[110:113]
	v_mfma_f32_16x16x32_bf16 v[106:109], v[154:157], v[206:209], v[106:109]
	v_mfma_f32_16x16x32_bf16 v[94:97], v[140:143], v[214:217], v[94:97]
	v_mfma_f32_16x16x32_bf16 v[90:93], v[154:157], v[214:217], v[90:93]
	v_mfma_f32_16x16x32_bf16 v[78:81], v[140:143], v[222:225], v[78:81]
	v_mfma_f32_16x16x32_bf16 v[74:77], v[154:157], v[222:225], v[74:77]
	v_mfma_f32_16x16x32_bf16 v[126:129], v[150:153], v[202:205], v[126:129]
	v_mfma_f32_16x16x32_bf16 v[122:125], v[158:161], v[202:205], v[122:125]
	v_mfma_f32_16x16x32_bf16 v[110:113], v[150:153], v[210:213], v[110:113]
	v_mfma_f32_16x16x32_bf16 v[106:109], v[158:161], v[210:213], v[106:109]
	v_mfma_f32_16x16x32_bf16 v[94:97], v[150:153], v[218:221], v[94:97]
	v_mfma_f32_16x16x32_bf16 v[90:93], v[158:161], v[218:221], v[90:93]
	v_mfma_f32_16x16x32_bf16 v[78:81], v[150:153], v[226:229], v[78:81]
	v_mfma_f32_16x16x32_bf16 v[74:77], v[158:161], v[226:229], v[74:77]
	v_mfma_f32_16x16x32_bf16 v[118:121], v[182:185], v[198:201], v[118:121]
	v_mfma_f32_16x16x32_bf16 v[114:117], v[190:193], v[198:201], v[114:117]
	v_mfma_f32_16x16x32_bf16 v[102:105], v[182:185], v[206:209], v[102:105]
	v_mfma_f32_16x16x32_bf16 v[98:101], v[190:193], v[206:209], v[98:101]
	v_mfma_f32_16x16x32_bf16 v[86:89], v[182:185], v[214:217], v[86:89]
	v_mfma_f32_16x16x32_bf16 v[82:85], v[190:193], v[214:217], v[82:85]
	v_mfma_f32_16x16x32_bf16 v[70:73], v[182:185], v[222:225], v[70:73]
	v_mfma_f32_16x16x32_bf16 v[66:69], v[190:193], v[222:225], v[66:69]
	v_mfma_f32_16x16x32_bf16 v[118:121], v[186:189], v[202:205], v[118:121]
	v_mfma_f32_16x16x32_bf16 v[114:117], v[194:197], v[202:205], v[114:117]
	v_mfma_f32_16x16x32_bf16 v[102:105], v[186:189], v[210:213], v[102:105]
	v_mfma_f32_16x16x32_bf16 v[98:101], v[194:197], v[210:213], v[98:101]
	v_mfma_f32_16x16x32_bf16 v[86:89], v[186:189], v[218:221], v[86:89]
	v_mfma_f32_16x16x32_bf16 v[82:85], v[194:197], v[218:221], v[82:85]
	v_mfma_f32_16x16x32_bf16 v[70:73], v[186:189], v[226:229], v[70:73]
	v_mfma_f32_16x16x32_bf16 v[66:69], v[194:197], v[226:229], v[66:69]
	s_barrier
; #define PG8_STAGE(bufoff, gbase, voff) do { _Pragma("unroll") for (int _i = 0; _i < 2; ++_i) \
;         __builtin_amdgcn_global_load_lds((const unsigned*)((const char*)(gbase) + (voff)[_i]), (PG8_LAS unsigned*)(lds + (bufoff) + ldsw + _i * 8192), 16, 0, 0); } while (0)
; #define PG8_LDA(dst, b, h) do { _Pragma("unroll") for (int m = 0; m < 4; ++m) _Pragma("unroll") for (int k = 0; k < 2; ++k) dst[m][k] = *(const PG8_LAS bf16x8*)(lds + PG8_SA(b, h) + aoff + m * 2048 + k * 1024); } while (0)
; #define PG8_MMA(ai, bj, At, Bt) do { __builtin_amdgcn_s_setprio(1); _Pragma("unroll") for (int m = 0; m < 4; ++m) _Pragma("unroll") for (int n = 0; n < 2; ++n) _Pragma("unroll") for (int k = 0; k < 2; ++k) \
;         acc[ai][bj][m][n] = mma16<Epi::F16A>(Bt[n][k], At[m][k], acc[ai][bj][m][n]); __builtin_amdgcn_s_setprio(0); } while (0)
; #define PG8_WAIT_V(n) asm volatile("s_waitcnt vmcnt(" #n ")" ::: "memory")
; #define PG8_WAIT_L(n) asm volatile("s_waitcnt lgkmcnt(" #n ")" ::: "memory")
; #define PG8_BAR __builtin_amdgcn_s_barrier()
; #define PG8_SCHED __builtin_amdgcn_sched_barrier(0)
; template <class Epi, class Sched, bool ALIGN_EPI = false, bool SP2 = false>
; __device__ __forceinline__ void gemm_phase(PG8_LAS unsigned char* lds, const Gemm g, const Sched& S, const Epi& E) {
;     ...
;         for (int t = 0; t < nt; t += 2) {
;             const bool last = (t == nt - 2);
;     ...
;             PG8_LDA(At, 1, 1); PG8_STAGE(PG8_SB(1, 0), b3, voffB); PG8_STAGE(PG8_SB(1, 1), b3 + hstep, voffB); PG8_STAGE(PG8_SA(1, 0), a3, voffA);
;             PG8_WAIT_V(8); PG8_WAIT_L(0); PG8_BAR; PG8_MMA(1, 0, At, B0); PG8_MMA(1, 1, At, B1); PG8_BAR; PG8_SCHED;
	s_add_i32 s37, s37, s31
	v_lshl_add_u64 v[144:145], v[144:145], 0, s[92:93]
	s_mov_b32 m0, s37
	ds_read_b128 v[198:201], v149 offset:49152
	ds_read_b128 v[202:205], v149 offset:50176
	ds_read_b128 v[206:209], v149 offset:51200
	ds_read_b128 v[210:213], v149 offset:52224
	ds_read_b128 v[214:217], v149 offset:53248
	ds_read_b128 v[218:221], v149 offset:54272
	ds_read_b128 v[222:225], v149 offset:55296
	ds_read_b128 v[226:229], v149 offset:56320
	global_load_lds_dwordx4 v[144:145], off
	s_add_i32 m0, s37, 0x2000
	s_add_u32 s38, s38, 0x40080
	v_lshl_add_u64 v[144:145], v[162:163], 0, s[92:93]
	s_addc_u32 s39, s39, 0
	s_add_i32 s37, s57, s31
	global_load_lds_dwordx4 v[144:145], off
	v_lshl_add_u64 v[144:145], s[38:39], 0, v[0:1]
	s_mov_b32 m0, s37
	s_nop 0
	global_load_lds_dwordx4 v[144:145], off
	v_lshl_add_u64 v[144:145], s[38:39], 0, v[130:131]
	s_add_i32 m0, s37, 0x2000
	s_nop 0
	global_load_lds_dwordx4 v[144:145], off
	v_lshl_add_u64 v[144:145], v[230:231], 0, s[92:93]
	s_mov_b32 m0, s48
	s_nop 0
	global_load_lds_dwordx4 v[144:145], off
	v_lshl_add_u64 v[144:145], v[234:235], 0, s[92:93]
	s_mov_b32 m0, s49
	s_nop 0
	global_load_lds_dwordx4 v[144:145], off
	s_waitcnt vmcnt(8)
	s_waitcnt lgkmcnt(0)
	s_barrier
	s_waitcnt lgkmcnt(0)
	v_mfma_f32_16x16x32_bf16 v[62:65], v[140:143], v[198:201], v[62:65]
	v_mfma_f32_16x16x32_bf16 v[58:61], v[154:157], v[198:201], v[58:61]
	v_mfma_f32_16x16x32_bf16 v[46:49], v[140:143], v[206:209], v[46:49]
	v_mfma_f32_16x16x32_bf16 v[42:45], v[154:157], v[206:209], v[42:45]
	v_mfma_f32_16x16x32_bf16 v[30:33], v[140:143], v[214:217], v[30:33]
	v_mfma_f32_16x16x32_bf16 v[26:29], v[154:157], v[214:217], v[26:29]
	v_mfma_f32_16x16x32_bf16 v[14:17], v[140:143], v[222:225], v[14:17]
	v_mfma_f32_16x16x32_bf16 v[10:13], v[154:157], v[222:225], v[10:13]
	v_mfma_f32_16x16x32_bf16 v[62:65], v[150:153], v[202:205], v[62:65]
	v_mfma_f32_16x16x32_bf16 v[58:61], v[158:161], v[202:205], v[58:61]
	v_mfma_f32_16x16x32_bf16 v[46:49], v[150:153], v[210:213], v[46:49]
	v_mfma_f32_16x16x32_bf16 v[42:45], v[158:161], v[210:213], v[42:45]
	v_mfma_f32_16x16x32_bf16 v[30:33], v[150:153], v[218:221], v[30:33]
	v_mfma_f32_16x16x32_bf16 v[26:29], v[158:161], v[218:221], v[26:29]
	v_mfma_f32_16x16x32_bf16 v[14:17], v[150:153], v[226:229], v[14:17]
	v_mfma_f32_16x16x32_bf16 v[10:13], v[158:161], v[226:229], v[10:13]
	v_mfma_f32_16x16x32_bf16 v[54:57], v[182:185], v[198:201], v[54:57]
	v_mfma_f32_16x16x32_bf16 v[50:53], v[190:193], v[198:201], v[50:53]
	v_mfma_f32_16x16x32_bf16 v[38:41], v[182:185], v[206:209], v[38:41]
	v_mfma_f32_16x16x32_bf16 v[34:37], v[190:193], v[206:209], v[34:37]
	v_mfma_f32_16x16x32_bf16 v[22:25], v[182:185], v[214:217], v[22:25]
	v_mfma_f32_16x16x32_bf16 v[18:21], v[190:193], v[214:217], v[18:21]
	v_mfma_f32_16x16x32_bf16 v[6:9], v[182:185], v[222:225], v[6:9]
	v_mfma_f32_16x16x32_bf16 v[2:5], v[190:193], v[222:225], v[2:5]
	v_mfma_f32_16x16x32_bf16 v[54:57], v[186:189], v[202:205], v[54:57]
	v_mfma_f32_16x16x32_bf16 v[50:53], v[194:197], v[202:205], v[50:53]
	v_mfma_f32_16x16x32_bf16 v[38:41], v[186:189], v[210:213], v[38:41]
	v_mfma_f32_16x16x32_bf16 v[34:37], v[194:197], v[210:213], v[34:37]
	v_mfma_f32_16x16x32_bf16 v[22:25], v[186:189], v[218:221], v[22:25]
	v_mfma_f32_16x16x32_bf16 v[18:21], v[194:197], v[218:221], v[18:21]
	v_mfma_f32_16x16x32_bf16 v[6:9], v[186:189], v[226:229], v[6:9]
	v_mfma_f32_16x16x32_bf16 v[2:5], v[194:197], v[226:229], v[2:5]
	s_barrier
	s_add_i32 s5, s5, 2
	s_add_u32 s26, s26, 0x100
	s_addc_u32 s27, s27, 0
	s_add_u32 s55, s55, 0x100
	s_addc_u32 s4, s4, 0
	s_cmp_gt_u32 s5, 13
	s_cbranch_scc0 .LBB0_770
	s_and_b64 vcc, exec, s[12:13]
	s_cbranch_vccz .LBB0_773
	s_barrier

; #define PG8_STAGE(bufoff, gbase, voff) do { _Pragma("unroll") for (int _i = 0; _i < 2; ++_i) \
;         __builtin_amdgcn_global_load_lds((const unsigned*)((const char*)(gbase) + (voff)[_i]), (PG8_LAS unsigned*)(lds + (bufoff) + ldsw + _i * 8192), 16, 0, 0); } while (0)
; #define PG8_LDA(dst, b, h) do { _Pragma("unroll") for (int m = 0; m < 4; ++m) _Pragma("unroll") for (int k = 0; k < 2; ++k) dst[m][k] = *(const PG8_LAS bf16x8*)(lds + PG8_SA(b, h) + aoff + m * 2048 + k * 1024); } while (0)
; #define PG8_LDB(dst, b, h) do { _Pragma("unroll") for (int n = 0; n < 2; ++n) _Pragma("unroll") for (int k = 0; k < 2; ++k) dst[n][k] = *(const PG8_LAS bf16x8*)(lds + PG8_SB(b, h) + boff + n * 2048 + k * 1024); } while (0)
; #define PG8_MMA(ai, bj, At, Bt) do { __builtin_amdgcn_s_setprio(1); _Pragma("unroll") for (int m = 0; m < 4; ++m) _Pragma("unroll") for (int n = 0; n < 2; ++n) _Pragma("unroll") for (int k = 0; k < 2; ++k) \
;         acc[ai][bj][m][n] = mma16<Epi::F16A>(Bt[n][k], At[m][k], acc[ai][bj][m][n]); __builtin_amdgcn_s_setprio(0); } while (0)
; #define PG8_WAIT_V(n) asm volatile("s_waitcnt vmcnt(" #n ")" ::: "memory")
; #define PG8_WAIT_L(n) asm volatile("s_waitcnt lgkmcnt(" #n ")" ::: "memory")
; #define PG8_BAR __builtin_amdgcn_s_barrier()
; template <class Epi, class Sched, bool ALIGN_EPI = false, bool SP2 = false>
; __device__ __forceinline__ void gemm_phase(PG8_LAS unsigned char* lds, const Gemm g, const Sched& S, const Epi& E) {
;     ...
;             const bool last = (t == nt - 2);
;             const char* a1 = cA + (size_t)(t + 1) * kstep;
;             const char* a2 = last ? nA : cA + (size_t)(t + 2) * kstep; const char* b2 = last ? nB : cB + (size_t)(t + 2) * kstep;
;             const char* a3 = a2 + kstep; const char* b3 = b2 + kstep;
;             if (last && has_next) S.a_ready(nxt);
;             if constexpr (SP2) {
;             PG8_LDB(B0, 0, 0); PG8_LDB(B1, 0, 1); PG8_SCHED; PG8_LDA(At, 0, 0); PG8_STAGE(PG8_SA(1, 1), a1 + hstep, voffA);
;             PG8_WAIT_V(8); PG8_WAIT_L(0); PG8_BAR; PG8_MMA(0, 0, At, B0); PG8_MMA(0, 1, At, B1); PG8_BAR; PG8_SCHED;
;             PG8_LDA(At, 0, 1); PG8_STAGE(PG8_SB(0, 0), b2, voffB); PG8_STAGE(PG8_SB(0, 1), b2 + hstep, voffB); PG8_STAGE(PG8_SA(0, 0), a2, voffA);
;             PG8_WAIT_V(8); PG8_WAIT_L(0); PG8_BAR; PG8_MMA(1, 0, At, B0); PG8_MMA(1, 1, At, B1); PG8_BAR; PG8_SCHED;
.LBB0_902:
	s_add_u32 s26, s24, 0xfffc0080
	s_addc_u32 s27, s25, -1
	s_add_i32 s37, 0, 0x10000
	s_cmp_eq_u32 s5, 12
	s_cselect_b32 s39, s17, s27
	s_cselect_b32 s38, s52, s26
	s_cselect_b32 s27, s13, s4
	s_cselect_b32 s26, s53, s54
	s_add_i32 s55, 0, 0x14000
	v_add_u32_e32 v156, s37, v146
	v_add_u32_e32 v190, s55, v146
	ds_read_b128 v[140:143], v156
	ds_read_b128 v[148:151], v156 offset:1024
	ds_read_b128 v[152:155], v156 offset:2048
	ds_read_b128 v[156:159], v156 offset:3072
	ds_read_b128 v[160:163], v190
	ds_read_b128 v[182:185], v190 offset:1024
	ds_read_b128 v[186:189], v190 offset:2048
	ds_read_b128 v[190:193], v190 offset:3072
	v_lshl_add_u64 v[226:227], s[24:25], 0, v[136:137]
	s_add_i32 m0, s33, 0xc000
	ds_read_b128 v[194:197], v147
	ds_read_b128 v[198:201], v147 offset:1024
	ds_read_b128 v[202:205], v147 offset:2048
	ds_read_b128 v[206:209], v147 offset:3072
	ds_read_b128 v[210:213], v147 offset:4096
	ds_read_b128 v[214:217], v147 offset:5120
	ds_read_b128 v[218:221], v147 offset:6144
	ds_read_b128 v[222:225], v147 offset:7168
	global_load_lds_dwordx4 v[226:227], off
	v_lshl_add_u64 v[226:227], s[24:25], 0, v[138:139]
	s_add_i32 m0, s33, 0xe000
	s_nop 0
	global_load_lds_dwordx4 v[226:227], off
	s_waitcnt vmcnt(8)
	s_waitcnt lgkmcnt(0)
	s_barrier
	s_waitcnt lgkmcnt(0)
	v_mfma_f32_16x16x32_bf16 v[126:129], v[140:143], v[194:197], v[126:129]
	v_mfma_f32_16x16x32_bf16 v[122:125], v[152:155], v[194:197], v[122:125]
	v_mfma_f32_16x16x32_bf16 v[118:121], v[140:143], v[202:205], v[118:121]
	v_mfma_f32_16x16x32_bf16 v[114:117], v[152:155], v[202:205], v[114:117]
	v_mfma_f32_16x16x32_bf16 v[94:97], v[140:143], v[210:213], v[94:97]
	v_mfma_f32_16x16x32_bf16 v[90:93], v[152:155], v[210:213], v[90:93]
	v_mfma_f32_16x16x32_bf16 v[86:89], v[140:143], v[218:221], v[86:89]
	v_mfma_f32_16x16x32_bf16 v[82:85], v[152:155], v[218:221], v[82:85]
	v_mfma_f32_16x16x32_bf16 v[126:129], v[148:151], v[198:201], v[126:129]
	v_mfma_f32_16x16x32_bf16 v[122:125], v[156:159], v[198:201], v[122:125]
	v_mfma_f32_16x16x32_bf16 v[118:121], v[148:151], v[206:209], v[118:121]
	v_mfma_f32_16x16x32_bf16 v[114:117], v[156:159], v[206:209], v[114:117]
	v_mfma_f32_16x16x32_bf16 v[94:97], v[148:151], v[214:217], v[94:97]
	v_mfma_f32_16x16x32_bf16 v[90:93], v[156:159], v[214:217], v[90:93]
	v_mfma_f32_16x16x32_bf16 v[86:89], v[148:151], v[222:225], v[86:89]
	v_mfma_f32_16x16x32_bf16 v[82:85], v[156:159], v[222:225], v[82:85]
	v_mfma_f32_16x16x32_bf16 v[110:113], v[160:163], v[194:197], v[110:113]
	v_mfma_f32_16x16x32_bf16 v[106:109], v[186:189], v[194:197], v[106:109]
	v_mfma_f32_16x16x32_bf16 v[102:105], v[160:163], v[202:205], v[102:105]
	v_mfma_f32_16x16x32_bf16 v[98:101], v[186:189], v[202:205], v[98:101]
	v_mfma_f32_16x16x32_bf16 v[78:81], v[160:163], v[210:213], v[78:81]
	v_mfma_f32_16x16x32_bf16 v[74:77], v[186:189], v[210:213], v[74:77]
	v_mfma_f32_16x16x32_bf16 v[70:73], v[160:163], v[218:221], v[70:73]
	v_mfma_f32_16x16x32_bf16 v[66:69], v[186:189], v[218:221], v[66:69]
	v_mfma_f32_16x16x32_bf16 v[110:113], v[182:185], v[198:201], v[110:113]
	v_mfma_f32_16x16x32_bf16 v[106:109], v[190:193], v[198:201], v[106:109]
	v_mfma_f32_16x16x32_bf16 v[102:105], v[182:185], v[206:209], v[102:105]
	v_mfma_f32_16x16x32_bf16 v[98:101], v[190:193], v[206:209], v[98:101]
	v_mfma_f32_16x16x32_bf16 v[78:81], v[182:185], v[214:217], v[78:81]
	v_mfma_f32_16x16x32_bf16 v[74:77], v[190:193], v[214:217], v[74:77]
	v_mfma_f32_16x16x32_bf16 v[70:73], v[182:185], v[222:225], v[70:73]
	v_mfma_f32_16x16x32_bf16 v[66:69], v[190:193], v[222:225], v[66:69]
	s_barrier
	s_add_i32 s37, s37, s28
	v_lshl_add_u64 v[226:227], s[26:27], 0, v[0:1]
	s_mov_b32 m0, s37
	ds_read_b128 v[194:197], v147 offset:16384
	ds_read_b128 v[198:201], v147 offset:17408
	ds_read_b128 v[202:205], v147 offset:18432
	ds_read_b128 v[206:209], v147 offset:19456
	ds_read_b128 v[210:213], v147 offset:20480
	ds_read_b128 v[214:217], v147 offset:21504
	ds_read_b128 v[218:221], v147 offset:22528
	ds_read_b128 v[222:225], v147 offset:23552
	global_load_lds_dwordx4 v[226:227], off
	s_add_i32 m0, s37, 0x2000
	s_add_u32 s64, s26, 0x40000
	v_lshl_add_u64 v[228:229], s[26:27], 0, v[130:131]
	s_addc_u32 s65, s27, 0
	s_add_i32 s37, s55, s28
	global_load_lds_dwordx4 v[228:229], off
	v_lshl_add_u64 v[230:231], s[64:65], 0, v[0:1]
	s_mov_b32 m0, s37
	v_lshl_add_u64 v[234:235], s[38:39], 0, v[132:133]
	global_load_lds_dwordx4 v[230:231], off
	v_lshl_add_u64 v[230:231], s[64:65], 0, v[130:131]
	s_add_i32 m0, s37, 0x2000
	s_nop 0
	global_load_lds_dwordx4 v[230:231], off
	v_lshl_add_u64 v[230:231], s[38:39], 0, v[134:135]
	s_mov_b32 m0, s33
	s_nop 0
	global_load_lds_dwordx4 v[230:231], off
	s_mov_b32 m0, s36
	s_nop 0
	global_load_lds_dwordx4 v[234:235], off
	s_waitcnt vmcnt(8)
	s_waitcnt lgkmcnt(0)
	s_barrier
; #define PG8_STAGE(bufoff, gbase, voff) do { _Pragma("unroll") for (int _i = 0; _i < 2; ++_i) \
;         __builtin_amdgcn_global_load_lds((const unsigned*)((const char*)(gbase) + (voff)[_i]), (PG8_LAS unsigned*)(lds + (bufoff) + ldsw + _i * 8192), 16, 0, 0); } while (0)
; #define PG8_LDA(dst, b, h) do { _Pragma("unroll") for (int m = 0; m < 4; ++m) _Pragma("unroll") for (int k = 0; k < 2; ++k) dst[m][k] = *(const PG8_LAS bf16x8*)(lds + PG8_SA(b, h) + aoff + m * 2048 + k * 1024); } while (0)
; #define PG8_LDB(dst, b, h) do { _Pragma("unroll") for (int n = 0; n < 2; ++n) _Pragma("unroll") for (int k = 0; k < 2; ++k) dst[n][k] = *(const PG8_LAS bf16x8*)(lds + PG8_SB(b, h) + boff + n * 2048 + k * 1024); } while (0)
; #define PG8_MMA(ai, bj, At, Bt) do { __builtin_amdgcn_s_setprio(1); _Pragma("unroll") for (int m = 0; m < 4; ++m) _Pragma("unroll") for (int n = 0; n < 2; ++n) _Pragma("unroll") for (int k = 0; k < 2; ++k) \
;         acc[ai][bj][m][n] = mma16<Epi::F16A>(Bt[n][k], At[m][k], acc[ai][bj][m][n]); __builtin_amdgcn_s_setprio(0); } while (0)
; #define PG8_WAIT_V(n) asm volatile("s_waitcnt vmcnt(" #n ")" ::: "memory")
; #define PG8_WAIT_L(n) asm volatile("s_waitcnt lgkmcnt(" #n ")" ::: "memory")
; #define PG8_BAR __builtin_amdgcn_s_barrier()
; #define PG8_SCHED __builtin_amdgcn_sched_barrier(0)
; template <class Epi, class Sched, bool ALIGN_EPI = false, bool SP2 = false>
; __device__ __forceinline__ void gemm_phase(PG8_LAS unsigned char* lds, const Gemm g, const Sched& S, const Epi& E) {
;     ...
;             PG8_WAIT_V(8); PG8_WAIT_L(0); PG8_BAR; PG8_MMA(1, 0, At, B0); PG8_MMA(1, 1, At, B1); PG8_BAR; PG8_SCHED;
;             PG8_LDB(B0, 1, 0); PG8_LDB(B1, 1, 1); PG8_SCHED; PG8_LDA(At, 1, 0); PG8_STAGE(PG8_SA(0, 1), a2 + hstep, voffA);
;             PG8_WAIT_V(8); PG8_WAIT_L(0); PG8_BAR; PG8_MMA(0, 0, At, B0); PG8_MMA(0, 1, At, B1); PG8_BAR; PG8_SCHED;
	s_waitcnt lgkmcnt(0)
	v_mfma_f32_16x16x32_bf16 v[62:65], v[140:143], v[194:197], v[62:65]
	v_mfma_f32_16x16x32_bf16 v[58:61], v[152:155], v[194:197], v[58:61]
	v_mfma_f32_16x16x32_bf16 v[54:57], v[140:143], v[202:205], v[54:57]
	v_mfma_f32_16x16x32_bf16 v[50:53], v[152:155], v[202:205], v[50:53]
	v_mfma_f32_16x16x32_bf16 v[30:33], v[140:143], v[210:213], v[30:33]
	v_mfma_f32_16x16x32_bf16 v[26:29], v[152:155], v[210:213], v[26:29]
	v_mfma_f32_16x16x32_bf16 v[22:25], v[140:143], v[218:221], v[22:25]
	v_mfma_f32_16x16x32_bf16 v[18:21], v[152:155], v[218:221], v[18:21]
	v_mfma_f32_16x16x32_bf16 v[62:65], v[148:151], v[198:201], v[62:65]
	v_mfma_f32_16x16x32_bf16 v[58:61], v[156:159], v[198:201], v[58:61]
	v_mfma_f32_16x16x32_bf16 v[54:57], v[148:151], v[206:209], v[54:57]
	v_mfma_f32_16x16x32_bf16 v[50:53], v[156:159], v[206:209], v[50:53]
	v_mfma_f32_16x16x32_bf16 v[30:33], v[148:151], v[214:217], v[30:33]
	v_mfma_f32_16x16x32_bf16 v[26:29], v[156:159], v[214:217], v[26:29]
	v_mfma_f32_16x16x32_bf16 v[22:25], v[148:151], v[222:225], v[22:25]
	v_mfma_f32_16x16x32_bf16 v[18:21], v[156:159], v[222:225], v[18:21]
	v_mfma_f32_16x16x32_bf16 v[46:49], v[160:163], v[194:197], v[46:49]
	v_mfma_f32_16x16x32_bf16 v[42:45], v[186:189], v[194:197], v[42:45]
	v_mfma_f32_16x16x32_bf16 v[38:41], v[160:163], v[202:205], v[38:41]
	v_mfma_f32_16x16x32_bf16 v[34:37], v[186:189], v[202:205], v[34:37]
	v_mfma_f32_16x16x32_bf16 v[14:17], v[160:163], v[210:213], v[14:17]
	v_mfma_f32_16x16x32_bf16 v[10:13], v[186:189], v[210:213], v[10:13]
	v_mfma_f32_16x16x32_bf16 v[6:9], v[160:163], v[218:221], v[6:9]
	v_mfma_f32_16x16x32_bf16 v[2:5], v[186:189], v[218:221], v[2:5]
	v_mfma_f32_16x16x32_bf16 v[46:49], v[182:185], v[198:201], v[46:49]
	v_mfma_f32_16x16x32_bf16 v[42:45], v[190:193], v[198:201], v[42:45]
	v_mfma_f32_16x16x32_bf16 v[38:41], v[182:185], v[206:209], v[38:41]
	v_mfma_f32_16x16x32_bf16 v[34:37], v[190:193], v[206:209], v[34:37]
	v_mfma_f32_16x16x32_bf16 v[14:17], v[182:185], v[214:217], v[14:17]
	v_mfma_f32_16x16x32_bf16 v[10:13], v[190:193], v[214:217], v[10:13]
	v_mfma_f32_16x16x32_bf16 v[6:9], v[182:185], v[222:225], v[6:9]
	v_mfma_f32_16x16x32_bf16 v[2:5], v[190:193], v[222:225], v[2:5]
	s_barrier
	s_add_i32 s37, 0, 0x18000
	s_add_i32 s55, 0, 0x1c000
	v_add_u32_e32 v156, s37, v146
	v_add_u32_e32 v190, s55, v146
	ds_read_b128 v[140:143], v156
	ds_read_b128 v[148:151], v156 offset:1024
	ds_read_b128 v[152:155], v156 offset:2048
	ds_read_b128 v[156:159], v156 offset:3072
	ds_read_b128 v[160:163], v190
	ds_read_b128 v[182:185], v190 offset:1024
	ds_read_b128 v[186:189], v190 offset:2048
	ds_read_b128 v[190:193], v190 offset:3072
	s_add_u32 s38, s38, 0x40000
	s_addc_u32 s39, s39, 0
	s_mov_b32 m0, s40
	v_lshl_add_u64 v[236:237], s[38:39], 0, v[134:135]
	ds_read_b128 v[194:197], v147 offset:32768
	ds_read_b128 v[198:201], v147 offset:33792
	ds_read_b128 v[202:205], v147 offset:34816
	ds_read_b128 v[206:209], v147 offset:35840
	ds_read_b128 v[210:213], v147 offset:36864
	ds_read_b128 v[214:217], v147 offset:37888
	ds_read_b128 v[218:221], v147 offset:38912
	ds_read_b128 v[222:225], v147 offset:39936
	global_load_lds_dwordx4 v[236:237], off
	v_lshl_add_u64 v[236:237], s[38:39], 0, v[132:133]
	s_mov_b32 m0, s41
	s_nop 0
	global_load_lds_dwordx4 v[236:237], off
	s_waitcnt vmcnt(8)
	s_waitcnt lgkmcnt(0)
	s_barrier
	s_waitcnt lgkmcnt(0)
	v_mfma_f32_16x16x32_bf16 v[126:129], v[140:143], v[194:197], v[126:129]
	v_mfma_f32_16x16x32_bf16 v[122:125], v[152:155], v[194:197], v[122:125]
	v_mfma_f32_16x16x32_bf16 v[118:121], v[140:143], v[202:205], v[118:121]
	v_mfma_f32_16x16x32_bf16 v[114:117], v[152:155], v[202:205], v[114:117]
	v_mfma_f32_16x16x32_bf16 v[94:97], v[140:143], v[210:213], v[94:97]
	v_mfma_f32_16x16x32_bf16 v[90:93], v[152:155], v[210:213], v[90:93]
	v_mfma_f32_16x16x32_bf16 v[86:89], v[140:143], v[218:221], v[86:89]
	v_mfma_f32_16x16x32_bf16 v[82:85], v[152:155], v[218:221], v[82:85]
	v_mfma_f32_16x16x32_bf16 v[126:129], v[148:151], v[198:201], v[126:129]
	v_mfma_f32_16x16x32_bf16 v[122:125], v[156:159], v[198:201], v[122:125]
	v_mfma_f32_16x16x32_bf16 v[118:121], v[148:151], v[206:209], v[118:121]
	v_mfma_f32_16x16x32_bf16 v[114:117], v[156:159], v[206:209], v[114:117]
	v_mfma_f32_16x16x32_bf16 v[94:97], v[148:151], v[214:217], v[94:97]
	v_mfma_f32_16x16x32_bf16 v[90:93], v[156:159], v[214:217], v[90:93]
	v_mfma_f32_16x16x32_bf16 v[86:89], v[148:151], v[222:225], v[86:89]
	v_mfma_f32_16x16x32_bf16 v[82:85], v[156:159], v[222:225], v[82:85]
	v_mfma_f32_16x16x32_bf16 v[110:113], v[160:163], v[194:197], v[110:113]
	v_mfma_f32_16x16x32_bf16 v[106:109], v[186:189], v[194:197], v[106:109]
	v_mfma_f32_16x16x32_bf16 v[102:105], v[160:163], v[202:205], v[102:105]
	v_mfma_f32_16x16x32_bf16 v[98:101], v[186:189], v[202:205], v[98:101]
	v_mfma_f32_16x16x32_bf16 v[78:81], v[160:163], v[210:213], v[78:81]
	v_mfma_f32_16x16x32_bf16 v[74:77], v[186:189], v[210:213], v[74:77]
	v_mfma_f32_16x16x32_bf16 v[70:73], v[160:163], v[218:221], v[70:73]
	v_mfma_f32_16x16x32_bf16 v[66:69], v[186:189], v[218:221], v[66:69]
	v_mfma_f32_16x16x32_bf16 v[110:113], v[182:185], v[198:201], v[110:113]
	v_mfma_f32_16x16x32_bf16 v[106:109], v[190:193], v[198:201], v[106:109]
	v_mfma_f32_16x16x32_bf16 v[102:105], v[182:185], v[206:209], v[102:105]
	v_mfma_f32_16x16x32_bf16 v[98:101], v[190:193], v[206:209], v[98:101]
	v_mfma_f32_16x16x32_bf16 v[78:81], v[182:185], v[214:217], v[78:81]
	v_mfma_f32_16x16x32_bf16 v[74:77], v[190:193], v[214:217], v[74:77]
	v_mfma_f32_16x16x32_bf16 v[70:73], v[182:185], v[222:225], v[70:73]
	v_mfma_f32_16x16x32_bf16 v[66:69], v[190:193], v[222:225], v[66:69]
	s_barrier
; #define PG8_STAGE(bufoff, gbase, voff) do { _Pragma("unroll") for (int _i = 0; _i < 2; ++_i) \
;         __builtin_amdgcn_global_load_lds((const unsigned*)((const char*)(gbase) + (voff)[_i]), (PG8_LAS unsigned*)(lds + (bufoff) + ldsw + _i * 8192), 16, 0, 0); } while (0)
; #define PG8_LDA(dst, b, h) do { _Pragma("unroll") for (int m = 0; m < 4; ++m) _Pragma("unroll") for (int k = 0; k < 2; ++k) dst[m][k] = *(const PG8_LAS bf16x8*)(lds + PG8_SA(b, h) + aoff + m * 2048 + k * 1024); } while (0)
; #define PG8_MMA(ai, bj, At, Bt) do { __builtin_amdgcn_s_setprio(1); _Pragma("unroll") for (int m = 0; m < 4; ++m) _Pragma("unroll") for (int n = 0; n < 2; ++n) _Pragma("unroll") for (int k = 0; k < 2; ++k) \
;         acc[ai][bj][m][n] = mma16<Epi::F16A>(Bt[n][k], At[m][k], acc[ai][bj][m][n]); __builtin_amdgcn_s_setprio(0); } while (0)
; #define PG8_WAIT_V(n) asm volatile("s_waitcnt vmcnt(" #n ")" ::: "memory")
; #define PG8_WAIT_L(n) asm volatile("s_waitcnt lgkmcnt(" #n ")" ::: "memory")
; #define PG8_BAR __builtin_amdgcn_s_barrier()
; #define PG8_SCHED __builtin_amdgcn_sched_barrier(0)
; template <class Epi, class Sched, bool ALIGN_EPI = false, bool SP2 = false>
; __device__ __forceinline__ void gemm_phase(PG8_LAS unsigned char* lds, const Gemm g, const Sched& S, const Epi& E) {
;     ...
;         for (int t = 0; t < nt; t += 2) {
;             const bool last = (t == nt - 2);
;     ...
;             PG8_LDA(At, 1, 1); PG8_STAGE(PG8_SB(1, 0), b3, voffB); PG8_STAGE(PG8_SB(1, 1), b3 + hstep, voffB); PG8_STAGE(PG8_SA(1, 0), a3, voffA);
;             PG8_WAIT_V(8); PG8_WAIT_L(0); PG8_BAR; PG8_MMA(1, 0, At, B0); PG8_MMA(1, 1, At, B1); PG8_BAR; PG8_SCHED;
	s_add_i32 s37, s37, s28
	v_lshl_add_u64 v[226:227], v[226:227], 0, s[92:93]
	s_mov_b32 m0, s37
	ds_read_b128 v[194:197], v147 offset:49152
	ds_read_b128 v[198:201], v147 offset:50176
	ds_read_b128 v[202:205], v147 offset:51200
	ds_read_b128 v[206:209], v147 offset:52224
	ds_read_b128 v[210:213], v147 offset:53248
	ds_read_b128 v[214:217], v147 offset:54272
	ds_read_b128 v[218:221], v147 offset:55296
	ds_read_b128 v[222:225], v147 offset:56320
	global_load_lds_dwordx4 v[226:227], off
	s_add_i32 m0, s37, 0x2000
	s_add_u32 s26, s26, 0x40080
	v_lshl_add_u64 v[226:227], v[228:229], 0, s[92:93]
	s_addc_u32 s27, s27, 0
	s_add_i32 s37, s55, s28
	global_load_lds_dwordx4 v[226:227], off
	v_lshl_add_u64 v[226:227], s[26:27], 0, v[0:1]
	s_mov_b32 m0, s37
	s_nop 0
	global_load_lds_dwordx4 v[226:227], off
	v_lshl_add_u64 v[226:227], s[26:27], 0, v[130:131]
	s_add_i32 m0, s37, 0x2000
	s_nop 0
	global_load_lds_dwordx4 v[226:227], off
	v_lshl_add_u64 v[226:227], v[230:231], 0, s[92:93]
	s_mov_b32 m0, s45
	s_nop 0
	global_load_lds_dwordx4 v[226:227], off
	v_lshl_add_u64 v[226:227], v[234:235], 0, s[92:93]
	s_mov_b32 m0, s46
	s_nop 0
	global_load_lds_dwordx4 v[226:227], off
	s_waitcnt vmcnt(8)
	s_waitcnt lgkmcnt(0)
	s_barrier
	s_waitcnt lgkmcnt(0)
	v_mfma_f32_16x16x32_bf16 v[62:65], v[140:143], v[194:197], v[62:65]
	v_mfma_f32_16x16x32_bf16 v[58:61], v[152:155], v[194:197], v[58:61]
	v_mfma_f32_16x16x32_bf16 v[54:57], v[140:143], v[202:205], v[54:57]
	v_mfma_f32_16x16x32_bf16 v[50:53], v[152:155], v[202:205], v[50:53]
	v_mfma_f32_16x16x32_bf16 v[30:33], v[140:143], v[210:213], v[30:33]
	v_mfma_f32_16x16x32_bf16 v[26:29], v[152:155], v[210:213], v[26:29]
	v_mfma_f32_16x16x32_bf16 v[22:25], v[140:143], v[218:221], v[22:25]
	v_mfma_f32_16x16x32_bf16 v[18:21], v[152:155], v[218:221], v[18:21]
	v_mfma_f32_16x16x32_bf16 v[62:65], v[148:151], v[198:201], v[62:65]
	v_mfma_f32_16x16x32_bf16 v[58:61], v[156:159], v[198:201], v[58:61]
	v_mfma_f32_16x16x32_bf16 v[54:57], v[148:151], v[206:209], v[54:57]
	v_mfma_f32_16x16x32_bf16 v[50:53], v[156:159], v[206:209], v[50:53]
	v_mfma_f32_16x16x32_bf16 v[30:33], v[148:151], v[214:217], v[30:33]
	v_mfma_f32_16x16x32_bf16 v[26:29], v[156:159], v[214:217], v[26:29]
	v_mfma_f32_16x16x32_bf16 v[22:25], v[148:151], v[222:225], v[22:25]
	v_mfma_f32_16x16x32_bf16 v[18:21], v[156:159], v[222:225], v[18:21]
	v_mfma_f32_16x16x32_bf16 v[46:49], v[160:163], v[194:197], v[46:49]
	v_mfma_f32_16x16x32_bf16 v[42:45], v[186:189], v[194:197], v[42:45]
	v_mfma_f32_16x16x32_bf16 v[38:41], v[160:163], v[202:205], v[38:41]
	v_mfma_f32_16x16x32_bf16 v[34:37], v[186:189], v[202:205], v[34:37]
	v_mfma_f32_16x16x32_bf16 v[14:17], v[160:163], v[210:213], v[14:17]
	v_mfma_f32_16x16x32_bf16 v[10:13], v[186:189], v[210:213], v[10:13]
	v_mfma_f32_16x16x32_bf16 v[6:9], v[160:163], v[218:221], v[6:9]
	v_mfma_f32_16x16x32_bf16 v[2:5], v[186:189], v[218:221], v[2:5]
	v_mfma_f32_16x16x32_bf16 v[46:49], v[182:185], v[198:201], v[46:49]
	v_mfma_f32_16x16x32_bf16 v[42:45], v[190:193], v[198:201], v[42:45]
	v_mfma_f32_16x16x32_bf16 v[38:41], v[182:185], v[206:209], v[38:41]
	v_mfma_f32_16x16x32_bf16 v[34:37], v[190:193], v[206:209], v[34:37]
	v_mfma_f32_16x16x32_bf16 v[14:17], v[182:185], v[214:217], v[14:17]
	v_mfma_f32_16x16x32_bf16 v[10:13], v[190:193], v[214:217], v[10:13]
	v_mfma_f32_16x16x32_bf16 v[6:9], v[182:185], v[222:225], v[6:9]
	v_mfma_f32_16x16x32_bf16 v[2:5], v[190:193], v[222:225], v[2:5]
	s_barrier
	s_add_i32 s5, s5, 2
	s_add_u32 s24, s24, 0x100
	s_addc_u32 s25, s25, 0
	s_add_u32 s54, s54, 0x100
	s_addc_u32 s4, s4, 0
	s_cmp_gt_u32 s5, 13
	s_cbranch_scc0 .LBB0_902
	s_and_b64 vcc, exec, s[10:11]
	s_cbranch_vccz .LBB0_905
	s_barrier

; #define PG8_STAGE(bufoff, gbase, voff) do { _Pragma("unroll") for (int _i = 0; _i < 2; ++_i) \
;         __builtin_amdgcn_global_load_lds((const unsigned*)((const char*)(gbase) + (voff)[_i]), (PG8_LAS unsigned*)(lds + (bufoff) + ldsw + _i * 8192), 16, 0, 0); } while (0)
; #define PG8_LDA(dst, b, h) do { _Pragma("unroll") for (int m = 0; m < 4; ++m) _Pragma("unroll") for (int k = 0; k < 2; ++k) dst[m][k] = *(const PG8_LAS bf16x8*)(lds + PG8_SA(b, h) + aoff + m * 2048 + k * 1024); } while (0)
; #define PG8_LDB(dst, b, h) do { _Pragma("unroll") for (int n = 0; n < 2; ++n) _Pragma("unroll") for (int k = 0; k < 2; ++k) dst[n][k] = *(const PG8_LAS bf16x8*)(lds + PG8_SB(b, h) + boff + n * 2048 + k * 1024); } while (0)
; #define PG8_MMA(ai, bj, At, Bt) do { __builtin_amdgcn_s_setprio(1); _Pragma("unroll") for (int m = 0; m < 4; ++m) _Pragma("unroll") for (int n = 0; n < 2; ++n) _Pragma("unroll") for (int k = 0; k < 2; ++k) \
;         acc[ai][bj][m][n] = mma16<Epi::F16A>(Bt[n][k], At[m][k], acc[ai][bj][m][n]); __builtin_amdgcn_s_setprio(0); } while (0)
; #define PG8_WAIT_V(n) asm volatile("s_waitcnt vmcnt(" #n ")" ::: "memory")
; #define PG8_WAIT_L(n) asm volatile("s_waitcnt lgkmcnt(" #n ")" ::: "memory")
; #define PG8_BAR __builtin_amdgcn_s_barrier()
; template <class Epi, class Sched, bool ALIGN_EPI = false, bool SP2 = false>
; __device__ __forceinline__ void gemm_phase(PG8_LAS unsigned char* lds, const Gemm g, const Sched& S, const Epi& E) {
;     ...
;             const bool last = (t == nt - 2);
;             const char* a1 = cA + (size_t)(t + 1) * kstep;
;             const char* a2 = last ? nA : cA + (size_t)(t + 2) * kstep; const char* b2 = last ? nB : cB + (size_t)(t + 2) * kstep;
;             const char* a3 = a2 + kstep; const char* b3 = b2 + kstep;
;             if (last && has_next) S.a_ready(nxt);
;             if constexpr (SP2) {
;             PG8_LDB(B0, 0, 0); PG8_LDB(B1, 0, 1); PG8_SCHED; PG8_LDA(At, 0, 0); PG8_STAGE(PG8_SA(1, 1), a1 + hstep, voffA);
;             PG8_WAIT_V(8); PG8_WAIT_L(0); PG8_BAR; PG8_MMA(0, 0, At, B0); PG8_MMA(0, 1, At, B1); PG8_BAR; PG8_SCHED;
;             PG8_LDA(At, 0, 1); PG8_STAGE(PG8_SB(0, 0), b2, voffB); PG8_STAGE(PG8_SB(0, 1), b2 + hstep, voffB); PG8_STAGE(PG8_SA(0, 0), a2, voffA);
;             PG8_WAIT_V(8); PG8_WAIT_L(0); PG8_BAR; PG8_MMA(1, 0, At, B0); PG8_MMA(1, 1, At, B1); PG8_BAR; PG8_SCHED;
.LBB0_1063:
	s_add_u32 s37, s26, 0xfffe0080
	s_addc_u32 s38, s27, -1
	s_add_i32 s57, 0, 0x10000
	s_cmp_eq_u32 s5, 4
	s_cselect_b32 s41, s21, s38
	s_cselect_b32 s40, s53, s37
	v_add_u32_e32 v144, s57, v148
	s_cselect_b32 s39, s17, s4
	s_cselect_b32 s38, s54, s55
	s_add_i32 s37, 0, 0x14000
	ds_read_b128 v[140:143], v144
	ds_read_b128 v[150:153], v144 offset:1024
	ds_read_b128 v[154:157], v144 offset:2048
	ds_read_b128 v[158:161], v144 offset:3072
	v_add_u32_e32 v144, s37, v148
	ds_read_b128 v[182:185], v144
	ds_read_b128 v[186:189], v144 offset:1024
	ds_read_b128 v[190:193], v144 offset:2048
	ds_read_b128 v[194:197], v144 offset:3072
	v_lshl_add_u64 v[144:145], s[26:27], 0, v[136:137]
	s_add_i32 m0, s33, 0xc000
	ds_read_b128 v[198:201], v149
	ds_read_b128 v[202:205], v149 offset:1024
	ds_read_b128 v[206:209], v149 offset:2048
	ds_read_b128 v[210:213], v149 offset:3072
	ds_read_b128 v[214:217], v149 offset:4096
	ds_read_b128 v[218:221], v149 offset:5120
	ds_read_b128 v[222:225], v149 offset:6144
	ds_read_b128 v[226:229], v149 offset:7168
	global_load_lds_dwordx4 v[144:145], off
	v_lshl_add_u64 v[144:145], s[26:27], 0, v[138:139]
	s_add_i32 m0, s33, 0xe000
	s_nop 0
	global_load_lds_dwordx4 v[144:145], off
	s_waitcnt vmcnt(8)
	s_waitcnt lgkmcnt(0)
	s_barrier
	s_waitcnt lgkmcnt(0)
	v_mfma_f32_16x16x32_bf16 v[126:129], v[140:143], v[198:201], v[126:129]
	v_mfma_f32_16x16x32_bf16 v[122:125], v[154:157], v[198:201], v[122:125]
	v_mfma_f32_16x16x32_bf16 v[110:113], v[140:143], v[206:209], v[110:113]
	v_mfma_f32_16x16x32_bf16 v[106:109], v[154:157], v[206:209], v[106:109]
	v_mfma_f32_16x16x32_bf16 v[94:97], v[140:143], v[214:217], v[94:97]
	v_mfma_f32_16x16x32_bf16 v[90:93], v[154:157], v[214:217], v[90:93]
	v_mfma_f32_16x16x32_bf16 v[78:81], v[140:143], v[222:225], v[78:81]
	v_mfma_f32_16x16x32_bf16 v[74:77], v[154:157], v[222:225], v[74:77]
	v_mfma_f32_16x16x32_bf16 v[126:129], v[150:153], v[202:205], v[126:129]
	v_mfma_f32_16x16x32_bf16 v[122:125], v[158:161], v[202:205], v[122:125]
	v_mfma_f32_16x16x32_bf16 v[110:113], v[150:153], v[210:213], v[110:113]
	v_mfma_f32_16x16x32_bf16 v[106:109], v[158:161], v[210:213], v[106:109]
	v_mfma_f32_16x16x32_bf16 v[94:97], v[150:153], v[218:221], v[94:97]
	v_mfma_f32_16x16x32_bf16 v[90:93], v[158:161], v[218:221], v[90:93]
	v_mfma_f32_16x16x32_bf16 v[78:81], v[150:153], v[226:229], v[78:81]
	v_mfma_f32_16x16x32_bf16 v[74:77], v[158:161], v[226:229], v[74:77]
	v_mfma_f32_16x16x32_bf16 v[118:121], v[182:185], v[198:201], v[118:121]
	v_mfma_f32_16x16x32_bf16 v[114:117], v[190:193], v[198:201], v[114:117]
	v_mfma_f32_16x16x32_bf16 v[102:105], v[182:185], v[206:209], v[102:105]
	v_mfma_f32_16x16x32_bf16 v[98:101], v[190:193], v[206:209], v[98:101]
	v_mfma_f32_16x16x32_bf16 v[86:89], v[182:185], v[214:217], v[86:89]
	v_mfma_f32_16x16x32_bf16 v[82:85], v[190:193], v[214:217], v[82:85]
	v_mfma_f32_16x16x32_bf16 v[70:73], v[182:185], v[222:225], v[70:73]
	v_mfma_f32_16x16x32_bf16 v[66:69], v[190:193], v[222:225], v[66:69]
	v_mfma_f32_16x16x32_bf16 v[118:121], v[186:189], v[202:205], v[118:121]
	v_mfma_f32_16x16x32_bf16 v[114:117], v[194:197], v[202:205], v[114:117]
	v_mfma_f32_16x16x32_bf16 v[102:105], v[186:189], v[210:213], v[102:105]
	v_mfma_f32_16x16x32_bf16 v[98:101], v[194:197], v[210:213], v[98:101]
	v_mfma_f32_16x16x32_bf16 v[86:89], v[186:189], v[218:221], v[86:89]
	v_mfma_f32_16x16x32_bf16 v[82:85], v[194:197], v[218:221], v[82:85]
	v_mfma_f32_16x16x32_bf16 v[70:73], v[186:189], v[226:229], v[70:73]
	v_mfma_f32_16x16x32_bf16 v[66:69], v[194:197], v[226:229], v[66:69]
	s_barrier
	s_add_i32 s57, s57, s31
	v_lshl_add_u64 v[144:145], s[38:39], 0, v[0:1]
	s_mov_b32 m0, s57
	ds_read_b128 v[198:201], v149 offset:16384
	ds_read_b128 v[202:205], v149 offset:17408
	ds_read_b128 v[206:209], v149 offset:18432
	ds_read_b128 v[210:213], v149 offset:19456
	ds_read_b128 v[214:217], v149 offset:20480
	ds_read_b128 v[218:221], v149 offset:21504
	ds_read_b128 v[222:225], v149 offset:22528
	ds_read_b128 v[226:229], v149 offset:23552
	global_load_lds_dwordx4 v[144:145], off
	s_add_i32 m0, s57, 0x2000
	s_add_u32 s64, s38, 0x20000
	v_lshl_add_u64 v[162:163], s[38:39], 0, v[130:131]
	s_addc_u32 s65, s39, 0
	s_add_i32 s37, s37, s31
	global_load_lds_dwordx4 v[162:163], off
	v_lshl_add_u64 v[230:231], s[64:65], 0, v[0:1]
	s_mov_b32 m0, s37
	v_lshl_add_u64 v[234:235], s[40:41], 0, v[132:133]
	global_load_lds_dwordx4 v[230:231], off
	v_lshl_add_u64 v[230:231], s[64:65], 0, v[130:131]
	s_add_i32 m0, s37, 0x2000
	s_nop 0
	global_load_lds_dwordx4 v[230:231], off
	v_lshl_add_u64 v[230:231], s[40:41], 0, v[134:135]
	s_mov_b32 m0, s33
	s_nop 0
	global_load_lds_dwordx4 v[230:231], off
	s_mov_b32 m0, s36
	s_nop 0
	global_load_lds_dwordx4 v[234:235], off
	s_waitcnt vmcnt(8)
	s_waitcnt lgkmcnt(0)
	s_barrier
; #define PG8_STAGE(bufoff, gbase, voff) do { _Pragma("unroll") for (int _i = 0; _i < 2; ++_i) \
;         __builtin_amdgcn_global_load_lds((const unsigned*)((const char*)(gbase) + (voff)[_i]), (PG8_LAS unsigned*)(lds + (bufoff) + ldsw + _i * 8192), 16, 0, 0); } while (0)
; #define PG8_LDA(dst, b, h) do { _Pragma("unroll") for (int m = 0; m < 4; ++m) _Pragma("unroll") for (int k = 0; k < 2; ++k) dst[m][k] = *(const PG8_LAS bf16x8*)(lds + PG8_SA(b, h) + aoff + m * 2048 + k * 1024); } while (0)
; #define PG8_LDB(dst, b, h) do { _Pragma("unroll") for (int n = 0; n < 2; ++n) _Pragma("unroll") for (int k = 0; k < 2; ++k) dst[n][k] = *(const PG8_LAS bf16x8*)(lds + PG8_SB(b, h) + boff + n * 2048 + k * 1024); } while (0)
; #define PG8_MMA(ai, bj, At, Bt) do { __builtin_amdgcn_s_setprio(1); _Pragma("unroll") for (int m = 0; m < 4; ++m) _Pragma("unroll") for (int n = 0; n < 2; ++n) _Pragma("unroll") for (int k = 0; k < 2; ++k) \
;         acc[ai][bj][m][n] = mma16<Epi::F16A>(Bt[n][k], At[m][k], acc[ai][bj][m][n]); __builtin_amdgcn_s_setprio(0); } while (0)
; #define PG8_WAIT_V(n) asm volatile("s_waitcnt vmcnt(" #n ")" ::: "memory")
; #define PG8_WAIT_L(n) asm volatile("s_waitcnt lgkmcnt(" #n ")" ::: "memory")
; #define PG8_BAR __builtin_amdgcn_s_barrier()
; #define PG8_SCHED __builtin_amdgcn_sched_barrier(0)
; template <class Epi, class Sched, bool ALIGN_EPI = false, bool SP2 = false>
; __device__ __forceinline__ void gemm_phase(PG8_LAS unsigned char* lds, const Gemm g, const Sched& S, const Epi& E) {
;     ...
;             PG8_WAIT_V(8); PG8_WAIT_L(0); PG8_BAR; PG8_MMA(1, 0, At, B0); PG8_MMA(1, 1, At, B1); PG8_BAR; PG8_SCHED;
;             PG8_LDB(B0, 1, 0); PG8_LDB(B1, 1, 1); PG8_SCHED; PG8_LDA(At, 1, 0); PG8_STAGE(PG8_SA(0, 1), a2 + hstep, voffA);
;             PG8_WAIT_V(8); PG8_WAIT_L(0); PG8_BAR; PG8_MMA(0, 0, At, B0); PG8_MMA(0, 1, At, B1); PG8_BAR; PG8_SCHED;
	s_waitcnt lgkmcnt(0)
	v_mfma_f32_16x16x32_bf16 v[62:65], v[140:143], v[198:201], v[62:65]
	v_mfma_f32_16x16x32_bf16 v[58:61], v[154:157], v[198:201], v[58:61]
	v_mfma_f32_16x16x32_bf16 v[46:49], v[140:143], v[206:209], v[46:49]
	v_mfma_f32_16x16x32_bf16 v[42:45], v[154:157], v[206:209], v[42:45]
	v_mfma_f32_16x16x32_bf16 v[30:33], v[140:143], v[214:217], v[30:33]
	v_mfma_f32_16x16x32_bf16 v[26:29], v[154:157], v[214:217], v[26:29]
	v_mfma_f32_16x16x32_bf16 v[14:17], v[140:143], v[222:225], v[14:17]
	v_mfma_f32_16x16x32_bf16 v[10:13], v[154:157], v[222:225], v[10:13]
	v_mfma_f32_16x16x32_bf16 v[62:65], v[150:153], v[202:205], v[62:65]
	v_mfma_f32_16x16x32_bf16 v[58:61], v[158:161], v[202:205], v[58:61]
	v_mfma_f32_16x16x32_bf16 v[46:49], v[150:153], v[210:213], v[46:49]
	v_mfma_f32_16x16x32_bf16 v[42:45], v[158:161], v[210:213], v[42:45]
	v_mfma_f32_16x16x32_bf16 v[30:33], v[150:153], v[218:221], v[30:33]
	v_mfma_f32_16x16x32_bf16 v[26:29], v[158:161], v[218:221], v[26:29]
	v_mfma_f32_16x16x32_bf16 v[14:17], v[150:153], v[226:229], v[14:17]
	v_mfma_f32_16x16x32_bf16 v[10:13], v[158:161], v[226:229], v[10:13]
	v_mfma_f32_16x16x32_bf16 v[54:57], v[182:185], v[198:201], v[54:57]
	v_mfma_f32_16x16x32_bf16 v[50:53], v[190:193], v[198:201], v[50:53]
	v_mfma_f32_16x16x32_bf16 v[38:41], v[182:185], v[206:209], v[38:41]
	v_mfma_f32_16x16x32_bf16 v[34:37], v[190:193], v[206:209], v[34:37]
	v_mfma_f32_16x16x32_bf16 v[22:25], v[182:185], v[214:217], v[22:25]
	v_mfma_f32_16x16x32_bf16 v[18:21], v[190:193], v[214:217], v[18:21]
	v_mfma_f32_16x16x32_bf16 v[6:9], v[182:185], v[222:225], v[6:9]
	v_mfma_f32_16x16x32_bf16 v[2:5], v[190:193], v[222:225], v[2:5]
	v_mfma_f32_16x16x32_bf16 v[54:57], v[186:189], v[202:205], v[54:57]
	v_mfma_f32_16x16x32_bf16 v[50:53], v[194:197], v[202:205], v[50:53]
	v_mfma_f32_16x16x32_bf16 v[38:41], v[186:189], v[210:213], v[38:41]
	v_mfma_f32_16x16x32_bf16 v[34:37], v[194:197], v[210:213], v[34:37]
	v_mfma_f32_16x16x32_bf16 v[22:25], v[186:189], v[218:221], v[22:25]
	v_mfma_f32_16x16x32_bf16 v[18:21], v[194:197], v[218:221], v[18:21]
	v_mfma_f32_16x16x32_bf16 v[6:9], v[186:189], v[226:229], v[6:9]
	v_mfma_f32_16x16x32_bf16 v[2:5], v[194:197], v[226:229], v[2:5]
	s_barrier
	s_add_i32 s37, 0, 0x18000
	s_add_i32 s57, 0, 0x1c000
	v_add_u32_e32 v158, s37, v148
	v_add_u32_e32 v194, s57, v148
	ds_read_b128 v[140:143], v158
	ds_read_b128 v[150:153], v158 offset:1024
	ds_read_b128 v[154:157], v158 offset:2048
	ds_read_b128 v[158:161], v158 offset:3072
	ds_read_b128 v[182:185], v194
	ds_read_b128 v[186:189], v194 offset:1024
	ds_read_b128 v[190:193], v194 offset:2048
	ds_read_b128 v[194:197], v194 offset:3072
	s_add_u32 s40, s40, 0x20000
	s_addc_u32 s41, s41, 0
	s_mov_b32 m0, s43
	v_lshl_add_u64 v[236:237], s[40:41], 0, v[134:135]
	ds_read_b128 v[198:201], v149 offset:32768
	ds_read_b128 v[202:205], v149 offset:33792
	ds_read_b128 v[206:209], v149 offset:34816
	ds_read_b128 v[210:213], v149 offset:35840
	ds_read_b128 v[214:217], v149 offset:36864
	ds_read_b128 v[218:221], v149 offset:37888
	ds_read_b128 v[222:225], v149 offset:38912
	ds_read_b128 v[226:229], v149 offset:39936
	global_load_lds_dwordx4 v[236:237], off
	v_lshl_add_u64 v[236:237], s[40:41], 0, v[132:133]
	s_mov_b32 m0, s44
	s_nop 0
	global_load_lds_dwordx4 v[236:237], off
	s_waitcnt vmcnt(8)
	s_waitcnt lgkmcnt(0)
	s_barrier
	s_waitcnt lgkmcnt(0)
	v_mfma_f32_16x16x32_bf16 v[126:129], v[140:143], v[198:201], v[126:129]
	v_mfma_f32_16x16x32_bf16 v[122:125], v[154:157], v[198:201], v[122:125]
	v_mfma_f32_16x16x32_bf16 v[110:113], v[140:143], v[206:209], v[110:113]
	v_mfma_f32_16x16x32_bf16 v[106:109], v[154:157], v[206:209], v[106:109]
	v_mfma_f32_16x16x32_bf16 v[94:97], v[140:143], v[214:217], v[94:97]
	v_mfma_f32_16x16x32_bf16 v[90:93], v[154:157], v[214:217], v[90:93]
	v_mfma_f32_16x16x32_bf16 v[78:81], v[140:143], v[222:225], v[78:81]
	v_mfma_f32_16x16x32_bf16 v[74:77], v[154:157], v[222:225], v[74:77]
	v_mfma_f32_16x16x32_bf16 v[126:129], v[150:153], v[202:205], v[126:129]
	v_mfma_f32_16x16x32_bf16 v[122:125], v[158:161], v[202:205], v[122:125]
	v_mfma_f32_16x16x32_bf16 v[110:113], v[150:153], v[210:213], v[110:113]
	v_mfma_f32_16x16x32_bf16 v[106:109], v[158:161], v[210:213], v[106:109]
	v_mfma_f32_16x16x32_bf16 v[94:97], v[150:153], v[218:221], v[94:97]
	v_mfma_f32_16x16x32_bf16 v[90:93], v[158:161], v[218:221], v[90:93]
	v_mfma_f32_16x16x32_bf16 v[78:81], v[150:153], v[226:229], v[78:81]
	v_mfma_f32_16x16x32_bf16 v[74:77], v[158:161], v[226:229], v[74:77]
	v_mfma_f32_16x16x32_bf16 v[118:121], v[182:185], v[198:201], v[118:121]
	v_mfma_f32_16x16x32_bf16 v[114:117], v[190:193], v[198:201], v[114:117]
	v_mfma_f32_16x16x32_bf16 v[102:105], v[182:185], v[206:209], v[102:105]
	v_mfma_f32_16x16x32_bf16 v[98:101], v[190:193], v[206:209], v[98:101]
	v_mfma_f32_16x16x32_bf16 v[86:89], v[182:185], v[214:217], v[86:89]
	v_mfma_f32_16x16x32_bf16 v[82:85], v[190:193], v[214:217], v[82:85]
	v_mfma_f32_16x16x32_bf16 v[70:73], v[182:185], v[222:225], v[70:73]
	v_mfma_f32_16x16x32_bf16 v[66:69], v[190:193], v[222:225], v[66:69]
	v_mfma_f32_16x16x32_bf16 v[118:121], v[186:189], v[202:205], v[118:121]
	v_mfma_f32_16x16x32_bf16 v[114:117], v[194:197], v[202:205], v[114:117]
	v_mfma_f32_16x16x32_bf16 v[102:105], v[186:189], v[210:213], v[102:105]
	v_mfma_f32_16x16x32_bf16 v[98:101], v[194:197], v[210:213], v[98:101]
	v_mfma_f32_16x16x32_bf16 v[86:89], v[186:189], v[218:221], v[86:89]
	v_mfma_f32_16x16x32_bf16 v[82:85], v[194:197], v[218:221], v[82:85]
	v_mfma_f32_16x16x32_bf16 v[70:73], v[186:189], v[226:229], v[70:73]
	v_mfma_f32_16x16x32_bf16 v[66:69], v[194:197], v[226:229], v[66:69]
	s_barrier
; #define PG8_STAGE(bufoff, gbase, voff) do { _Pragma("unroll") for (int _i = 0; _i < 2; ++_i) \
;         __builtin_amdgcn_global_load_lds((const unsigned*)((const char*)(gbase) + (voff)[_i]), (PG8_LAS unsigned*)(lds + (bufoff) + ldsw + _i * 8192), 16, 0, 0); } while (0)
; #define PG8_LDA(dst, b, h) do { _Pragma("unroll") for (int m = 0; m < 4; ++m) _Pragma("unroll") for (int k = 0; k < 2; ++k) dst[m][k] = *(const PG8_LAS bf16x8*)(lds + PG8_SA(b, h) + aoff + m * 2048 + k * 1024); } while (0)
; #define PG8_MMA(ai, bj, At, Bt) do { __builtin_amdgcn_s_setprio(1); _Pragma("unroll") for (int m = 0; m < 4; ++m) _Pragma("unroll") for (int n = 0; n < 2; ++n) _Pragma("unroll") for (int k = 0; k < 2; ++k) \
;         acc[ai][bj][m][n] = mma16<Epi::F16A>(Bt[n][k], At[m][k], acc[ai][bj][m][n]); __builtin_amdgcn_s_setprio(0); } while (0)
; #define PG8_WAIT_V(n) asm volatile("s_waitcnt vmcnt(" #n ")" ::: "memory")
; #define PG8_WAIT_L(n) asm volatile("s_waitcnt lgkmcnt(" #n ")" ::: "memory")
; #define PG8_BAR __builtin_amdgcn_s_barrier()
; #define PG8_SCHED __builtin_amdgcn_sched_barrier(0)
; template <class Epi, class Sched, bool ALIGN_EPI = false, bool SP2 = false>
; __device__ __forceinline__ void gemm_phase(PG8_LAS unsigned char* lds, const Gemm g, const Sched& S, const Epi& E) {
;     ...
;         for (int t = 0; t < nt; t += 2) {
;             const bool last = (t == nt - 2);
;     ...
;             PG8_LDA(At, 1, 1); PG8_STAGE(PG8_SB(1, 0), b3, voffB); PG8_STAGE(PG8_SB(1, 1), b3 + hstep, voffB); PG8_STAGE(PG8_SA(1, 0), a3, voffA);
;             PG8_WAIT_V(8); PG8_WAIT_L(0); PG8_BAR; PG8_MMA(1, 0, At, B0); PG8_MMA(1, 1, At, B1); PG8_BAR; PG8_SCHED;
	s_add_i32 s37, s37, s31
	v_lshl_add_u64 v[144:145], v[144:145], 0, s[92:93]
	s_mov_b32 m0, s37
	ds_read_b128 v[198:201], v149 offset:49152
	ds_read_b128 v[202:205], v149 offset:50176
	ds_read_b128 v[206:209], v149 offset:51200
	ds_read_b128 v[210:213], v149 offset:52224
	ds_read_b128 v[214:217], v149 offset:53248
	ds_read_b128 v[218:221], v149 offset:54272
	ds_read_b128 v[222:225], v149 offset:55296
	ds_read_b128 v[226:229], v149 offset:56320
	global_load_lds_dwordx4 v[144:145], off
	s_add_i32 m0, s37, 0x2000
	s_add_u32 s38, s38, 0x20080
	v_lshl_add_u64 v[144:145], v[162:163], 0, s[92:93]
	s_addc_u32 s39, s39, 0
	s_add_i32 s37, s57, s31
	global_load_lds_dwordx4 v[144:145], off
	v_lshl_add_u64 v[144:145], s[38:39], 0, v[0:1]
	s_mov_b32 m0, s37
	s_nop 0
	global_load_lds_dwordx4 v[144:145], off
	v_lshl_add_u64 v[144:145], s[38:39], 0, v[130:131]
	s_add_i32 m0, s37, 0x2000
	s_nop 0
	global_load_lds_dwordx4 v[144:145], off
	v_lshl_add_u64 v[144:145], v[230:231], 0, s[92:93]
	s_mov_b32 m0, s48
	s_nop 0
	global_load_lds_dwordx4 v[144:145], off
	v_lshl_add_u64 v[144:145], v[234:235], 0, s[92:93]
	s_mov_b32 m0, s49
	s_nop 0
	global_load_lds_dwordx4 v[144:145], off
	s_waitcnt vmcnt(8)
	s_waitcnt lgkmcnt(0)
	s_barrier
	s_waitcnt lgkmcnt(0)
	v_mfma_f32_16x16x32_bf16 v[62:65], v[140:143], v[198:201], v[62:65]
	v_mfma_f32_16x16x32_bf16 v[58:61], v[154:157], v[198:201], v[58:61]
	v_mfma_f32_16x16x32_bf16 v[46:49], v[140:143], v[206:209], v[46:49]
	v_mfma_f32_16x16x32_bf16 v[42:45], v[154:157], v[206:209], v[42:45]
	v_mfma_f32_16x16x32_bf16 v[30:33], v[140:143], v[214:217], v[30:33]
	v_mfma_f32_16x16x32_bf16 v[26:29], v[154:157], v[214:217], v[26:29]
	v_mfma_f32_16x16x32_bf16 v[14:17], v[140:143], v[222:225], v[14:17]
	v_mfma_f32_16x16x32_bf16 v[10:13], v[154:157], v[222:225], v[10:13]
	v_mfma_f32_16x16x32_bf16 v[62:65], v[150:153], v[202:205], v[62:65]
	v_mfma_f32_16x16x32_bf16 v[58:61], v[158:161], v[202:205], v[58:61]
	v_mfma_f32_16x16x32_bf16 v[46:49], v[150:153], v[210:213], v[46:49]
	v_mfma_f32_16x16x32_bf16 v[42:45], v[158:161], v[210:213], v[42:45]
	v_mfma_f32_16x16x32_bf16 v[30:33], v[150:153], v[218:221], v[30:33]
	v_mfma_f32_16x16x32_bf16 v[26:29], v[158:161], v[218:221], v[26:29]
	v_mfma_f32_16x16x32_bf16 v[14:17], v[150:153], v[226:229], v[14:17]
	v_mfma_f32_16x16x32_bf16 v[10:13], v[158:161], v[226:229], v[10:13]
	v_mfma_f32_16x16x32_bf16 v[54:57], v[182:185], v[198:201], v[54:57]
	v_mfma_f32_16x16x32_bf16 v[50:53], v[190:193], v[198:201], v[50:53]
	v_mfma_f32_16x16x32_bf16 v[38:41], v[182:185], v[206:209], v[38:41]
	v_mfma_f32_16x16x32_bf16 v[34:37], v[190:193], v[206:209], v[34:37]
	v_mfma_f32_16x16x32_bf16 v[22:25], v[182:185], v[214:217], v[22:25]
	v_mfma_f32_16x16x32_bf16 v[18:21], v[190:193], v[214:217], v[18:21]
	v_mfma_f32_16x16x32_bf16 v[6:9], v[182:185], v[222:225], v[6:9]
	v_mfma_f32_16x16x32_bf16 v[2:5], v[190:193], v[222:225], v[2:5]
	v_mfma_f32_16x16x32_bf16 v[54:57], v[186:189], v[202:205], v[54:57]
	v_mfma_f32_16x16x32_bf16 v[50:53], v[194:197], v[202:205], v[50:53]
	v_mfma_f32_16x16x32_bf16 v[38:41], v[186:189], v[210:213], v[38:41]
	v_mfma_f32_16x16x32_bf16 v[34:37], v[194:197], v[210:213], v[34:37]
	v_mfma_f32_16x16x32_bf16 v[22:25], v[186:189], v[218:221], v[22:25]
	v_mfma_f32_16x16x32_bf16 v[18:21], v[194:197], v[218:221], v[18:21]
	v_mfma_f32_16x16x32_bf16 v[6:9], v[186:189], v[226:229], v[6:9]
	v_mfma_f32_16x16x32_bf16 v[2:5], v[194:197], v[226:229], v[2:5]
	s_barrier
	s_add_i32 s5, s5, 2
	s_add_u32 s26, s26, 0x100
	s_addc_u32 s27, s27, 0
	s_add_u32 s55, s55, 0x100
	s_addc_u32 s4, s4, 0
	s_cmp_gt_u32 s5, 5
	s_cbranch_scc0 .LBB0_1063
	s_and_b64 vcc, exec, s[12:13]
	s_cbranch_vccz .LBB0_1066
	s_barrier

; #define PG8_STAGE(bufoff, gbase, voff) do { _Pragma("unroll") for (int _i = 0; _i < 2; ++_i) \
;         __builtin_amdgcn_global_load_lds((const unsigned*)((const char*)(gbase) + (voff)[_i]), (PG8_LAS unsigned*)(lds + (bufoff) + ldsw + _i * 8192), 16, 0, 0); } while (0)
; #define PG8_LDA(dst, b, h) do { _Pragma("unroll") for (int m = 0; m < 4; ++m) _Pragma("unroll") for (int k = 0; k < 2; ++k) dst[m][k] = *(const PG8_LAS bf16x8*)(lds + PG8_SA(b, h) + aoff + m * 2048 + k * 1024); } while (0)
; #define PG8_LDB(dst, b, h) do { _Pragma("unroll") for (int n = 0; n < 2; ++n) _Pragma("unroll") for (int k = 0; k < 2; ++k) dst[n][k] = *(const PG8_LAS bf16x8*)(lds + PG8_SB(b, h) + boff + n * 2048 + k * 1024); } while (0)
; #define PG8_MMA(ai, bj, At, Bt) do { __builtin_amdgcn_s_setprio(1); _Pragma("unroll") for (int m = 0; m < 4; ++m) _Pragma("unroll") for (int n = 0; n < 2; ++n) _Pragma("unroll") for (int k = 0; k < 2; ++k) \
;         acc[ai][bj][m][n] = mma16<Epi::F16A>(Bt[n][k], At[m][k], acc[ai][bj][m][n]); __builtin_amdgcn_s_setprio(0); } while (0)
; #define PG8_WAIT_V(n) asm volatile("s_waitcnt vmcnt(" #n ")" ::: "memory")
; #define PG8_WAIT_L(n) asm volatile("s_waitcnt lgkmcnt(" #n ")" ::: "memory")
; #define PG8_BAR __builtin_amdgcn_s_barrier()
; template <class Epi, class Sched, bool ALIGN_EPI = false, bool SP2 = false>
; __device__ __forceinline__ void gemm_phase(PG8_LAS unsigned char* lds, const Gemm g, const Sched& S, const Epi& E) {
;     ...
;             const bool last = (t == nt - 2);
;             const char* a1 = cA + (size_t)(t + 1) * kstep;
;             const char* a2 = last ? nA : cA + (size_t)(t + 2) * kstep; const char* b2 = last ? nB : cB + (size_t)(t + 2) * kstep;
;             const char* a3 = a2 + kstep; const char* b3 = b2 + kstep;
;             if (last && has_next) S.a_ready(nxt);
;             if constexpr (SP2) {
;             PG8_LDB(B0, 0, 0); PG8_LDB(B1, 0, 1); PG8_SCHED; PG8_LDA(At, 0, 0); PG8_STAGE(PG8_SA(1, 1), a1 + hstep, voffA);
;             PG8_WAIT_V(8); PG8_WAIT_L(0); PG8_BAR; PG8_MMA(0, 0, At, B0); PG8_MMA(0, 1, At, B1); PG8_BAR; PG8_SCHED;
;             PG8_LDA(At, 0, 1); PG8_STAGE(PG8_SB(0, 0), b2, voffB); PG8_STAGE(PG8_SB(0, 1), b2 + hstep, voffB); PG8_STAGE(PG8_SA(0, 0), a2, voffA);
;             PG8_WAIT_V(8); PG8_WAIT_L(0); PG8_BAR; PG8_MMA(1, 0, At, B0); PG8_MMA(1, 1, At, B1); PG8_BAR; PG8_SCHED;
.LBB0_1175:
	s_add_u32 s8, s0, 0xfffc0080
	s_addc_u32 s9, s1, -1
	s_add_i32 s88, 0, 0x10000
	s_cmp_eq_u32 s37, 12
	s_cselect_b32 s11, s27, s9
	s_cselect_b32 s10, vcc_lo, s8
	s_cselect_b32 s9, s25, s5
	s_cselect_b32 s8, vcc_hi, s4
	s_add_i32 s60, 0, 0x14000
	v_add_u32_e32 v142, s88, v208
	v_add_u32_e32 v154, s60, v208
	ds_read_b128 v[130:133], v142
	ds_read_b128 v[134:137], v142 offset:1024
	ds_read_b128 v[138:141], v142 offset:2048
	ds_read_b128 v[142:145], v142 offset:3072
	ds_read_b128 v[146:149], v154
	ds_read_b128 v[150:153], v154 offset:1024
	ds_read_b128 v[186:189], v154 offset:2048
	ds_read_b128 v[190:193], v154 offset:3072
	v_lshl_add_u64 v[154:155], s[0:1], 0, v[182:183]
	s_add_i32 m0, s54, 0xc000
	ds_read_b128 v[194:197], v209
	ds_read_b128 v[198:201], v209 offset:1024
	ds_read_b128 v[202:205], v209 offset:2048
	ds_read_b128 v[210:213], v209 offset:3072
	ds_read_b128 v[214:217], v209 offset:4096
	ds_read_b128 v[218:221], v209 offset:5120
	ds_read_b128 v[222:225], v209 offset:6144
	ds_read_b128 v[226:229], v209 offset:7168
	global_load_lds_dwordx4 v[154:155], off
	v_lshl_add_u64 v[154:155], s[0:1], 0, v[184:185]
	s_add_i32 m0, s54, 0xe000
	s_nop 0
	global_load_lds_dwordx4 v[154:155], off
	s_waitcnt vmcnt(8)
	s_waitcnt lgkmcnt(0)
	s_barrier
	s_waitcnt lgkmcnt(0)
	v_mfma_f32_16x16x32_bf16 v[126:129], v[130:133], v[194:197], v[126:129]
	v_mfma_f32_16x16x32_bf16 v[122:125], v[138:141], v[194:197], v[122:125]
	v_mfma_f32_16x16x32_bf16 v[106:109], v[130:133], v[202:205], v[106:109]
	v_mfma_f32_16x16x32_bf16 v[78:81], v[138:141], v[202:205], v[78:81]
	v_mfma_f32_16x16x32_bf16 v[102:105], v[130:133], v[214:217], v[102:105]
	v_mfma_f32_16x16x32_bf16 v[74:77], v[138:141], v[214:217], v[74:77]
	v_mfma_f32_16x16x32_bf16 v[118:121], v[130:133], v[222:225], v[118:121]
	v_mfma_f32_16x16x32_bf16 v[110:113], v[138:141], v[222:225], v[110:113]
	v_mfma_f32_16x16x32_bf16 v[126:129], v[134:137], v[198:201], v[126:129]
	v_mfma_f32_16x16x32_bf16 v[122:125], v[142:145], v[198:201], v[122:125]
	v_mfma_f32_16x16x32_bf16 v[106:109], v[134:137], v[210:213], v[106:109]
	v_mfma_f32_16x16x32_bf16 v[78:81], v[142:145], v[210:213], v[78:81]
	v_mfma_f32_16x16x32_bf16 v[102:105], v[134:137], v[218:221], v[102:105]
	v_mfma_f32_16x16x32_bf16 v[74:77], v[142:145], v[218:221], v[74:77]
	v_mfma_f32_16x16x32_bf16 v[118:121], v[134:137], v[226:229], v[118:121]
	v_mfma_f32_16x16x32_bf16 v[110:113], v[142:145], v[226:229], v[110:113]
	v_mfma_f32_16x16x32_bf16 v[86:89], v[146:149], v[194:197], v[86:89]
	v_mfma_f32_16x16x32_bf16 v[58:61], v[186:189], v[194:197], v[58:61]
	v_mfma_f32_16x16x32_bf16 v[42:45], v[146:149], v[202:205], v[42:45]
	v_mfma_f32_16x16x32_bf16 v[18:21], v[186:189], v[202:205], v[18:21]
	v_mfma_f32_16x16x32_bf16 v[38:41], v[146:149], v[214:217], v[38:41]
	v_mfma_f32_16x16x32_bf16 v[14:17], v[186:189], v[214:217], v[14:17]
	v_mfma_f32_16x16x32_bf16 v[98:101], v[146:149], v[222:225], v[98:101]
	v_mfma_f32_16x16x32_bf16 v[70:73], v[186:189], v[222:225], v[70:73]
	v_mfma_f32_16x16x32_bf16 v[86:89], v[150:153], v[198:201], v[86:89]
	v_mfma_f32_16x16x32_bf16 v[58:61], v[190:193], v[198:201], v[58:61]
	v_mfma_f32_16x16x32_bf16 v[42:45], v[150:153], v[210:213], v[42:45]
	v_mfma_f32_16x16x32_bf16 v[18:21], v[190:193], v[210:213], v[18:21]
	v_mfma_f32_16x16x32_bf16 v[38:41], v[150:153], v[218:221], v[38:41]
	v_mfma_f32_16x16x32_bf16 v[14:17], v[190:193], v[218:221], v[14:17]
	v_mfma_f32_16x16x32_bf16 v[98:101], v[150:153], v[226:229], v[98:101]
	v_mfma_f32_16x16x32_bf16 v[70:73], v[190:193], v[226:229], v[70:73]
	s_barrier
	s_add_i32 s88, s88, s28
	v_lshl_add_u64 v[154:155], s[8:9], 0, v[0:1]
	s_mov_b32 m0, s88
	ds_read_b128 v[194:197], v209 offset:16384
	ds_read_b128 v[198:201], v209 offset:17408
	ds_read_b128 v[202:205], v209 offset:18432
	ds_read_b128 v[210:213], v209 offset:19456
	ds_read_b128 v[214:217], v209 offset:20480
	ds_read_b128 v[218:221], v209 offset:21504
	ds_read_b128 v[222:225], v209 offset:22528
	ds_read_b128 v[226:229], v209 offset:23552
	global_load_lds_dwordx4 v[154:155], off
	s_add_i32 m0, s88, 0x2000
	s_add_u32 s88, s8, 0x40000
	v_lshl_add_u64 v[162:163], s[8:9], 0, v[156:157]
	s_addc_u32 s89, s9, 0
	s_add_i32 s60, s60, s28
	global_load_lds_dwordx4 v[162:163], off
	v_lshl_add_u64 v[230:231], s[88:89], 0, v[0:1]
	s_mov_b32 m0, s60
	v_lshl_add_u64 v[234:235], s[10:11], 0, v[158:159]
	global_load_lds_dwordx4 v[230:231], off
	v_lshl_add_u64 v[230:231], s[88:89], 0, v[156:157]
	s_add_i32 m0, s60, 0x2000
	s_nop 0
	global_load_lds_dwordx4 v[230:231], off
	v_lshl_add_u64 v[230:231], s[10:11], 0, v[160:161]
	s_mov_b32 m0, s54
	s_nop 0
	global_load_lds_dwordx4 v[230:231], off
	s_mov_b32 m0, s55
	s_nop 0
	global_load_lds_dwordx4 v[234:235], off
	s_waitcnt vmcnt(8)
	s_waitcnt lgkmcnt(0)
	s_barrier
; #define PG8_STAGE(bufoff, gbase, voff) do { _Pragma("unroll") for (int _i = 0; _i < 2; ++_i) \
;         __builtin_amdgcn_global_load_lds((const unsigned*)((const char*)(gbase) + (voff)[_i]), (PG8_LAS unsigned*)(lds + (bufoff) + ldsw + _i * 8192), 16, 0, 0); } while (0)
; #define PG8_LDA(dst, b, h) do { _Pragma("unroll") for (int m = 0; m < 4; ++m) _Pragma("unroll") for (int k = 0; k < 2; ++k) dst[m][k] = *(const PG8_LAS bf16x8*)(lds + PG8_SA(b, h) + aoff + m * 2048 + k * 1024); } while (0)
; #define PG8_LDB(dst, b, h) do { _Pragma("unroll") for (int n = 0; n < 2; ++n) _Pragma("unroll") for (int k = 0; k < 2; ++k) dst[n][k] = *(const PG8_LAS bf16x8*)(lds + PG8_SB(b, h) + boff + n * 2048 + k * 1024); } while (0)
; #define PG8_MMA(ai, bj, At, Bt) do { __builtin_amdgcn_s_setprio(1); _Pragma("unroll") for (int m = 0; m < 4; ++m) _Pragma("unroll") for (int n = 0; n < 2; ++n) _Pragma("unroll") for (int k = 0; k < 2; ++k) \
;         acc[ai][bj][m][n] = mma16<Epi::F16A>(Bt[n][k], At[m][k], acc[ai][bj][m][n]); __builtin_amdgcn_s_setprio(0); } while (0)
; #define PG8_WAIT_V(n) asm volatile("s_waitcnt vmcnt(" #n ")" ::: "memory")
; #define PG8_WAIT_L(n) asm volatile("s_waitcnt lgkmcnt(" #n ")" ::: "memory")
; #define PG8_BAR __builtin_amdgcn_s_barrier()
; #define PG8_SCHED __builtin_amdgcn_sched_barrier(0)
; template <class Epi, class Sched, bool ALIGN_EPI = false, bool SP2 = false>
; __device__ __forceinline__ void gemm_phase(PG8_LAS unsigned char* lds, const Gemm g, const Sched& S, const Epi& E) {
;     ...
;             PG8_WAIT_V(8); PG8_WAIT_L(0); PG8_BAR; PG8_MMA(1, 0, At, B0); PG8_MMA(1, 1, At, B1); PG8_BAR; PG8_SCHED;
;             PG8_LDB(B0, 1, 0); PG8_LDB(B1, 1, 1); PG8_SCHED; PG8_LDA(At, 1, 0); PG8_STAGE(PG8_SA(0, 1), a2 + hstep, voffA);
;             PG8_WAIT_V(8); PG8_WAIT_L(0); PG8_BAR; PG8_MMA(0, 0, At, B0); PG8_MMA(0, 1, At, B1); PG8_BAR; PG8_SCHED;
	s_waitcnt lgkmcnt(0)
	v_mfma_f32_16x16x32_bf16 v[94:97], v[130:133], v[194:197], v[94:97]
	v_mfma_f32_16x16x32_bf16 v[66:69], v[138:141], v[194:197], v[66:69]
	v_mfma_f32_16x16x32_bf16 v[90:93], v[130:133], v[202:205], v[90:93]
	v_mfma_f32_16x16x32_bf16 v[62:65], v[138:141], v[202:205], v[62:65]
	v_mfma_f32_16x16x32_bf16 v[46:49], v[130:133], v[214:217], v[46:49]
	v_mfma_f32_16x16x32_bf16 v[54:57], v[138:141], v[214:217], v[54:57]
	v_mfma_f32_16x16x32_bf16 v[114:117], v[130:133], v[222:225], v[114:117]
	v_mfma_f32_16x16x32_bf16 v[82:85], v[138:141], v[222:225], v[82:85]
	v_mfma_f32_16x16x32_bf16 v[94:97], v[134:137], v[198:201], v[94:97]
	v_mfma_f32_16x16x32_bf16 v[66:69], v[142:145], v[198:201], v[66:69]
	v_mfma_f32_16x16x32_bf16 v[90:93], v[134:137], v[210:213], v[90:93]
	v_mfma_f32_16x16x32_bf16 v[62:65], v[142:145], v[210:213], v[62:65]
	v_mfma_f32_16x16x32_bf16 v[46:49], v[134:137], v[218:221], v[46:49]
	v_mfma_f32_16x16x32_bf16 v[54:57], v[142:145], v[218:221], v[54:57]
	v_mfma_f32_16x16x32_bf16 v[114:117], v[134:137], v[226:229], v[114:117]
	v_mfma_f32_16x16x32_bf16 v[82:85], v[142:145], v[226:229], v[82:85]
	v_mfma_f32_16x16x32_bf16 v[34:37], v[146:149], v[194:197], v[34:37]
	v_mfma_f32_16x16x32_bf16 v[10:13], v[186:189], v[194:197], v[10:13]
	v_mfma_f32_16x16x32_bf16 v[26:29], v[146:149], v[202:205], v[26:29]
	v_mfma_f32_16x16x32_bf16 v[6:9], v[186:189], v[202:205], v[6:9]
	v_mfma_f32_16x16x32_bf16 v[22:25], v[146:149], v[214:217], v[22:25]
	v_mfma_f32_16x16x32_bf16 v[2:5], v[186:189], v[214:217], v[2:5]
	v_mfma_f32_16x16x32_bf16 v[50:53], v[146:149], v[222:225], v[50:53]
	v_mfma_f32_16x16x32_bf16 v[30:33], v[186:189], v[222:225], v[30:33]
	v_mfma_f32_16x16x32_bf16 v[34:37], v[150:153], v[198:201], v[34:37]
	v_mfma_f32_16x16x32_bf16 v[10:13], v[190:193], v[198:201], v[10:13]
	v_mfma_f32_16x16x32_bf16 v[26:29], v[150:153], v[210:213], v[26:29]
	v_mfma_f32_16x16x32_bf16 v[6:9], v[190:193], v[210:213], v[6:9]
	v_mfma_f32_16x16x32_bf16 v[22:25], v[150:153], v[218:221], v[22:25]
	v_mfma_f32_16x16x32_bf16 v[2:5], v[190:193], v[218:221], v[2:5]
	v_mfma_f32_16x16x32_bf16 v[50:53], v[150:153], v[226:229], v[50:53]
	v_mfma_f32_16x16x32_bf16 v[30:33], v[190:193], v[226:229], v[30:33]
	s_barrier
	s_add_i32 s60, 0, 0x18000
	s_add_i32 s88, 0, 0x1c000
	v_add_u32_e32 v142, s60, v208
	v_add_u32_e32 v190, s88, v208
	ds_read_b128 v[130:133], v142
	ds_read_b128 v[134:137], v142 offset:1024
	ds_read_b128 v[138:141], v142 offset:2048
	ds_read_b128 v[142:145], v142 offset:3072
	ds_read_b128 v[146:149], v190
	ds_read_b128 v[150:153], v190 offset:1024
	ds_read_b128 v[186:189], v190 offset:2048
	ds_read_b128 v[190:193], v190 offset:3072
	s_add_u32 s10, s10, 0x40000
	s_addc_u32 s11, s11, 0
	s_mov_b32 m0, s57
	v_lshl_add_u64 v[236:237], s[10:11], 0, v[160:161]
	ds_read_b128 v[194:197], v209 offset:32768
	ds_read_b128 v[198:201], v209 offset:33792
	ds_read_b128 v[202:205], v209 offset:34816
	ds_read_b128 v[210:213], v209 offset:35840
	ds_read_b128 v[214:217], v209 offset:36864
	ds_read_b128 v[218:221], v209 offset:37888
	ds_read_b128 v[222:225], v209 offset:38912
	ds_read_b128 v[226:229], v209 offset:39936
	global_load_lds_dwordx4 v[236:237], off
	v_lshl_add_u64 v[236:237], s[10:11], 0, v[158:159]
	s_mov_b32 m0, s59
	s_nop 0
	global_load_lds_dwordx4 v[236:237], off
	s_waitcnt vmcnt(8)
	s_waitcnt lgkmcnt(0)
	s_barrier
	s_waitcnt lgkmcnt(0)
	v_mfma_f32_16x16x32_bf16 v[126:129], v[130:133], v[194:197], v[126:129]
	v_mfma_f32_16x16x32_bf16 v[122:125], v[138:141], v[194:197], v[122:125]
	v_mfma_f32_16x16x32_bf16 v[106:109], v[130:133], v[202:205], v[106:109]
	v_mfma_f32_16x16x32_bf16 v[78:81], v[138:141], v[202:205], v[78:81]
	v_mfma_f32_16x16x32_bf16 v[102:105], v[130:133], v[214:217], v[102:105]
	v_mfma_f32_16x16x32_bf16 v[74:77], v[138:141], v[214:217], v[74:77]
	v_mfma_f32_16x16x32_bf16 v[118:121], v[130:133], v[222:225], v[118:121]
	v_mfma_f32_16x16x32_bf16 v[110:113], v[138:141], v[222:225], v[110:113]
	v_mfma_f32_16x16x32_bf16 v[126:129], v[134:137], v[198:201], v[126:129]
	v_mfma_f32_16x16x32_bf16 v[122:125], v[142:145], v[198:201], v[122:125]
	v_mfma_f32_16x16x32_bf16 v[106:109], v[134:137], v[210:213], v[106:109]
	v_mfma_f32_16x16x32_bf16 v[78:81], v[142:145], v[210:213], v[78:81]
	v_mfma_f32_16x16x32_bf16 v[102:105], v[134:137], v[218:221], v[102:105]
	v_mfma_f32_16x16x32_bf16 v[74:77], v[142:145], v[218:221], v[74:77]
	v_mfma_f32_16x16x32_bf16 v[118:121], v[134:137], v[226:229], v[118:121]
	v_mfma_f32_16x16x32_bf16 v[110:113], v[142:145], v[226:229], v[110:113]
	v_mfma_f32_16x16x32_bf16 v[86:89], v[146:149], v[194:197], v[86:89]
	v_mfma_f32_16x16x32_bf16 v[58:61], v[186:189], v[194:197], v[58:61]
	v_mfma_f32_16x16x32_bf16 v[42:45], v[146:149], v[202:205], v[42:45]
	v_mfma_f32_16x16x32_bf16 v[18:21], v[186:189], v[202:205], v[18:21]
	v_mfma_f32_16x16x32_bf16 v[38:41], v[146:149], v[214:217], v[38:41]
	v_mfma_f32_16x16x32_bf16 v[14:17], v[186:189], v[214:217], v[14:17]
	v_mfma_f32_16x16x32_bf16 v[98:101], v[146:149], v[222:225], v[98:101]
	v_mfma_f32_16x16x32_bf16 v[70:73], v[186:189], v[222:225], v[70:73]
	v_mfma_f32_16x16x32_bf16 v[86:89], v[150:153], v[198:201], v[86:89]
	v_mfma_f32_16x16x32_bf16 v[58:61], v[190:193], v[198:201], v[58:61]
	v_mfma_f32_16x16x32_bf16 v[42:45], v[150:153], v[210:213], v[42:45]
	v_mfma_f32_16x16x32_bf16 v[18:21], v[190:193], v[210:213], v[18:21]
	v_mfma_f32_16x16x32_bf16 v[38:41], v[150:153], v[218:221], v[38:41]
	v_mfma_f32_16x16x32_bf16 v[14:17], v[190:193], v[218:221], v[14:17]
	v_mfma_f32_16x16x32_bf16 v[98:101], v[150:153], v[226:229], v[98:101]
	v_mfma_f32_16x16x32_bf16 v[70:73], v[190:193], v[226:229], v[70:73]
	s_barrier
; #define PG8_STAGE(bufoff, gbase, voff) do { _Pragma("unroll") for (int _i = 0; _i < 2; ++_i) \
;         __builtin_amdgcn_global_load_lds((const unsigned*)((const char*)(gbase) + (voff)[_i]), (PG8_LAS unsigned*)(lds + (bufoff) + ldsw + _i * 8192), 16, 0, 0); } while (0)
; #define PG8_LDA(dst, b, h) do { _Pragma("unroll") for (int m = 0; m < 4; ++m) _Pragma("unroll") for (int k = 0; k < 2; ++k) dst[m][k] = *(const PG8_LAS bf16x8*)(lds + PG8_SA(b, h) + aoff + m * 2048 + k * 1024); } while (0)
; #define PG8_MMA(ai, bj, At, Bt) do { __builtin_amdgcn_s_setprio(1); _Pragma("unroll") for (int m = 0; m < 4; ++m) _Pragma("unroll") for (int n = 0; n < 2; ++n) _Pragma("unroll") for (int k = 0; k < 2; ++k) \
;         acc[ai][bj][m][n] = mma16<Epi::F16A>(Bt[n][k], At[m][k], acc[ai][bj][m][n]); __builtin_amdgcn_s_setprio(0); } while (0)
; #define PG8_WAIT_V(n) asm volatile("s_waitcnt vmcnt(" #n ")" ::: "memory")
; #define PG8_WAIT_L(n) asm volatile("s_waitcnt lgkmcnt(" #n ")" ::: "memory")
; #define PG8_BAR __builtin_amdgcn_s_barrier()
; #define PG8_SCHED __builtin_amdgcn_sched_barrier(0)
; template <class Epi, class Sched, bool ALIGN_EPI = false, bool SP2 = false>
; __device__ __forceinline__ void gemm_phase(PG8_LAS unsigned char* lds, const Gemm g, const Sched& S, const Epi& E) {
;     ...
;         for (int t = 0; t < nt; t += 2) {
;             const bool last = (t == nt - 2);
;     ...
;             PG8_LDA(At, 1, 1); PG8_STAGE(PG8_SB(1, 0), b3, voffB); PG8_STAGE(PG8_SB(1, 1), b3 + hstep, voffB); PG8_STAGE(PG8_SA(1, 0), a3, voffA);
;             PG8_WAIT_V(8); PG8_WAIT_L(0); PG8_BAR; PG8_MMA(1, 0, At, B0); PG8_MMA(1, 1, At, B1); PG8_BAR; PG8_SCHED;
	s_add_i32 s10, s60, s28
	v_lshl_add_u64 v[154:155], v[154:155], 0, s[92:93]
	s_mov_b32 m0, s10
	ds_read_b128 v[194:197], v209 offset:49152
	ds_read_b128 v[198:201], v209 offset:50176
	ds_read_b128 v[202:205], v209 offset:51200
	ds_read_b128 v[210:213], v209 offset:52224
	ds_read_b128 v[214:217], v209 offset:53248
	ds_read_b128 v[218:221], v209 offset:54272
	ds_read_b128 v[222:225], v209 offset:55296
	ds_read_b128 v[226:229], v209 offset:56320
	global_load_lds_dwordx4 v[154:155], off
	s_add_i32 m0, s10, 0x2000
	s_add_u32 s8, s8, 0x40080
	v_lshl_add_u64 v[154:155], v[162:163], 0, s[92:93]
	s_addc_u32 s9, s9, 0
	s_add_i32 s10, s88, s28
	global_load_lds_dwordx4 v[154:155], off
	v_lshl_add_u64 v[154:155], s[8:9], 0, v[0:1]
	s_mov_b32 m0, s10
	s_nop 0
	global_load_lds_dwordx4 v[154:155], off
	v_lshl_add_u64 v[154:155], s[8:9], 0, v[156:157]
	s_add_i32 m0, s10, 0x2000
	s_nop 0
	global_load_lds_dwordx4 v[154:155], off
	v_lshl_add_u64 v[154:155], v[230:231], 0, s[92:93]
	s_mov_b32 m0, s70
	s_nop 0
	global_load_lds_dwordx4 v[154:155], off
	v_lshl_add_u64 v[154:155], v[234:235], 0, s[92:93]
	s_mov_b32 m0, s71
	s_nop 0
	global_load_lds_dwordx4 v[154:155], off
	s_waitcnt vmcnt(8)
	s_waitcnt lgkmcnt(0)
	s_barrier
	s_waitcnt lgkmcnt(0)
	v_mfma_f32_16x16x32_bf16 v[94:97], v[130:133], v[194:197], v[94:97]
	v_mfma_f32_16x16x32_bf16 v[66:69], v[138:141], v[194:197], v[66:69]
	v_mfma_f32_16x16x32_bf16 v[90:93], v[130:133], v[202:205], v[90:93]
	v_mfma_f32_16x16x32_bf16 v[62:65], v[138:141], v[202:205], v[62:65]
	v_mfma_f32_16x16x32_bf16 v[46:49], v[130:133], v[214:217], v[46:49]
	v_mfma_f32_16x16x32_bf16 v[54:57], v[138:141], v[214:217], v[54:57]
	v_mfma_f32_16x16x32_bf16 v[114:117], v[130:133], v[222:225], v[114:117]
	v_mfma_f32_16x16x32_bf16 v[82:85], v[138:141], v[222:225], v[82:85]
	v_mfma_f32_16x16x32_bf16 v[94:97], v[134:137], v[198:201], v[94:97]
	v_mfma_f32_16x16x32_bf16 v[66:69], v[142:145], v[198:201], v[66:69]
	v_mfma_f32_16x16x32_bf16 v[90:93], v[134:137], v[210:213], v[90:93]
	v_mfma_f32_16x16x32_bf16 v[62:65], v[142:145], v[210:213], v[62:65]
	v_mfma_f32_16x16x32_bf16 v[46:49], v[134:137], v[218:221], v[46:49]
	v_mfma_f32_16x16x32_bf16 v[54:57], v[142:145], v[218:221], v[54:57]
	v_mfma_f32_16x16x32_bf16 v[114:117], v[134:137], v[226:229], v[114:117]
	v_mfma_f32_16x16x32_bf16 v[82:85], v[142:145], v[226:229], v[82:85]
	v_mfma_f32_16x16x32_bf16 v[34:37], v[146:149], v[194:197], v[34:37]
	v_mfma_f32_16x16x32_bf16 v[10:13], v[186:189], v[194:197], v[10:13]
	v_mfma_f32_16x16x32_bf16 v[26:29], v[146:149], v[202:205], v[26:29]
	v_mfma_f32_16x16x32_bf16 v[6:9], v[186:189], v[202:205], v[6:9]
	v_mfma_f32_16x16x32_bf16 v[22:25], v[146:149], v[214:217], v[22:25]
	v_mfma_f32_16x16x32_bf16 v[2:5], v[186:189], v[214:217], v[2:5]
	v_mfma_f32_16x16x32_bf16 v[50:53], v[146:149], v[222:225], v[50:53]
	v_mfma_f32_16x16x32_bf16 v[30:33], v[186:189], v[222:225], v[30:33]
	v_mfma_f32_16x16x32_bf16 v[34:37], v[150:153], v[198:201], v[34:37]
	v_mfma_f32_16x16x32_bf16 v[10:13], v[190:193], v[198:201], v[10:13]
	v_mfma_f32_16x16x32_bf16 v[26:29], v[150:153], v[210:213], v[26:29]
	v_mfma_f32_16x16x32_bf16 v[6:9], v[190:193], v[210:213], v[6:9]
	v_mfma_f32_16x16x32_bf16 v[22:25], v[150:153], v[218:221], v[22:25]
	v_mfma_f32_16x16x32_bf16 v[2:5], v[190:193], v[218:221], v[2:5]
	v_mfma_f32_16x16x32_bf16 v[50:53], v[150:153], v[226:229], v[50:53]
	v_mfma_f32_16x16x32_bf16 v[30:33], v[190:193], v[226:229], v[30:33]
	s_barrier
	s_add_i32 s37, s37, 2
	s_add_u32 s0, s0, 0x100
	s_addc_u32 s1, s1, 0
	s_add_u32 s4, s4, 0x100
	s_addc_u32 s5, s5, 0
	s_cmp_gt_u32 s37, 13
	s_cbranch_scc0 .LBB0_1175
	s_and_b64 vcc, exec, s[50:51]
	s_cbranch_vccz .LBB0_1178
	s_barrier

; #define PG8_STAGE(bufoff, gbase, voff) do { _Pragma("unroll") for (int _i = 0; _i < 2; ++_i) \
;         __builtin_amdgcn_global_load_lds((const unsigned*)((const char*)(gbase) + (voff)[_i]), (PG8_LAS unsigned*)(lds + (bufoff) + ldsw + _i * 8192), 16, 0, 0); } while (0)
; #define PG8_LDA(dst, b, h) do { _Pragma("unroll") for (int m = 0; m < 4; ++m) _Pragma("unroll") for (int k = 0; k < 2; ++k) dst[m][k] = *(const PG8_LAS bf16x8*)(lds + PG8_SA(b, h) + aoff + m * 2048 + k * 1024); } while (0)
; #define PG8_LDB(dst, b, h) do { _Pragma("unroll") for (int n = 0; n < 2; ++n) _Pragma("unroll") for (int k = 0; k < 2; ++k) dst[n][k] = *(const PG8_LAS bf16x8*)(lds + PG8_SB(b, h) + boff + n * 2048 + k * 1024); } while (0)
; #define PG8_MMA(ai, bj, At, Bt) do { __builtin_amdgcn_s_setprio(1); _Pragma("unroll") for (int m = 0; m < 4; ++m) _Pragma("unroll") for (int n = 0; n < 2; ++n) _Pragma("unroll") for (int k = 0; k < 2; ++k) \
;         acc[ai][bj][m][n] = mma16<Epi::F16A>(Bt[n][k], At[m][k], acc[ai][bj][m][n]); __builtin_amdgcn_s_setprio(0); } while (0)
; #define PG8_WAIT_V(n) asm volatile("s_waitcnt vmcnt(" #n ")" ::: "memory")
; #define PG8_WAIT_L(n) asm volatile("s_waitcnt lgkmcnt(" #n ")" ::: "memory")
; #define PG8_BAR __builtin_amdgcn_s_barrier()
; template <class Epi, class Sched, bool ALIGN_EPI = false, bool SP2 = false>
; __device__ __forceinline__ void gemm_phase(PG8_LAS unsigned char* lds, const Gemm g, const Sched& S, const Epi& E) {
;     ...
;             const bool last = (t == nt - 2);
;             const char* a1 = cA + (size_t)(t + 1) * kstep;
;             const char* a2 = last ? nA : cA + (size_t)(t + 2) * kstep; const char* b2 = last ? nB : cB + (size_t)(t + 2) * kstep;
;             const char* a3 = a2 + kstep; const char* b3 = b2 + kstep;
;             if (last && has_next) S.a_ready(nxt);
;             if constexpr (SP2) {
;             PG8_LDB(B0, 0, 0); PG8_LDB(B1, 0, 1); PG8_SCHED; PG8_LDA(At, 0, 0); PG8_STAGE(PG8_SA(1, 1), a1 + hstep, voffA);
;             PG8_WAIT_V(8); PG8_WAIT_L(0); PG8_BAR; PG8_MMA(0, 0, At, B0); PG8_MMA(0, 1, At, B1); PG8_BAR; PG8_SCHED;
;             PG8_LDA(At, 0, 1); PG8_STAGE(PG8_SB(0, 0), b2, voffB); PG8_STAGE(PG8_SB(0, 1), b2 + hstep, voffB); PG8_STAGE(PG8_SA(0, 0), a2, voffA);
;             PG8_WAIT_V(8); PG8_WAIT_L(0); PG8_BAR; PG8_MMA(1, 0, At, B0); PG8_MMA(1, 1, At, B1); PG8_BAR; PG8_SCHED;
.LBB0_1298:
	s_add_u32 s26, s24, 0x100
	s_addc_u32 s27, s25, 0
	s_add_i32 s55, 0, 0x10000
	s_cmp_eq_u32 s37, 40
	s_cselect_b32 s41, s1, s27
	s_cselect_b32 s40, s0, s26
	v_add_u32_e32 v146, s55, v150
	s_cselect_b32 s39, s23, s5
	s_cselect_b32 s38, s22, s4
	s_add_i32 s57, 0, 0x14000
	ds_read_b128 v[142:145], v146
	ds_read_b128 v[152:155], v146 offset:1024
	ds_read_b128 v[156:159], v146 offset:2048
	ds_read_b128 v[160:163], v146 offset:3072
	v_add_u32_e32 v146, s57, v150
	ds_read_b128 v[182:185], v146
	ds_read_b128 v[186:189], v146 offset:1024
	ds_read_b128 v[190:193], v146 offset:2048
	ds_read_b128 v[194:197], v146 offset:3072
	v_lshl_add_u64 v[146:147], s[24:25], 0, v[138:139]
	s_add_i32 m0, s15, 0xc000
	ds_read_b128 v[198:201], v151
	ds_read_b128 v[202:205], v151 offset:1024
	ds_read_b128 v[206:209], v151 offset:2048
	ds_read_b128 v[210:213], v151 offset:3072
	ds_read_b128 v[214:217], v151 offset:4096
	ds_read_b128 v[218:221], v151 offset:5120
	ds_read_b128 v[222:225], v151 offset:6144
	ds_read_b128 v[226:229], v151 offset:7168
	global_load_lds_dwordx4 v[146:147], off
	v_lshl_add_u64 v[146:147], s[24:25], 0, v[140:141]
	s_add_i32 m0, s15, 0xe000
	s_nop 0
	global_load_lds_dwordx4 v[146:147], off
	s_waitcnt vmcnt(8)
	s_waitcnt lgkmcnt(0)
	s_barrier
	s_waitcnt lgkmcnt(0)
	v_mfma_f32_16x16x32_bf16 v[126:129], v[142:145], v[198:201], v[126:129]
	v_mfma_f32_16x16x32_bf16 v[122:125], v[156:159], v[198:201], v[122:125]
	v_mfma_f32_16x16x32_bf16 v[110:113], v[142:145], v[206:209], v[110:113]
	v_mfma_f32_16x16x32_bf16 v[106:109], v[156:159], v[206:209], v[106:109]
	v_mfma_f32_16x16x32_bf16 v[94:97], v[142:145], v[214:217], v[94:97]
	v_mfma_f32_16x16x32_bf16 v[90:93], v[156:159], v[214:217], v[90:93]
	v_mfma_f32_16x16x32_bf16 v[78:81], v[142:145], v[222:225], v[78:81]
	v_mfma_f32_16x16x32_bf16 v[74:77], v[156:159], v[222:225], v[74:77]
	v_mfma_f32_16x16x32_bf16 v[126:129], v[152:155], v[202:205], v[126:129]
	v_mfma_f32_16x16x32_bf16 v[122:125], v[160:163], v[202:205], v[122:125]
	v_mfma_f32_16x16x32_bf16 v[110:113], v[152:155], v[210:213], v[110:113]
	v_mfma_f32_16x16x32_bf16 v[106:109], v[160:163], v[210:213], v[106:109]
	v_mfma_f32_16x16x32_bf16 v[94:97], v[152:155], v[218:221], v[94:97]
	v_mfma_f32_16x16x32_bf16 v[90:93], v[160:163], v[218:221], v[90:93]
	v_mfma_f32_16x16x32_bf16 v[78:81], v[152:155], v[226:229], v[78:81]
	v_mfma_f32_16x16x32_bf16 v[74:77], v[160:163], v[226:229], v[74:77]
	v_mfma_f32_16x16x32_bf16 v[118:121], v[182:185], v[198:201], v[118:121]
	v_mfma_f32_16x16x32_bf16 v[114:117], v[190:193], v[198:201], v[114:117]
	v_mfma_f32_16x16x32_bf16 v[102:105], v[182:185], v[206:209], v[102:105]
	v_mfma_f32_16x16x32_bf16 v[98:101], v[190:193], v[206:209], v[98:101]
	v_mfma_f32_16x16x32_bf16 v[86:89], v[182:185], v[214:217], v[86:89]
	v_mfma_f32_16x16x32_bf16 v[82:85], v[190:193], v[214:217], v[82:85]
	v_mfma_f32_16x16x32_bf16 v[70:73], v[182:185], v[222:225], v[70:73]
	v_mfma_f32_16x16x32_bf16 v[66:69], v[190:193], v[222:225], v[66:69]
	v_mfma_f32_16x16x32_bf16 v[118:121], v[186:189], v[202:205], v[118:121]
	v_mfma_f32_16x16x32_bf16 v[114:117], v[194:197], v[202:205], v[114:117]
	v_mfma_f32_16x16x32_bf16 v[102:105], v[186:189], v[210:213], v[102:105]
	v_mfma_f32_16x16x32_bf16 v[98:101], v[194:197], v[210:213], v[98:101]
	v_mfma_f32_16x16x32_bf16 v[86:89], v[186:189], v[218:221], v[86:89]
	v_mfma_f32_16x16x32_bf16 v[82:85], v[194:197], v[218:221], v[82:85]
	v_mfma_f32_16x16x32_bf16 v[70:73], v[186:189], v[226:229], v[70:73]
	v_mfma_f32_16x16x32_bf16 v[66:69], v[194:197], v[226:229], v[66:69]
	s_barrier
	s_add_i32 s24, s55, s14
	v_lshl_add_u64 v[146:147], s[38:39], 0, v[0:1]
	s_mov_b32 m0, s24
	ds_read_b128 v[198:201], v151 offset:16384
	ds_read_b128 v[202:205], v151 offset:17408
	ds_read_b128 v[206:209], v151 offset:18432
	ds_read_b128 v[210:213], v151 offset:19456
	ds_read_b128 v[214:217], v151 offset:20480
	ds_read_b128 v[218:221], v151 offset:21504
	ds_read_b128 v[222:225], v151 offset:22528
	ds_read_b128 v[226:229], v151 offset:23552
	global_load_lds_dwordx4 v[146:147], off
	s_add_i32 m0, s24, 0x2000
	s_add_u32 s24, s38, 0xb0000
	v_lshl_add_u64 v[230:231], s[38:39], 0, v[132:133]
	s_addc_u32 s25, s39, 0
	s_add_i32 s55, s57, s14
	global_load_lds_dwordx4 v[230:231], off
	v_lshl_add_u64 v[234:235], s[24:25], 0, v[0:1]
	s_mov_b32 m0, s55
	v_lshl_add_u64 v[236:237], s[40:41], 0, v[134:135]
	global_load_lds_dwordx4 v[234:235], off
	v_lshl_add_u64 v[234:235], s[24:25], 0, v[132:133]
	s_add_i32 m0, s55, 0x2000
	s_nop 0
	global_load_lds_dwordx4 v[234:235], off
	v_lshl_add_u64 v[234:235], s[40:41], 0, v[136:137]
	s_mov_b32 m0, s15
	s_nop 0
	global_load_lds_dwordx4 v[234:235], off
	s_mov_b32 m0, s28
	s_nop 0
	global_load_lds_dwordx4 v[236:237], off
	s_waitcnt vmcnt(8)
	s_waitcnt lgkmcnt(0)
	s_barrier
; #define PG8_STAGE(bufoff, gbase, voff) do { _Pragma("unroll") for (int _i = 0; _i < 2; ++_i) \
;         __builtin_amdgcn_global_load_lds((const unsigned*)((const char*)(gbase) + (voff)[_i]), (PG8_LAS unsigned*)(lds + (bufoff) + ldsw + _i * 8192), 16, 0, 0); } while (0)
; #define PG8_LDA(dst, b, h) do { _Pragma("unroll") for (int m = 0; m < 4; ++m) _Pragma("unroll") for (int k = 0; k < 2; ++k) dst[m][k] = *(const PG8_LAS bf16x8*)(lds + PG8_SA(b, h) + aoff + m * 2048 + k * 1024); } while (0)
; #define PG8_LDB(dst, b, h) do { _Pragma("unroll") for (int n = 0; n < 2; ++n) _Pragma("unroll") for (int k = 0; k < 2; ++k) dst[n][k] = *(const PG8_LAS bf16x8*)(lds + PG8_SB(b, h) + boff + n * 2048 + k * 1024); } while (0)
; #define PG8_MMA(ai, bj, At, Bt) do { __builtin_amdgcn_s_setprio(1); _Pragma("unroll") for (int m = 0; m < 4; ++m) _Pragma("unroll") for (int n = 0; n < 2; ++n) _Pragma("unroll") for (int k = 0; k < 2; ++k) \
;         acc[ai][bj][m][n] = mma16<Epi::F16A>(Bt[n][k], At[m][k], acc[ai][bj][m][n]); __builtin_amdgcn_s_setprio(0); } while (0)
; #define PG8_WAIT_V(n) asm volatile("s_waitcnt vmcnt(" #n ")" ::: "memory")
; #define PG8_WAIT_L(n) asm volatile("s_waitcnt lgkmcnt(" #n ")" ::: "memory")
; #define PG8_BAR __builtin_amdgcn_s_barrier()
; #define PG8_SCHED __builtin_amdgcn_sched_barrier(0)
; template <class Epi, class Sched, bool ALIGN_EPI = false, bool SP2 = false>
; __device__ __forceinline__ void gemm_phase(PG8_LAS unsigned char* lds, const Gemm g, const Sched& S, const Epi& E) {
;     ...
;             PG8_WAIT_V(8); PG8_WAIT_L(0); PG8_BAR; PG8_MMA(1, 0, At, B0); PG8_MMA(1, 1, At, B1); PG8_BAR; PG8_SCHED;
;             PG8_LDB(B0, 1, 0); PG8_LDB(B1, 1, 1); PG8_SCHED; PG8_LDA(At, 1, 0); PG8_STAGE(PG8_SA(0, 1), a2 + hstep, voffA);
;             PG8_WAIT_V(8); PG8_WAIT_L(0); PG8_BAR; PG8_MMA(0, 0, At, B0); PG8_MMA(0, 1, At, B1); PG8_BAR; PG8_SCHED;
	s_waitcnt lgkmcnt(0)
	v_mfma_f32_16x16x32_bf16 v[62:65], v[142:145], v[198:201], v[62:65]
	v_mfma_f32_16x16x32_bf16 v[58:61], v[156:159], v[198:201], v[58:61]
	v_mfma_f32_16x16x32_bf16 v[46:49], v[142:145], v[206:209], v[46:49]
	v_mfma_f32_16x16x32_bf16 v[42:45], v[156:159], v[206:209], v[42:45]
	v_mfma_f32_16x16x32_bf16 v[30:33], v[142:145], v[214:217], v[30:33]
	v_mfma_f32_16x16x32_bf16 v[26:29], v[156:159], v[214:217], v[26:29]
	v_mfma_f32_16x16x32_bf16 v[14:17], v[142:145], v[222:225], v[14:17]
	v_mfma_f32_16x16x32_bf16 v[10:13], v[156:159], v[222:225], v[10:13]
	v_mfma_f32_16x16x32_bf16 v[62:65], v[152:155], v[202:205], v[62:65]
	v_mfma_f32_16x16x32_bf16 v[58:61], v[160:163], v[202:205], v[58:61]
	v_mfma_f32_16x16x32_bf16 v[46:49], v[152:155], v[210:213], v[46:49]
	v_mfma_f32_16x16x32_bf16 v[42:45], v[160:163], v[210:213], v[42:45]
	v_mfma_f32_16x16x32_bf16 v[30:33], v[152:155], v[218:221], v[30:33]
	v_mfma_f32_16x16x32_bf16 v[26:29], v[160:163], v[218:221], v[26:29]
	v_mfma_f32_16x16x32_bf16 v[14:17], v[152:155], v[226:229], v[14:17]
	v_mfma_f32_16x16x32_bf16 v[10:13], v[160:163], v[226:229], v[10:13]
	v_mfma_f32_16x16x32_bf16 v[54:57], v[182:185], v[198:201], v[54:57]
	v_mfma_f32_16x16x32_bf16 v[50:53], v[190:193], v[198:201], v[50:53]
	v_mfma_f32_16x16x32_bf16 v[38:41], v[182:185], v[206:209], v[38:41]
	v_mfma_f32_16x16x32_bf16 v[34:37], v[190:193], v[206:209], v[34:37]
	v_mfma_f32_16x16x32_bf16 v[22:25], v[182:185], v[214:217], v[22:25]
	v_mfma_f32_16x16x32_bf16 v[18:21], v[190:193], v[214:217], v[18:21]
	v_mfma_f32_16x16x32_bf16 v[6:9], v[182:185], v[222:225], v[6:9]
	v_mfma_f32_16x16x32_bf16 v[2:5], v[190:193], v[222:225], v[2:5]
	v_mfma_f32_16x16x32_bf16 v[54:57], v[186:189], v[202:205], v[54:57]
	v_mfma_f32_16x16x32_bf16 v[50:53], v[194:197], v[202:205], v[50:53]
	v_mfma_f32_16x16x32_bf16 v[38:41], v[186:189], v[210:213], v[38:41]
	v_mfma_f32_16x16x32_bf16 v[34:37], v[194:197], v[210:213], v[34:37]
	v_mfma_f32_16x16x32_bf16 v[22:25], v[186:189], v[218:221], v[22:25]
	v_mfma_f32_16x16x32_bf16 v[18:21], v[194:197], v[218:221], v[18:21]
	v_mfma_f32_16x16x32_bf16 v[6:9], v[186:189], v[226:229], v[6:9]
	v_mfma_f32_16x16x32_bf16 v[2:5], v[194:197], v[226:229], v[2:5]
	s_barrier
	s_add_i32 s55, 0, 0x18000
	s_add_i32 s57, 0, 0x1c000
	v_add_u32_e32 v160, s55, v150
	v_add_u32_e32 v194, s57, v150
	ds_read_b128 v[142:145], v160
	ds_read_b128 v[152:155], v160 offset:1024
	ds_read_b128 v[156:159], v160 offset:2048
	ds_read_b128 v[160:163], v160 offset:3072
	ds_read_b128 v[182:185], v194
	ds_read_b128 v[186:189], v194 offset:1024
	ds_read_b128 v[190:193], v194 offset:2048
	ds_read_b128 v[194:197], v194 offset:3072
	s_add_u32 s24, s40, 0xb0000
	s_addc_u32 s25, s41, 0
	s_mov_b32 m0, s30
	v_lshl_add_u64 v[240:241], s[24:25], 0, v[136:137]
	ds_read_b128 v[198:201], v151 offset:32768
	ds_read_b128 v[202:205], v151 offset:33792
	ds_read_b128 v[206:209], v151 offset:34816
	ds_read_b128 v[210:213], v151 offset:35840
	ds_read_b128 v[214:217], v151 offset:36864
	ds_read_b128 v[218:221], v151 offset:37888
	ds_read_b128 v[222:225], v151 offset:38912
	ds_read_b128 v[226:229], v151 offset:39936
	global_load_lds_dwordx4 v[240:241], off
	v_lshl_add_u64 v[240:241], s[24:25], 0, v[134:135]
	s_mov_b32 m0, s31
	s_nop 0
	global_load_lds_dwordx4 v[240:241], off
	s_waitcnt vmcnt(8)
	s_waitcnt lgkmcnt(0)
	s_barrier
	s_waitcnt lgkmcnt(0)
	v_mfma_f32_16x16x32_bf16 v[126:129], v[142:145], v[198:201], v[126:129]
	v_mfma_f32_16x16x32_bf16 v[122:125], v[156:159], v[198:201], v[122:125]
	v_mfma_f32_16x16x32_bf16 v[110:113], v[142:145], v[206:209], v[110:113]
	v_mfma_f32_16x16x32_bf16 v[106:109], v[156:159], v[206:209], v[106:109]
	v_mfma_f32_16x16x32_bf16 v[94:97], v[142:145], v[214:217], v[94:97]
	v_mfma_f32_16x16x32_bf16 v[90:93], v[156:159], v[214:217], v[90:93]
	v_mfma_f32_16x16x32_bf16 v[78:81], v[142:145], v[222:225], v[78:81]
	v_mfma_f32_16x16x32_bf16 v[74:77], v[156:159], v[222:225], v[74:77]
	v_mfma_f32_16x16x32_bf16 v[126:129], v[152:155], v[202:205], v[126:129]
	v_mfma_f32_16x16x32_bf16 v[122:125], v[160:163], v[202:205], v[122:125]
	v_mfma_f32_16x16x32_bf16 v[110:113], v[152:155], v[210:213], v[110:113]
	v_mfma_f32_16x16x32_bf16 v[106:109], v[160:163], v[210:213], v[106:109]
	v_mfma_f32_16x16x32_bf16 v[94:97], v[152:155], v[218:221], v[94:97]
	v_mfma_f32_16x16x32_bf16 v[90:93], v[160:163], v[218:221], v[90:93]
	v_mfma_f32_16x16x32_bf16 v[78:81], v[152:155], v[226:229], v[78:81]
	v_mfma_f32_16x16x32_bf16 v[74:77], v[160:163], v[226:229], v[74:77]
	v_mfma_f32_16x16x32_bf16 v[118:121], v[182:185], v[198:201], v[118:121]
	v_mfma_f32_16x16x32_bf16 v[114:117], v[190:193], v[198:201], v[114:117]
	v_mfma_f32_16x16x32_bf16 v[102:105], v[182:185], v[206:209], v[102:105]
	v_mfma_f32_16x16x32_bf16 v[98:101], v[190:193], v[206:209], v[98:101]
	v_mfma_f32_16x16x32_bf16 v[86:89], v[182:185], v[214:217], v[86:89]
	v_mfma_f32_16x16x32_bf16 v[82:85], v[190:193], v[214:217], v[82:85]
	v_mfma_f32_16x16x32_bf16 v[70:73], v[182:185], v[222:225], v[70:73]
	v_mfma_f32_16x16x32_bf16 v[66:69], v[190:193], v[222:225], v[66:69]
	v_mfma_f32_16x16x32_bf16 v[118:121], v[186:189], v[202:205], v[118:121]
	v_mfma_f32_16x16x32_bf16 v[114:117], v[194:197], v[202:205], v[114:117]
	v_mfma_f32_16x16x32_bf16 v[102:105], v[186:189], v[210:213], v[102:105]
	v_mfma_f32_16x16x32_bf16 v[98:101], v[194:197], v[210:213], v[98:101]
	v_mfma_f32_16x16x32_bf16 v[86:89], v[186:189], v[218:221], v[86:89]
	v_mfma_f32_16x16x32_bf16 v[82:85], v[194:197], v[218:221], v[82:85]
	v_mfma_f32_16x16x32_bf16 v[70:73], v[186:189], v[226:229], v[70:73]
	v_mfma_f32_16x16x32_bf16 v[66:69], v[194:197], v[226:229], v[66:69]
	s_barrier
; #define PG8_STAGE(bufoff, gbase, voff) do { _Pragma("unroll") for (int _i = 0; _i < 2; ++_i) \
;         __builtin_amdgcn_global_load_lds((const unsigned*)((const char*)(gbase) + (voff)[_i]), (PG8_LAS unsigned*)(lds + (bufoff) + ldsw + _i * 8192), 16, 0, 0); } while (0)
; #define PG8_LDA(dst, b, h) do { _Pragma("unroll") for (int m = 0; m < 4; ++m) _Pragma("unroll") for (int k = 0; k < 2; ++k) dst[m][k] = *(const PG8_LAS bf16x8*)(lds + PG8_SA(b, h) + aoff + m * 2048 + k * 1024); } while (0)
; #define PG8_MMA(ai, bj, At, Bt) do { __builtin_amdgcn_s_setprio(1); _Pragma("unroll") for (int m = 0; m < 4; ++m) _Pragma("unroll") for (int n = 0; n < 2; ++n) _Pragma("unroll") for (int k = 0; k < 2; ++k) \
;         acc[ai][bj][m][n] = mma16<Epi::F16A>(Bt[n][k], At[m][k], acc[ai][bj][m][n]); __builtin_amdgcn_s_setprio(0); } while (0)
; #define PG8_WAIT_V(n) asm volatile("s_waitcnt vmcnt(" #n ")" ::: "memory")
; #define PG8_WAIT_L(n) asm volatile("s_waitcnt lgkmcnt(" #n ")" ::: "memory")
; #define PG8_BAR __builtin_amdgcn_s_barrier()
; #define PG8_SCHED __builtin_amdgcn_sched_barrier(0)
; template <class Epi, class Sched, bool ALIGN_EPI = false, bool SP2 = false>
; __device__ __forceinline__ void gemm_phase(PG8_LAS unsigned char* lds, const Gemm g, const Sched& S, const Epi& E) {
;     ...
;         for (int t = 0; t < nt; t += 2) {
;             const bool last = (t == nt - 2);
;     ...
;             PG8_LDA(At, 1, 1); PG8_STAGE(PG8_SB(1, 0), b3, voffB); PG8_STAGE(PG8_SB(1, 1), b3 + hstep, voffB); PG8_STAGE(PG8_SA(1, 0), a3, voffA);
;             PG8_WAIT_V(8); PG8_WAIT_L(0); PG8_BAR; PG8_MMA(1, 0, At, B0); PG8_MMA(1, 1, At, B1); PG8_BAR; PG8_SCHED;
	s_add_i32 s24, s55, s14
	v_lshl_add_u64 v[146:147], v[146:147], 0, s[92:93]
	s_mov_b32 m0, s24
	ds_read_b128 v[198:201], v151 offset:49152
	ds_read_b128 v[202:205], v151 offset:50176
	ds_read_b128 v[206:209], v151 offset:51200
	ds_read_b128 v[210:213], v151 offset:52224
	ds_read_b128 v[214:217], v151 offset:53248
	ds_read_b128 v[218:221], v151 offset:54272
	ds_read_b128 v[222:225], v151 offset:55296
	ds_read_b128 v[226:229], v151 offset:56320
	global_load_lds_dwordx4 v[146:147], off
	s_add_i32 m0, s24, 0x2000
	s_add_u32 s24, s38, 0xb0080
	v_lshl_add_u64 v[146:147], v[230:231], 0, s[92:93]
	s_addc_u32 s25, s39, 0
	s_add_i32 s38, s57, s14
	global_load_lds_dwordx4 v[146:147], off
	v_lshl_add_u64 v[146:147], s[24:25], 0, v[0:1]
	s_mov_b32 m0, s38
	s_nop 0
	global_load_lds_dwordx4 v[146:147], off
	v_lshl_add_u64 v[146:147], s[24:25], 0, v[132:133]
	s_add_i32 m0, s38, 0x2000
	s_nop 0
	global_load_lds_dwordx4 v[146:147], off
	v_lshl_add_u64 v[146:147], v[234:235], 0, s[92:93]
	s_mov_b32 m0, s48
	s_nop 0
	global_load_lds_dwordx4 v[146:147], off
	v_lshl_add_u64 v[146:147], v[236:237], 0, s[92:93]
	s_mov_b32 m0, s49
	s_nop 0
	global_load_lds_dwordx4 v[146:147], off
	s_waitcnt vmcnt(8)
	s_waitcnt lgkmcnt(0)
	s_barrier
	s_waitcnt lgkmcnt(0)
	v_mfma_f32_16x16x32_bf16 v[62:65], v[142:145], v[198:201], v[62:65]
	v_mfma_f32_16x16x32_bf16 v[58:61], v[156:159], v[198:201], v[58:61]
	v_mfma_f32_16x16x32_bf16 v[46:49], v[142:145], v[206:209], v[46:49]
	v_mfma_f32_16x16x32_bf16 v[42:45], v[156:159], v[206:209], v[42:45]
	v_mfma_f32_16x16x32_bf16 v[30:33], v[142:145], v[214:217], v[30:33]
	v_mfma_f32_16x16x32_bf16 v[26:29], v[156:159], v[214:217], v[26:29]
	v_mfma_f32_16x16x32_bf16 v[14:17], v[142:145], v[222:225], v[14:17]
	v_mfma_f32_16x16x32_bf16 v[10:13], v[156:159], v[222:225], v[10:13]
	v_mfma_f32_16x16x32_bf16 v[62:65], v[152:155], v[202:205], v[62:65]
	v_mfma_f32_16x16x32_bf16 v[58:61], v[160:163], v[202:205], v[58:61]
	v_mfma_f32_16x16x32_bf16 v[46:49], v[152:155], v[210:213], v[46:49]
	v_mfma_f32_16x16x32_bf16 v[42:45], v[160:163], v[210:213], v[42:45]
	v_mfma_f32_16x16x32_bf16 v[30:33], v[152:155], v[218:221], v[30:33]
	v_mfma_f32_16x16x32_bf16 v[26:29], v[160:163], v[218:221], v[26:29]
	v_mfma_f32_16x16x32_bf16 v[14:17], v[152:155], v[226:229], v[14:17]
	v_mfma_f32_16x16x32_bf16 v[10:13], v[160:163], v[226:229], v[10:13]
	v_mfma_f32_16x16x32_bf16 v[54:57], v[182:185], v[198:201], v[54:57]
	v_mfma_f32_16x16x32_bf16 v[50:53], v[190:193], v[198:201], v[50:53]
	v_mfma_f32_16x16x32_bf16 v[38:41], v[182:185], v[206:209], v[38:41]
	v_mfma_f32_16x16x32_bf16 v[34:37], v[190:193], v[206:209], v[34:37]
	v_mfma_f32_16x16x32_bf16 v[22:25], v[182:185], v[214:217], v[22:25]
	v_mfma_f32_16x16x32_bf16 v[18:21], v[190:193], v[214:217], v[18:21]
	v_mfma_f32_16x16x32_bf16 v[6:9], v[182:185], v[222:225], v[6:9]
	v_mfma_f32_16x16x32_bf16 v[2:5], v[190:193], v[222:225], v[2:5]
	v_mfma_f32_16x16x32_bf16 v[54:57], v[186:189], v[202:205], v[54:57]
	v_mfma_f32_16x16x32_bf16 v[50:53], v[194:197], v[202:205], v[50:53]
	v_mfma_f32_16x16x32_bf16 v[38:41], v[186:189], v[210:213], v[38:41]
	v_mfma_f32_16x16x32_bf16 v[34:37], v[194:197], v[210:213], v[34:37]
	v_mfma_f32_16x16x32_bf16 v[22:25], v[186:189], v[218:221], v[22:25]
	v_mfma_f32_16x16x32_bf16 v[18:21], v[194:197], v[218:221], v[18:21]
	v_mfma_f32_16x16x32_bf16 v[6:9], v[186:189], v[226:229], v[6:9]
	v_mfma_f32_16x16x32_bf16 v[2:5], v[194:197], v[226:229], v[2:5]
	s_barrier
	s_add_i32 s37, s37, 2
	s_add_u32 s4, s4, 0x100
	s_addc_u32 s5, s5, 0
	s_cmp_gt_u32 s37, 41
	s_mov_b64 s[24:25], s[26:27]
	s_cbranch_scc0 .LBB0_1298
	s_and_b64 vcc, exec, s[20:21]
	s_cbranch_vccz .LBB0_1301
	s_barrier

; #define PG8_STAGE(bufoff, gbase, voff) do { _Pragma("unroll") for (int _i = 0; _i < 2; ++_i) \
;         __builtin_amdgcn_global_load_lds((const unsigned*)((const char*)(gbase) + (voff)[_i]), (PG8_LAS unsigned*)(lds + (bufoff) + ldsw + _i * 8192), 16, 0, 0); } while (0)
; #define PG8_LDA(dst, b, h) do { _Pragma("unroll") for (int m = 0; m < 4; ++m) _Pragma("unroll") for (int k = 0; k < 2; ++k) dst[m][k] = *(const PG8_LAS bf16x8*)(lds + PG8_SA(b, h) + aoff + m * 2048 + k * 1024); } while (0)
; #define PG8_LDB(dst, b, h) do { _Pragma("unroll") for (int n = 0; n < 2; ++n) _Pragma("unroll") for (int k = 0; k < 2; ++k) dst[n][k] = *(const PG8_LAS bf16x8*)(lds + PG8_SB(b, h) + boff + n * 2048 + k * 1024); } while (0)
; #define PG8_MMA(ai, bj, At, Bt) do { __builtin_amdgcn_s_setprio(1); _Pragma("unroll") for (int m = 0; m < 4; ++m) _Pragma("unroll") for (int n = 0; n < 2; ++n) _Pragma("unroll") for (int k = 0; k < 2; ++k) \
;         acc[ai][bj][m][n] = mma16<Epi::F16A>(Bt[n][k], At[m][k], acc[ai][bj][m][n]); __builtin_amdgcn_s_setprio(0); } while (0)
; #define PG8_WAIT_V(n) asm volatile("s_waitcnt vmcnt(" #n ")" ::: "memory")
; #define PG8_WAIT_L(n) asm volatile("s_waitcnt lgkmcnt(" #n ")" ::: "memory")
; #define PG8_BAR __builtin_amdgcn_s_barrier()
; template <class Epi, class Sched, bool ALIGN_EPI = false, bool SP2 = false>
; __device__ __forceinline__ void gemm_phase(PG8_LAS unsigned char* lds, const Gemm g, const Sched& S, const Epi& E) {
;     ...
;             const bool last = (t == nt - 2);
;             const char* a1 = cA + (size_t)(t + 1) * kstep;
;             const char* a2 = last ? nA : cA + (size_t)(t + 2) * kstep; const char* b2 = last ? nB : cB + (size_t)(t + 2) * kstep;
;             const char* a3 = a2 + kstep; const char* b3 = b2 + kstep;
;             if (last && has_next) S.a_ready(nxt);
;             if constexpr (SP2) {
;             PG8_LDB(B0, 0, 0); PG8_LDB(B1, 0, 1); PG8_SCHED; PG8_LDA(At, 0, 0); PG8_STAGE(PG8_SA(1, 1), a1 + hstep, voffA);
;             PG8_WAIT_V(8); PG8_WAIT_L(0); PG8_BAR; PG8_MMA(0, 0, At, B0); PG8_MMA(0, 1, At, B1); PG8_BAR; PG8_SCHED;
;             PG8_LDA(At, 0, 1); PG8_STAGE(PG8_SB(0, 0), b2, voffB); PG8_STAGE(PG8_SB(0, 1), b2 + hstep, voffB); PG8_STAGE(PG8_SA(0, 0), a2, voffA);
;             PG8_WAIT_V(8); PG8_WAIT_L(0); PG8_BAR; PG8_MMA(1, 0, At, B0); PG8_MMA(1, 1, At, B1); PG8_BAR; PG8_SCHED;
.LBB0_1340:
	s_add_u32 s26, s24, 0x100
	s_addc_u32 s27, s25, 0
	s_add_i32 s59, 0, 0x10000
	s_cmp_eq_u32 s37, 40
	s_cselect_b32 s41, s1, s27
	s_cselect_b32 s40, s0, s26
	v_add_u32_e32 v144, s59, v148
	s_cselect_b32 s39, s23, s57
	s_cselect_b32 s38, s22, s55
	s_add_i32 s60, 0, 0x14000
	ds_read_b128 v[140:143], v144
	ds_read_b128 v[150:153], v144 offset:1024
	ds_read_b128 v[154:157], v144 offset:2048
	ds_read_b128 v[158:161], v144 offset:3072
	v_add_u32_e32 v144, s60, v148
	ds_read_b128 v[182:185], v144
	ds_read_b128 v[186:189], v144 offset:1024
	ds_read_b128 v[190:193], v144 offset:2048
	ds_read_b128 v[194:197], v144 offset:3072
	v_lshl_add_u64 v[144:145], s[24:25], 0, v[136:137]
	s_add_i32 m0, s15, 0xc000
	ds_read_b128 v[198:201], v149
	ds_read_b128 v[202:205], v149 offset:1024
	ds_read_b128 v[206:209], v149 offset:2048
	ds_read_b128 v[210:213], v149 offset:3072
	ds_read_b128 v[214:217], v149 offset:4096
	ds_read_b128 v[218:221], v149 offset:5120
	ds_read_b128 v[222:225], v149 offset:6144
	ds_read_b128 v[226:229], v149 offset:7168
	global_load_lds_dwordx4 v[144:145], off
	v_lshl_add_u64 v[144:145], s[24:25], 0, v[138:139]
	s_add_i32 m0, s15, 0xe000
	s_nop 0
	global_load_lds_dwordx4 v[144:145], off
	s_waitcnt vmcnt(8)
	s_waitcnt lgkmcnt(0)
	s_barrier
	s_waitcnt lgkmcnt(0)
	v_mfma_f32_16x16x32_bf16 v[126:129], v[140:143], v[198:201], v[126:129]
	v_mfma_f32_16x16x32_bf16 v[122:125], v[154:157], v[198:201], v[122:125]
	v_mfma_f32_16x16x32_bf16 v[110:113], v[140:143], v[206:209], v[110:113]
	v_mfma_f32_16x16x32_bf16 v[106:109], v[154:157], v[206:209], v[106:109]
	v_mfma_f32_16x16x32_bf16 v[94:97], v[140:143], v[214:217], v[94:97]
	v_mfma_f32_16x16x32_bf16 v[90:93], v[154:157], v[214:217], v[90:93]
	v_mfma_f32_16x16x32_bf16 v[78:81], v[140:143], v[222:225], v[78:81]
	v_mfma_f32_16x16x32_bf16 v[74:77], v[154:157], v[222:225], v[74:77]
	v_mfma_f32_16x16x32_bf16 v[126:129], v[150:153], v[202:205], v[126:129]
	v_mfma_f32_16x16x32_bf16 v[122:125], v[158:161], v[202:205], v[122:125]
	v_mfma_f32_16x16x32_bf16 v[110:113], v[150:153], v[210:213], v[110:113]
	v_mfma_f32_16x16x32_bf16 v[106:109], v[158:161], v[210:213], v[106:109]
	v_mfma_f32_16x16x32_bf16 v[94:97], v[150:153], v[218:221], v[94:97]
	v_mfma_f32_16x16x32_bf16 v[90:93], v[158:161], v[218:221], v[90:93]
	v_mfma_f32_16x16x32_bf16 v[78:81], v[150:153], v[226:229], v[78:81]
	v_mfma_f32_16x16x32_bf16 v[74:77], v[158:161], v[226:229], v[74:77]
	v_mfma_f32_16x16x32_bf16 v[118:121], v[182:185], v[198:201], v[118:121]
	v_mfma_f32_16x16x32_bf16 v[114:117], v[190:193], v[198:201], v[114:117]
	v_mfma_f32_16x16x32_bf16 v[102:105], v[182:185], v[206:209], v[102:105]
	v_mfma_f32_16x16x32_bf16 v[98:101], v[190:193], v[206:209], v[98:101]
	v_mfma_f32_16x16x32_bf16 v[86:89], v[182:185], v[214:217], v[86:89]
	v_mfma_f32_16x16x32_bf16 v[82:85], v[190:193], v[214:217], v[82:85]
	v_mfma_f32_16x16x32_bf16 v[70:73], v[182:185], v[222:225], v[70:73]
	v_mfma_f32_16x16x32_bf16 v[66:69], v[190:193], v[222:225], v[66:69]
	v_mfma_f32_16x16x32_bf16 v[118:121], v[186:189], v[202:205], v[118:121]
	v_mfma_f32_16x16x32_bf16 v[114:117], v[194:197], v[202:205], v[114:117]
	v_mfma_f32_16x16x32_bf16 v[102:105], v[186:189], v[210:213], v[102:105]
	v_mfma_f32_16x16x32_bf16 v[98:101], v[194:197], v[210:213], v[98:101]
	v_mfma_f32_16x16x32_bf16 v[86:89], v[186:189], v[218:221], v[86:89]
	v_mfma_f32_16x16x32_bf16 v[82:85], v[194:197], v[218:221], v[82:85]
	v_mfma_f32_16x16x32_bf16 v[70:73], v[186:189], v[226:229], v[70:73]
	v_mfma_f32_16x16x32_bf16 v[66:69], v[194:197], v[226:229], v[66:69]
	s_barrier
	s_add_i32 s24, s59, s14
	v_lshl_add_u64 v[144:145], s[38:39], 0, v[0:1]
	s_mov_b32 m0, s24
	ds_read_b128 v[198:201], v149 offset:16384
	ds_read_b128 v[202:205], v149 offset:17408
	ds_read_b128 v[206:209], v149 offset:18432
	ds_read_b128 v[210:213], v149 offset:19456
	ds_read_b128 v[214:217], v149 offset:20480
	ds_read_b128 v[218:221], v149 offset:21504
	ds_read_b128 v[222:225], v149 offset:22528
	ds_read_b128 v[226:229], v149 offset:23552
	global_load_lds_dwordx4 v[144:145], off
	s_add_i32 m0, s24, 0x2000
	s_add_u32 s24, s38, 0xb0000
	v_lshl_add_u64 v[162:163], s[38:39], 0, v[130:131]
	s_addc_u32 s25, s39, 0
	s_add_i32 s59, s60, s14
	global_load_lds_dwordx4 v[162:163], off
	v_lshl_add_u64 v[230:231], s[24:25], 0, v[0:1]
	s_mov_b32 m0, s59
	v_lshl_add_u64 v[234:235], s[40:41], 0, v[132:133]
	global_load_lds_dwordx4 v[230:231], off
	v_lshl_add_u64 v[230:231], s[24:25], 0, v[130:131]
	s_add_i32 m0, s59, 0x2000
	s_nop 0
	global_load_lds_dwordx4 v[230:231], off
	v_lshl_add_u64 v[230:231], s[40:41], 0, v[134:135]
	s_mov_b32 m0, s15
	s_nop 0
	global_load_lds_dwordx4 v[230:231], off
	s_mov_b32 m0, s28
	s_nop 0
	global_load_lds_dwordx4 v[234:235], off
	s_waitcnt vmcnt(8)
	s_waitcnt lgkmcnt(0)
	s_barrier
; #define PG8_STAGE(bufoff, gbase, voff) do { _Pragma("unroll") for (int _i = 0; _i < 2; ++_i) \
;         __builtin_amdgcn_global_load_lds((const unsigned*)((const char*)(gbase) + (voff)[_i]), (PG8_LAS unsigned*)(lds + (bufoff) + ldsw + _i * 8192), 16, 0, 0); } while (0)
; #define PG8_LDA(dst, b, h) do { _Pragma("unroll") for (int m = 0; m < 4; ++m) _Pragma("unroll") for (int k = 0; k < 2; ++k) dst[m][k] = *(const PG8_LAS bf16x8*)(lds + PG8_SA(b, h) + aoff + m * 2048 + k * 1024); } while (0)
; #define PG8_LDB(dst, b, h) do { _Pragma("unroll") for (int n = 0; n < 2; ++n) _Pragma("unroll") for (int k = 0; k < 2; ++k) dst[n][k] = *(const PG8_LAS bf16x8*)(lds + PG8_SB(b, h) + boff + n * 2048 + k * 1024); } while (0)
; #define PG8_MMA(ai, bj, At, Bt) do { __builtin_amdgcn_s_setprio(1); _Pragma("unroll") for (int m = 0; m < 4; ++m) _Pragma("unroll") for (int n = 0; n < 2; ++n) _Pragma("unroll") for (int k = 0; k < 2; ++k) \
;         acc[ai][bj][m][n] = mma16<Epi::F16A>(Bt[n][k], At[m][k], acc[ai][bj][m][n]); __builtin_amdgcn_s_setprio(0); } while (0)
; #define PG8_WAIT_V(n) asm volatile("s_waitcnt vmcnt(" #n ")" ::: "memory")
; #define PG8_WAIT_L(n) asm volatile("s_waitcnt lgkmcnt(" #n ")" ::: "memory")
; #define PG8_BAR __builtin_amdgcn_s_barrier()
; #define PG8_SCHED __builtin_amdgcn_sched_barrier(0)
; template <class Epi, class Sched, bool ALIGN_EPI = false, bool SP2 = false>
; __device__ __forceinline__ void gemm_phase(PG8_LAS unsigned char* lds, const Gemm g, const Sched& S, const Epi& E) {
;     ...
;             PG8_WAIT_V(8); PG8_WAIT_L(0); PG8_BAR; PG8_MMA(1, 0, At, B0); PG8_MMA(1, 1, At, B1); PG8_BAR; PG8_SCHED;
;             PG8_LDB(B0, 1, 0); PG8_LDB(B1, 1, 1); PG8_SCHED; PG8_LDA(At, 1, 0); PG8_STAGE(PG8_SA(0, 1), a2 + hstep, voffA);
;             PG8_WAIT_V(8); PG8_WAIT_L(0); PG8_BAR; PG8_MMA(0, 0, At, B0); PG8_MMA(0, 1, At, B1); PG8_BAR; PG8_SCHED;
	s_waitcnt lgkmcnt(0)
	v_mfma_f32_16x16x32_bf16 v[62:65], v[140:143], v[198:201], v[62:65]
	v_mfma_f32_16x16x32_bf16 v[58:61], v[154:157], v[198:201], v[58:61]
	v_mfma_f32_16x16x32_bf16 v[46:49], v[140:143], v[206:209], v[46:49]
	v_mfma_f32_16x16x32_bf16 v[42:45], v[154:157], v[206:209], v[42:45]
	v_mfma_f32_16x16x32_bf16 v[30:33], v[140:143], v[214:217], v[30:33]
	v_mfma_f32_16x16x32_bf16 v[26:29], v[154:157], v[214:217], v[26:29]
	v_mfma_f32_16x16x32_bf16 v[14:17], v[140:143], v[222:225], v[14:17]
	v_mfma_f32_16x16x32_bf16 v[10:13], v[154:157], v[222:225], v[10:13]
	v_mfma_f32_16x16x32_bf16 v[62:65], v[150:153], v[202:205], v[62:65]
	v_mfma_f32_16x16x32_bf16 v[58:61], v[158:161], v[202:205], v[58:61]
	v_mfma_f32_16x16x32_bf16 v[46:49], v[150:153], v[210:213], v[46:49]
	v_mfma_f32_16x16x32_bf16 v[42:45], v[158:161], v[210:213], v[42:45]
	v_mfma_f32_16x16x32_bf16 v[30:33], v[150:153], v[218:221], v[30:33]
	v_mfma_f32_16x16x32_bf16 v[26:29], v[158:161], v[218:221], v[26:29]
	v_mfma_f32_16x16x32_bf16 v[14:17], v[150:153], v[226:229], v[14:17]
	v_mfma_f32_16x16x32_bf16 v[10:13], v[158:161], v[226:229], v[10:13]
	v_mfma_f32_16x16x32_bf16 v[54:57], v[182:185], v[198:201], v[54:57]
	v_mfma_f32_16x16x32_bf16 v[50:53], v[190:193], v[198:201], v[50:53]
	v_mfma_f32_16x16x32_bf16 v[38:41], v[182:185], v[206:209], v[38:41]
	v_mfma_f32_16x16x32_bf16 v[34:37], v[190:193], v[206:209], v[34:37]
	v_mfma_f32_16x16x32_bf16 v[22:25], v[182:185], v[214:217], v[22:25]
	v_mfma_f32_16x16x32_bf16 v[18:21], v[190:193], v[214:217], v[18:21]
	v_mfma_f32_16x16x32_bf16 v[6:9], v[182:185], v[222:225], v[6:9]
	v_mfma_f32_16x16x32_bf16 v[2:5], v[190:193], v[222:225], v[2:5]
	v_mfma_f32_16x16x32_bf16 v[54:57], v[186:189], v[202:205], v[54:57]
	v_mfma_f32_16x16x32_bf16 v[50:53], v[194:197], v[202:205], v[50:53]
	v_mfma_f32_16x16x32_bf16 v[38:41], v[186:189], v[210:213], v[38:41]
	v_mfma_f32_16x16x32_bf16 v[34:37], v[194:197], v[210:213], v[34:37]
	v_mfma_f32_16x16x32_bf16 v[22:25], v[186:189], v[218:221], v[22:25]
	v_mfma_f32_16x16x32_bf16 v[18:21], v[194:197], v[218:221], v[18:21]
	v_mfma_f32_16x16x32_bf16 v[6:9], v[186:189], v[226:229], v[6:9]
	v_mfma_f32_16x16x32_bf16 v[2:5], v[194:197], v[226:229], v[2:5]
	s_barrier
	s_add_i32 s59, 0, 0x18000
	s_add_i32 s60, 0, 0x1c000
	v_add_u32_e32 v158, s59, v148
	v_add_u32_e32 v194, s60, v148
	ds_read_b128 v[140:143], v158
	ds_read_b128 v[150:153], v158 offset:1024
	ds_read_b128 v[154:157], v158 offset:2048
	ds_read_b128 v[158:161], v158 offset:3072
	ds_read_b128 v[182:185], v194
	ds_read_b128 v[186:189], v194 offset:1024
	ds_read_b128 v[190:193], v194 offset:2048
	ds_read_b128 v[194:197], v194 offset:3072
	s_add_u32 s24, s40, 0xb0000
	s_addc_u32 s25, s41, 0
	s_mov_b32 m0, s30
	v_lshl_add_u64 v[236:237], s[24:25], 0, v[134:135]
	ds_read_b128 v[198:201], v149 offset:32768
	ds_read_b128 v[202:205], v149 offset:33792
	ds_read_b128 v[206:209], v149 offset:34816
	ds_read_b128 v[210:213], v149 offset:35840
	ds_read_b128 v[214:217], v149 offset:36864
	ds_read_b128 v[218:221], v149 offset:37888
	ds_read_b128 v[222:225], v149 offset:38912
	ds_read_b128 v[226:229], v149 offset:39936
	global_load_lds_dwordx4 v[236:237], off
	v_lshl_add_u64 v[236:237], s[24:25], 0, v[132:133]
	s_mov_b32 m0, s31
	s_nop 0
	global_load_lds_dwordx4 v[236:237], off
	s_waitcnt vmcnt(8)
	s_waitcnt lgkmcnt(0)
	s_barrier
	s_waitcnt lgkmcnt(0)
	v_mfma_f32_16x16x32_bf16 v[126:129], v[140:143], v[198:201], v[126:129]
	v_mfma_f32_16x16x32_bf16 v[122:125], v[154:157], v[198:201], v[122:125]
	v_mfma_f32_16x16x32_bf16 v[110:113], v[140:143], v[206:209], v[110:113]
	v_mfma_f32_16x16x32_bf16 v[106:109], v[154:157], v[206:209], v[106:109]
	v_mfma_f32_16x16x32_bf16 v[94:97], v[140:143], v[214:217], v[94:97]
	v_mfma_f32_16x16x32_bf16 v[90:93], v[154:157], v[214:217], v[90:93]
	v_mfma_f32_16x16x32_bf16 v[78:81], v[140:143], v[222:225], v[78:81]
	v_mfma_f32_16x16x32_bf16 v[74:77], v[154:157], v[222:225], v[74:77]
	v_mfma_f32_16x16x32_bf16 v[126:129], v[150:153], v[202:205], v[126:129]
	v_mfma_f32_16x16x32_bf16 v[122:125], v[158:161], v[202:205], v[122:125]
	v_mfma_f32_16x16x32_bf16 v[110:113], v[150:153], v[210:213], v[110:113]
	v_mfma_f32_16x16x32_bf16 v[106:109], v[158:161], v[210:213], v[106:109]
	v_mfma_f32_16x16x32_bf16 v[94:97], v[150:153], v[218:221], v[94:97]
	v_mfma_f32_16x16x32_bf16 v[90:93], v[158:161], v[218:221], v[90:93]
	v_mfma_f32_16x16x32_bf16 v[78:81], v[150:153], v[226:229], v[78:81]
	v_mfma_f32_16x16x32_bf16 v[74:77], v[158:161], v[226:229], v[74:77]
	v_mfma_f32_16x16x32_bf16 v[118:121], v[182:185], v[198:201], v[118:121]
	v_mfma_f32_16x16x32_bf16 v[114:117], v[190:193], v[198:201], v[114:117]
	v_mfma_f32_16x16x32_bf16 v[102:105], v[182:185], v[206:209], v[102:105]
	v_mfma_f32_16x16x32_bf16 v[98:101], v[190:193], v[206:209], v[98:101]
	v_mfma_f32_16x16x32_bf16 v[86:89], v[182:185], v[214:217], v[86:89]
	v_mfma_f32_16x16x32_bf16 v[82:85], v[190:193], v[214:217], v[82:85]
	v_mfma_f32_16x16x32_bf16 v[70:73], v[182:185], v[222:225], v[70:73]
	v_mfma_f32_16x16x32_bf16 v[66:69], v[190:193], v[222:225], v[66:69]
	v_mfma_f32_16x16x32_bf16 v[118:121], v[186:189], v[202:205], v[118:121]
	v_mfma_f32_16x16x32_bf16 v[114:117], v[194:197], v[202:205], v[114:117]
	v_mfma_f32_16x16x32_bf16 v[102:105], v[186:189], v[210:213], v[102:105]
	v_mfma_f32_16x16x32_bf16 v[98:101], v[194:197], v[210:213], v[98:101]
	v_mfma_f32_16x16x32_bf16 v[86:89], v[186:189], v[218:221], v[86:89]
	v_mfma_f32_16x16x32_bf16 v[82:85], v[194:197], v[218:221], v[82:85]
	v_mfma_f32_16x16x32_bf16 v[70:73], v[186:189], v[226:229], v[70:73]
	v_mfma_f32_16x16x32_bf16 v[66:69], v[194:197], v[226:229], v[66:69]
	s_barrier
; #define PG8_STAGE(bufoff, gbase, voff) do { _Pragma("unroll") for (int _i = 0; _i < 2; ++_i) \
;         __builtin_amdgcn_global_load_lds((const unsigned*)((const char*)(gbase) + (voff)[_i]), (PG8_LAS unsigned*)(lds + (bufoff) + ldsw + _i * 8192), 16, 0, 0); } while (0)
; #define PG8_LDA(dst, b, h) do { _Pragma("unroll") for (int m = 0; m < 4; ++m) _Pragma("unroll") for (int k = 0; k < 2; ++k) dst[m][k] = *(const PG8_LAS bf16x8*)(lds + PG8_SA(b, h) + aoff + m * 2048 + k * 1024); } while (0)
; #define PG8_MMA(ai, bj, At, Bt) do { __builtin_amdgcn_s_setprio(1); _Pragma("unroll") for (int m = 0; m < 4; ++m) _Pragma("unroll") for (int n = 0; n < 2; ++n) _Pragma("unroll") for (int k = 0; k < 2; ++k) \
;         acc[ai][bj][m][n] = mma16<Epi::F16A>(Bt[n][k], At[m][k], acc[ai][bj][m][n]); __builtin_amdgcn_s_setprio(0); } while (0)
; #define PG8_WAIT_V(n) asm volatile("s_waitcnt vmcnt(" #n ")" ::: "memory")
; #define PG8_WAIT_L(n) asm volatile("s_waitcnt lgkmcnt(" #n ")" ::: "memory")
; #define PG8_BAR __builtin_amdgcn_s_barrier()
; #define PG8_SCHED __builtin_amdgcn_sched_barrier(0)
; template <class Epi, class Sched, bool ALIGN_EPI = false, bool SP2 = false>
; __device__ __forceinline__ void gemm_phase(PG8_LAS unsigned char* lds, const Gemm g, const Sched& S, const Epi& E) {
;     ...
;         for (int t = 0; t < nt; t += 2) {
;             const bool last = (t == nt - 2);
;     ...
;             PG8_LDA(At, 1, 1); PG8_STAGE(PG8_SB(1, 0), b3, voffB); PG8_STAGE(PG8_SB(1, 1), b3 + hstep, voffB); PG8_STAGE(PG8_SA(1, 0), a3, voffA);
;             PG8_WAIT_V(8); PG8_WAIT_L(0); PG8_BAR; PG8_MMA(1, 0, At, B0); PG8_MMA(1, 1, At, B1); PG8_BAR; PG8_SCHED;
	s_add_i32 s24, s59, s14
	v_lshl_add_u64 v[144:145], v[144:145], 0, s[92:93]
	s_mov_b32 m0, s24
	ds_read_b128 v[198:201], v149 offset:49152
	ds_read_b128 v[202:205], v149 offset:50176
	ds_read_b128 v[206:209], v149 offset:51200
	ds_read_b128 v[210:213], v149 offset:52224
	ds_read_b128 v[214:217], v149 offset:53248
	ds_read_b128 v[218:221], v149 offset:54272
	ds_read_b128 v[222:225], v149 offset:55296
	ds_read_b128 v[226:229], v149 offset:56320
	global_load_lds_dwordx4 v[144:145], off
	s_add_i32 m0, s24, 0x2000
	s_add_u32 s24, s38, 0xb0080
	v_lshl_add_u64 v[144:145], v[162:163], 0, s[92:93]
	s_addc_u32 s25, s39, 0
	s_add_i32 s38, s60, s14
	global_load_lds_dwordx4 v[144:145], off
	v_lshl_add_u64 v[144:145], s[24:25], 0, v[0:1]
	s_mov_b32 m0, s38
	s_nop 0
	global_load_lds_dwordx4 v[144:145], off
	v_lshl_add_u64 v[144:145], s[24:25], 0, v[130:131]
	s_add_i32 m0, s38, 0x2000
	s_nop 0
	global_load_lds_dwordx4 v[144:145], off
	v_lshl_add_u64 v[144:145], v[230:231], 0, s[92:93]
	s_mov_b32 m0, s48
	s_nop 0
	global_load_lds_dwordx4 v[144:145], off
	v_lshl_add_u64 v[144:145], v[234:235], 0, s[92:93]
	s_mov_b32 m0, s49
	s_nop 0
	global_load_lds_dwordx4 v[144:145], off
	s_waitcnt vmcnt(8)
	s_waitcnt lgkmcnt(0)
	s_barrier
	s_waitcnt lgkmcnt(0)
	v_mfma_f32_16x16x32_bf16 v[62:65], v[140:143], v[198:201], v[62:65]
	v_mfma_f32_16x16x32_bf16 v[58:61], v[154:157], v[198:201], v[58:61]
	v_mfma_f32_16x16x32_bf16 v[46:49], v[140:143], v[206:209], v[46:49]
	v_mfma_f32_16x16x32_bf16 v[42:45], v[154:157], v[206:209], v[42:45]
	v_mfma_f32_16x16x32_bf16 v[30:33], v[140:143], v[214:217], v[30:33]
	v_mfma_f32_16x16x32_bf16 v[26:29], v[154:157], v[214:217], v[26:29]
	v_mfma_f32_16x16x32_bf16 v[14:17], v[140:143], v[222:225], v[14:17]
	v_mfma_f32_16x16x32_bf16 v[10:13], v[154:157], v[222:225], v[10:13]
	v_mfma_f32_16x16x32_bf16 v[62:65], v[150:153], v[202:205], v[62:65]
	v_mfma_f32_16x16x32_bf16 v[58:61], v[158:161], v[202:205], v[58:61]
	v_mfma_f32_16x16x32_bf16 v[46:49], v[150:153], v[210:213], v[46:49]
	v_mfma_f32_16x16x32_bf16 v[42:45], v[158:161], v[210:213], v[42:45]
	v_mfma_f32_16x16x32_bf16 v[30:33], v[150:153], v[218:221], v[30:33]
	v_mfma_f32_16x16x32_bf16 v[26:29], v[158:161], v[218:221], v[26:29]
	v_mfma_f32_16x16x32_bf16 v[14:17], v[150:153], v[226:229], v[14:17]
	v_mfma_f32_16x16x32_bf16 v[10:13], v[158:161], v[226:229], v[10:13]
	v_mfma_f32_16x16x32_bf16 v[54:57], v[182:185], v[198:201], v[54:57]
	v_mfma_f32_16x16x32_bf16 v[50:53], v[190:193], v[198:201], v[50:53]
	v_mfma_f32_16x16x32_bf16 v[38:41], v[182:185], v[206:209], v[38:41]
	v_mfma_f32_16x16x32_bf16 v[34:37], v[190:193], v[206:209], v[34:37]
	v_mfma_f32_16x16x32_bf16 v[22:25], v[182:185], v[214:217], v[22:25]
	v_mfma_f32_16x16x32_bf16 v[18:21], v[190:193], v[214:217], v[18:21]
	v_mfma_f32_16x16x32_bf16 v[6:9], v[182:185], v[222:225], v[6:9]
	v_mfma_f32_16x16x32_bf16 v[2:5], v[190:193], v[222:225], v[2:5]
	v_mfma_f32_16x16x32_bf16 v[54:57], v[186:189], v[202:205], v[54:57]
	v_mfma_f32_16x16x32_bf16 v[50:53], v[194:197], v[202:205], v[50:53]
	v_mfma_f32_16x16x32_bf16 v[38:41], v[186:189], v[210:213], v[38:41]
	v_mfma_f32_16x16x32_bf16 v[34:37], v[194:197], v[210:213], v[34:37]
	v_mfma_f32_16x16x32_bf16 v[22:25], v[186:189], v[218:221], v[22:25]
	v_mfma_f32_16x16x32_bf16 v[18:21], v[194:197], v[218:221], v[18:21]
	v_mfma_f32_16x16x32_bf16 v[6:9], v[186:189], v[226:229], v[6:9]
	v_mfma_f32_16x16x32_bf16 v[2:5], v[194:197], v[226:229], v[2:5]
	s_barrier
	s_add_i32 s37, s37, 2
	s_add_u32 s55, s55, 0x100
	s_addc_u32 s57, s57, 0
	s_cmp_gt_u32 s37, 41
	s_mov_b64 s[24:25], s[26:27]
	s_cbranch_scc0 .LBB0_1340
	s_and_b64 vcc, exec, s[20:21]
	s_cbranch_vccz .LBB0_1343
	s_barrier
